# row2: row sum of squares comes from partials written by the gemm_out epilogue (no first pass over x), modulation tables from a per-wave LDS copy, router-weight ring 6 deep; lru_load_w and carry scan b
# speedup vs baseline: 1.1980x; 1.0297x over previous
; #define TIDX tid_opaque()
; DI void lru_load_w(const Params& P, int l, int g, char* Wt) {
;   const int tid = TIDX;
;   for (int dg = 0; dg < 4; dg++) {
;     const int dir = dg >> 1;
;     const float* w = ((dg & 1) ? P.gate_x_w : P.gate_a_w) + ((size_t)((l * 2 + dir) * 4 + g)) * 4096;
;     for (int idx = tid; idx < 4096; idx += 256) { int i = idx >> 6, o = idx & 63; *(half_t*)(Wt + dg * 8192 + swz128(o, i)) = (half_t)w[idx]; }
;   }
; }
.LBB0_346:
	s_or_b64 exec, exec, s[0:1]
	v_mov_b32_e32 v0, v172
	s_movk_i32 s0, 0x1000
	s_barrier
	s_nop 0
	v_cmp_gt_i32_e32 vcc, s0, v0
	s_and_saveexec_b64 s[2:3], vcc
	s_cbranch_execz .LBB0_391
	s_lshl_b32 s20, s22, 15
	v_readlane_b32 s0, v254, 23
	v_readlane_b32 s4, v253, 23
	v_readlane_b32 s5, v253, 24
	v_readlane_b32 s6, v253, 27
	v_readlane_b32 s7, v253, 28
	s_nop 3
	s_or_b32 s84, s20, s0
	s_lshl_b32 s0, s84, 2
	s_add_u32 s4, s4, s0
	s_addc_u32 s5, s5, 0
	s_add_u32 s6, s6, s0
	s_addc_u32 s7, s7, 0
	v_lshlrev_b32_e32 v54, 2, v172
	v_and_b32_e32 v55, 63, v172
	v_lshrrev_b32_e32 v57, 6, v172
	v_bfe_u32 v56, v172, 1, 3
	v_lshlrev_b32_e32 v55, 7, v55
	v_lshl_add_u32 v55, v57, 1, v55
	s_add_u32 s8, s4, 0x0
	s_addc_u32 s9, s5, 0
	global_load_dword v186, v54, s[8:9]
	global_load_dword v187, v54, s[8:9] offset:1024
	global_load_dword v188, v54, s[8:9] offset:2048
	global_load_dword v189, v54, s[8:9] offset:3072
	s_add_u32 s8, s4, 0x1000
	s_addc_u32 s9, s5, 0
	global_load_dword v190, v54, s[8:9]
	global_load_dword v191, v54, s[8:9] offset:1024
	global_load_dword v192, v54, s[8:9] offset:2048
	global_load_dword v193, v54, s[8:9] offset:3072
	s_add_u32 s8, s4, 0x2000
	s_addc_u32 s9, s5, 0
	global_load_dword v194, v54, s[8:9]
	global_load_dword v195, v54, s[8:9] offset:1024
	global_load_dword v196, v54, s[8:9] offset:2048
	global_load_dword v197, v54, s[8:9] offset:3072
	s_add_u32 s8, s4, 0x3000
	s_addc_u32 s9, s5, 0
	global_load_dword v198, v54, s[8:9]
	global_load_dword v199, v54, s[8:9] offset:1024
	global_load_dword v200, v54, s[8:9] offset:2048
	global_load_dword v201, v54, s[8:9] offset:3072
	s_add_u32 s8, s6, 0x0
	s_addc_u32 s9, s7, 0
	global_load_dword v202, v54, s[8:9]
	global_load_dword v203, v54, s[8:9] offset:1024
	global_load_dword v204, v54, s[8:9] offset:2048
	global_load_dword v205, v54, s[8:9] offset:3072
	s_add_u32 s8, s6, 0x1000
	s_addc_u32 s9, s7, 0
	global_load_dword v206, v54, s[8:9]
	global_load_dword v207, v54, s[8:9] offset:1024
	global_load_dword v208, v54, s[8:9] offset:2048
	global_load_dword v209, v54, s[8:9] offset:3072
	s_add_u32 s8, s6, 0x2000
	s_addc_u32 s9, s7, 0
	global_load_dword v210, v54, s[8:9]
	global_load_dword v211, v54, s[8:9] offset:1024
	global_load_dword v212, v54, s[8:9] offset:2048
	global_load_dword v213, v54, s[8:9] offset:3072
	s_add_u32 s8, s6, 0x3000
	s_addc_u32 s9, s7, 0
	global_load_dword v214, v54, s[8:9]
	global_load_dword v215, v54, s[8:9] offset:1024
	global_load_dword v216, v54, s[8:9] offset:2048
	global_load_dword v217, v54, s[8:9] offset:3072
	s_add_u32 s8, s4, 0x10000
	s_addc_u32 s9, s5, 0
	global_load_dword v218, v54, s[8:9]
	global_load_dword v219, v54, s[8:9] offset:1024
	global_load_dword v220, v54, s[8:9] offset:2048
	global_load_dword v221, v54, s[8:9] offset:3072
	s_add_u32 s8, s4, 0x11000
	s_addc_u32 s9, s5, 0
	global_load_dword v222, v54, s[8:9]
	global_load_dword v223, v54, s[8:9] offset:1024
	global_load_dword v224, v54, s[8:9] offset:2048
	global_load_dword v225, v54, s[8:9] offset:3072
	s_add_u32 s8, s4, 0x12000
	s_addc_u32 s9, s5, 0
	global_load_dword v226, v54, s[8:9]
	global_load_dword v227, v54, s[8:9] offset:1024
	global_load_dword v228, v54, s[8:9] offset:2048
	global_load_dword v229, v54, s[8:9] offset:3072
	s_add_u32 s8, s4, 0x13000
	s_addc_u32 s9, s5, 0
	global_load_dword v230, v54, s[8:9]
	global_load_dword v231, v54, s[8:9] offset:1024
	global_load_dword v232, v54, s[8:9] offset:2048
	global_load_dword v233, v54, s[8:9] offset:3072
	s_add_u32 s8, s6, 0x10000
	s_addc_u32 s9, s7, 0
	global_load_dword v234, v54, s[8:9]
	global_load_dword v235, v54, s[8:9] offset:1024
	global_load_dword v236, v54, s[8:9] offset:2048
	global_load_dword v237, v54, s[8:9] offset:3072
	s_add_u32 s8, s6, 0x11000
	s_addc_u32 s9, s7, 0
	global_load_dword v238, v54, s[8:9]
	global_load_dword v239, v54, s[8:9] offset:1024
	global_load_dword v240, v54, s[8:9] offset:2048
	global_load_dword v241, v54, s[8:9] offset:3072
	s_add_u32 s8, s6, 0x12000
	s_addc_u32 s9, s7, 0
	global_load_dword v242, v54, s[8:9]
	global_load_dword v243, v54, s[8:9] offset:1024
	global_load_dword v244, v54, s[8:9] offset:2048
	global_load_dword v245, v54, s[8:9] offset:3072
	s_add_u32 s8, s6, 0x13000
	s_addc_u32 s9, s7, 0
	global_load_dword v246, v54, s[8:9]
	global_load_dword v247, v54, s[8:9] offset:1024
	global_load_dword v248, v54, s[8:9] offset:2048
	global_load_dword v249, v54, s[8:9] offset:3072
	s_waitcnt vmcnt(63)
	v_cvt_f16_f32_e32 v58, v186
	v_xor_b32_e32 v57, 0, v56
	v_lshl_add_u32 v57, v57, 4, v55
	ds_write_b16 v57, v58 offset:0
	s_waitcnt vmcnt(62)
	v_cvt_f16_f32_e32 v58, v187
	v_xor_b32_e32 v57, 0, v56
	v_lshl_add_u32 v57, v57, 4, v55
	ds_write_b16 v57, v58 offset:8
	s_waitcnt vmcnt(61)
	v_cvt_f16_f32_e32 v58, v188
	v_xor_b32_e32 v57, 1, v56
	v_lshl_add_u32 v57, v57, 4, v55
	ds_write_b16 v57, v58 offset:0
	s_waitcnt vmcnt(60)
	v_cvt_f16_f32_e32 v58, v189
	v_xor_b32_e32 v57, 1, v56
	v_lshl_add_u32 v57, v57, 4, v55
	ds_write_b16 v57, v58 offset:8
	s_waitcnt vmcnt(59)
	v_cvt_f16_f32_e32 v58, v190
	v_xor_b32_e32 v57, 2, v56
	v_lshl_add_u32 v57, v57, 4, v55
	ds_write_b16 v57, v58 offset:0
	s_waitcnt vmcnt(58)
	v_cvt_f16_f32_e32 v58, v191
	v_xor_b32_e32 v57, 2, v56
	v_lshl_add_u32 v57, v57, 4, v55
	ds_write_b16 v57, v58 offset:8
	s_waitcnt vmcnt(57)
	v_cvt_f16_f32_e32 v58, v192
	v_xor_b32_e32 v57, 3, v56
	v_lshl_add_u32 v57, v57, 4, v55
	ds_write_b16 v57, v58 offset:0
	s_waitcnt vmcnt(56)
	v_cvt_f16_f32_e32 v58, v193
	v_xor_b32_e32 v57, 3, v56
	v_lshl_add_u32 v57, v57, 4, v55
	ds_write_b16 v57, v58 offset:8
	s_waitcnt vmcnt(55)
	v_cvt_f16_f32_e32 v58, v194
	v_xor_b32_e32 v57, 4, v56
	v_lshl_add_u32 v57, v57, 4, v55
	ds_write_b16 v57, v58 offset:0
	s_waitcnt vmcnt(54)
; #define TIDX tid_opaque()
; DI void lru_load_w(const Params& P, int l, int g, char* Wt) {
;   const int tid = TIDX;
;   for (int dg = 0; dg < 4; dg++) {
;     const int dir = dg >> 1;
;     const float* w = ((dg & 1) ? P.gate_x_w : P.gate_a_w) + ((size_t)((l * 2 + dir) * 4 + g)) * 4096;
;     for (int idx = tid; idx < 4096; idx += 256) { int i = idx >> 6, o = idx & 63; *(half_t*)(Wt + dg * 8192 + swz128(o, i)) = (half_t)w[idx]; }
;   }
; }
	v_cvt_f16_f32_e32 v58, v195
	v_xor_b32_e32 v57, 4, v56
	v_lshl_add_u32 v57, v57, 4, v55
	ds_write_b16 v57, v58 offset:8
	s_waitcnt vmcnt(53)
	v_cvt_f16_f32_e32 v58, v196
	v_xor_b32_e32 v57, 5, v56
	v_lshl_add_u32 v57, v57, 4, v55
	ds_write_b16 v57, v58 offset:0
	s_waitcnt vmcnt(52)
	v_cvt_f16_f32_e32 v58, v197
	v_xor_b32_e32 v57, 5, v56
	v_lshl_add_u32 v57, v57, 4, v55
	ds_write_b16 v57, v58 offset:8
	s_waitcnt vmcnt(51)
	v_cvt_f16_f32_e32 v58, v198
	v_xor_b32_e32 v57, 6, v56
	v_lshl_add_u32 v57, v57, 4, v55
	ds_write_b16 v57, v58 offset:0
	s_waitcnt vmcnt(50)
	v_cvt_f16_f32_e32 v58, v199
	v_xor_b32_e32 v57, 6, v56
	v_lshl_add_u32 v57, v57, 4, v55
	ds_write_b16 v57, v58 offset:8
	s_waitcnt vmcnt(49)
	v_cvt_f16_f32_e32 v58, v200
	v_xor_b32_e32 v57, 7, v56
	v_lshl_add_u32 v57, v57, 4, v55
	ds_write_b16 v57, v58 offset:0
	s_waitcnt vmcnt(48)
	v_cvt_f16_f32_e32 v58, v201
	v_xor_b32_e32 v57, 7, v56
	v_lshl_add_u32 v57, v57, 4, v55
	ds_write_b16 v57, v58 offset:8
	s_waitcnt vmcnt(47)
	v_cvt_f16_f32_e32 v58, v202
	v_xor_b32_e32 v57, 0, v56
	v_lshl_add_u32 v57, v57, 4, v55
	ds_write_b16 v57, v58 offset:8192
	s_waitcnt vmcnt(46)
	v_cvt_f16_f32_e32 v58, v203
	v_xor_b32_e32 v57, 0, v56
	v_lshl_add_u32 v57, v57, 4, v55
	ds_write_b16 v57, v58 offset:8200
	s_waitcnt vmcnt(45)
	v_cvt_f16_f32_e32 v58, v204
	v_xor_b32_e32 v57, 1, v56
	v_lshl_add_u32 v57, v57, 4, v55
	ds_write_b16 v57, v58 offset:8192
	s_waitcnt vmcnt(44)
	v_cvt_f16_f32_e32 v58, v205
	v_xor_b32_e32 v57, 1, v56
	v_lshl_add_u32 v57, v57, 4, v55
	ds_write_b16 v57, v58 offset:8200
	s_waitcnt vmcnt(43)
	v_cvt_f16_f32_e32 v58, v206
	v_xor_b32_e32 v57, 2, v56
	v_lshl_add_u32 v57, v57, 4, v55
	ds_write_b16 v57, v58 offset:8192
	s_waitcnt vmcnt(42)
	v_cvt_f16_f32_e32 v58, v207
	v_xor_b32_e32 v57, 2, v56
	v_lshl_add_u32 v57, v57, 4, v55
	ds_write_b16 v57, v58 offset:8200
	s_waitcnt vmcnt(41)
	v_cvt_f16_f32_e32 v58, v208
	v_xor_b32_e32 v57, 3, v56
	v_lshl_add_u32 v57, v57, 4, v55
	ds_write_b16 v57, v58 offset:8192
	s_waitcnt vmcnt(40)
	v_cvt_f16_f32_e32 v58, v209
	v_xor_b32_e32 v57, 3, v56
	v_lshl_add_u32 v57, v57, 4, v55
	ds_write_b16 v57, v58 offset:8200
	s_waitcnt vmcnt(39)
	v_cvt_f16_f32_e32 v58, v210
	v_xor_b32_e32 v57, 4, v56
	v_lshl_add_u32 v57, v57, 4, v55
	ds_write_b16 v57, v58 offset:8192
	s_waitcnt vmcnt(38)
	v_cvt_f16_f32_e32 v58, v211
	v_xor_b32_e32 v57, 4, v56
	v_lshl_add_u32 v57, v57, 4, v55
	ds_write_b16 v57, v58 offset:8200
	s_waitcnt vmcnt(37)
	v_cvt_f16_f32_e32 v58, v212
	v_xor_b32_e32 v57, 5, v56
	v_lshl_add_u32 v57, v57, 4, v55
	ds_write_b16 v57, v58 offset:8192
	s_waitcnt vmcnt(36)
	v_cvt_f16_f32_e32 v58, v213
	v_xor_b32_e32 v57, 5, v56
	v_lshl_add_u32 v57, v57, 4, v55
	ds_write_b16 v57, v58 offset:8200
	s_waitcnt vmcnt(35)
	v_cvt_f16_f32_e32 v58, v214
	v_xor_b32_e32 v57, 6, v56
	v_lshl_add_u32 v57, v57, 4, v55
	ds_write_b16 v57, v58 offset:8192
	s_waitcnt vmcnt(34)
	v_cvt_f16_f32_e32 v58, v215
	v_xor_b32_e32 v57, 6, v56
	v_lshl_add_u32 v57, v57, 4, v55
	ds_write_b16 v57, v58 offset:8200
	s_waitcnt vmcnt(33)
	v_cvt_f16_f32_e32 v58, v216
	v_xor_b32_e32 v57, 7, v56
	v_lshl_add_u32 v57, v57, 4, v55
	ds_write_b16 v57, v58 offset:8192
	s_waitcnt vmcnt(32)
	v_cvt_f16_f32_e32 v58, v217
	v_xor_b32_e32 v57, 7, v56
	v_lshl_add_u32 v57, v57, 4, v55
	ds_write_b16 v57, v58 offset:8200
	s_waitcnt vmcnt(31)
	v_cvt_f16_f32_e32 v58, v218
	v_xor_b32_e32 v57, 0, v56
	v_lshl_add_u32 v57, v57, 4, v55
	ds_write_b16 v57, v58 offset:16384
	s_waitcnt vmcnt(30)
	v_cvt_f16_f32_e32 v58, v219
	v_xor_b32_e32 v57, 0, v56
	v_lshl_add_u32 v57, v57, 4, v55
	ds_write_b16 v57, v58 offset:16392
	s_waitcnt vmcnt(29)
	v_cvt_f16_f32_e32 v58, v220
	v_xor_b32_e32 v57, 1, v56
	v_lshl_add_u32 v57, v57, 4, v55
	ds_write_b16 v57, v58 offset:16384
	s_waitcnt vmcnt(28)
	v_cvt_f16_f32_e32 v58, v221
	v_xor_b32_e32 v57, 1, v56
	v_lshl_add_u32 v57, v57, 4, v55
	ds_write_b16 v57, v58 offset:16392
	s_waitcnt vmcnt(27)
	v_cvt_f16_f32_e32 v58, v222
	v_xor_b32_e32 v57, 2, v56
	v_lshl_add_u32 v57, v57, 4, v55
	ds_write_b16 v57, v58 offset:16384
	s_waitcnt vmcnt(26)
; #define TIDX tid_opaque()
; DI void lru_load_w(const Params& P, int l, int g, char* Wt) {
;   const int tid = TIDX;
;   for (int dg = 0; dg < 4; dg++) {
;     const int dir = dg >> 1;
;     const float* w = ((dg & 1) ? P.gate_x_w : P.gate_a_w) + ((size_t)((l * 2 + dir) * 4 + g)) * 4096;
;     for (int idx = tid; idx < 4096; idx += 256) { int i = idx >> 6, o = idx & 63; *(half_t*)(Wt + dg * 8192 + swz128(o, i)) = (half_t)w[idx]; }
;   }
; }
	v_cvt_f16_f32_e32 v58, v223
	v_xor_b32_e32 v57, 2, v56
	v_lshl_add_u32 v57, v57, 4, v55
	ds_write_b16 v57, v58 offset:16392
	s_waitcnt vmcnt(25)
	v_cvt_f16_f32_e32 v58, v224
	v_xor_b32_e32 v57, 3, v56
	v_lshl_add_u32 v57, v57, 4, v55
	ds_write_b16 v57, v58 offset:16384
	s_waitcnt vmcnt(24)
	v_cvt_f16_f32_e32 v58, v225
	v_xor_b32_e32 v57, 3, v56
	v_lshl_add_u32 v57, v57, 4, v55
	ds_write_b16 v57, v58 offset:16392
	s_waitcnt vmcnt(23)
	v_cvt_f16_f32_e32 v58, v226
	v_xor_b32_e32 v57, 4, v56
	v_lshl_add_u32 v57, v57, 4, v55
	ds_write_b16 v57, v58 offset:16384
	s_waitcnt vmcnt(22)
	v_cvt_f16_f32_e32 v58, v227
	v_xor_b32_e32 v57, 4, v56
	v_lshl_add_u32 v57, v57, 4, v55
	ds_write_b16 v57, v58 offset:16392
	s_waitcnt vmcnt(21)
	v_cvt_f16_f32_e32 v58, v228
	v_xor_b32_e32 v57, 5, v56
	v_lshl_add_u32 v57, v57, 4, v55
	ds_write_b16 v57, v58 offset:16384
	s_waitcnt vmcnt(20)
	v_cvt_f16_f32_e32 v58, v229
	v_xor_b32_e32 v57, 5, v56
	v_lshl_add_u32 v57, v57, 4, v55
	ds_write_b16 v57, v58 offset:16392
	s_waitcnt vmcnt(19)
	v_cvt_f16_f32_e32 v58, v230
	v_xor_b32_e32 v57, 6, v56
	v_lshl_add_u32 v57, v57, 4, v55
	ds_write_b16 v57, v58 offset:16384
	s_waitcnt vmcnt(18)
	v_cvt_f16_f32_e32 v58, v231
	v_xor_b32_e32 v57, 6, v56
	v_lshl_add_u32 v57, v57, 4, v55
	ds_write_b16 v57, v58 offset:16392
	s_waitcnt vmcnt(17)
	v_cvt_f16_f32_e32 v58, v232
	v_xor_b32_e32 v57, 7, v56
	v_lshl_add_u32 v57, v57, 4, v55
	ds_write_b16 v57, v58 offset:16384
	s_waitcnt vmcnt(16)
	v_cvt_f16_f32_e32 v58, v233
	v_xor_b32_e32 v57, 7, v56
	v_lshl_add_u32 v57, v57, 4, v55
	ds_write_b16 v57, v58 offset:16392
	s_waitcnt vmcnt(15)
	v_cvt_f16_f32_e32 v58, v234
	v_xor_b32_e32 v57, 0, v56
	v_lshl_add_u32 v57, v57, 4, v55
	ds_write_b16 v57, v58 offset:24576
	s_waitcnt vmcnt(14)
	v_cvt_f16_f32_e32 v58, v235
	v_xor_b32_e32 v57, 0, v56
	v_lshl_add_u32 v57, v57, 4, v55
	ds_write_b16 v57, v58 offset:24584
	s_waitcnt vmcnt(13)
	v_cvt_f16_f32_e32 v58, v236
	v_xor_b32_e32 v57, 1, v56
	v_lshl_add_u32 v57, v57, 4, v55
	ds_write_b16 v57, v58 offset:24576
	s_waitcnt vmcnt(12)
	v_cvt_f16_f32_e32 v58, v237
	v_xor_b32_e32 v57, 1, v56
	v_lshl_add_u32 v57, v57, 4, v55
	ds_write_b16 v57, v58 offset:24584
	s_waitcnt vmcnt(11)
	v_cvt_f16_f32_e32 v58, v238
	v_xor_b32_e32 v57, 2, v56
	v_lshl_add_u32 v57, v57, 4, v55
	ds_write_b16 v57, v58 offset:24576
	s_waitcnt vmcnt(10)
	v_cvt_f16_f32_e32 v58, v239
	v_xor_b32_e32 v57, 2, v56
	v_lshl_add_u32 v57, v57, 4, v55
	ds_write_b16 v57, v58 offset:24584
	s_waitcnt vmcnt(9)
	v_cvt_f16_f32_e32 v58, v240
	v_xor_b32_e32 v57, 3, v56
	v_lshl_add_u32 v57, v57, 4, v55
	ds_write_b16 v57, v58 offset:24576
	s_waitcnt vmcnt(8)
	v_cvt_f16_f32_e32 v58, v241
	v_xor_b32_e32 v57, 3, v56
	v_lshl_add_u32 v57, v57, 4, v55
	ds_write_b16 v57, v58 offset:24584
	s_waitcnt vmcnt(7)
	v_cvt_f16_f32_e32 v58, v242
	v_xor_b32_e32 v57, 4, v56
	v_lshl_add_u32 v57, v57, 4, v55
	ds_write_b16 v57, v58 offset:24576
	s_waitcnt vmcnt(6)
	v_cvt_f16_f32_e32 v58, v243
	v_xor_b32_e32 v57, 4, v56
	v_lshl_add_u32 v57, v57, 4, v55
	ds_write_b16 v57, v58 offset:24584
	s_waitcnt vmcnt(5)
	v_cvt_f16_f32_e32 v58, v244
	v_xor_b32_e32 v57, 5, v56
	v_lshl_add_u32 v57, v57, 4, v55
	ds_write_b16 v57, v58 offset:24576
	s_waitcnt vmcnt(4)
	v_cvt_f16_f32_e32 v58, v245
	v_xor_b32_e32 v57, 5, v56
	v_lshl_add_u32 v57, v57, 4, v55
	ds_write_b16 v57, v58 offset:24584
	s_waitcnt vmcnt(3)
	v_cvt_f16_f32_e32 v58, v246
	v_xor_b32_e32 v57, 6, v56
	v_lshl_add_u32 v57, v57, 4, v55
	ds_write_b16 v57, v58 offset:24576
	s_waitcnt vmcnt(2)
	v_cvt_f16_f32_e32 v58, v247
	v_xor_b32_e32 v57, 6, v56
	v_lshl_add_u32 v57, v57, 4, v55
	ds_write_b16 v57, v58 offset:24584
	s_waitcnt vmcnt(1)
	v_cvt_f16_f32_e32 v58, v248
	v_xor_b32_e32 v57, 7, v56
	v_lshl_add_u32 v57, v57, 4, v55
	ds_write_b16 v57, v58 offset:24576
	s_waitcnt vmcnt(0)
	v_cvt_f16_f32_e32 v58, v249
	v_xor_b32_e32 v57, 7, v56
	v_lshl_add_u32 v57, v57, 4, v55
	ds_write_b16 v57, v58 offset:24584
	s_bitset1_b32 s84, 14

; #define TIDX tid_opaque()
; DI void lru_carry_item(const Params& P, int it) {
;   const int ch = TIDX, dir = it & 1;
;   const size_t base = (size_t)it * 132 * 256 + ch;
;   float c = 0.f;
; #pragma unroll 4
;   for (int k = 0; k < 132; k++) {
;     int tile = dir == 0 ? k : (k < 4 ? 3 - k : 135 - k);
;     float2 s = P.lsum[base + (size_t)tile * 256];
;     P.lcar[base + (size_t)tile * 256] = c;
;     c = s.x * c + s.y;
;   }
; }
.LBB0_469:
	s_and_b64 s[4:5], s[82:83], exec
	s_cselect_b32 s8, 0, -1
	s_xor_b32 s6, s8, 0x800
	s_sub_u32 s6, s6, s8
	s_xor_b32 s7, s8, 0x400
	s_sub_u32 s7, s7, s8
	v_lshlrev_b32_e32 v156, 3, v0
	v_lshlrev_b32_e32 v157, 2, v0
	s_and_b32 s2, s8, 3
	s_lshl_b32 s2, s2, 11
	s_add_u32 s2, s70, s2
	s_addc_u32 s3, s71, 0
	s_and_b32 s4, s8, 3
	s_lshl_b32 s4, s4, 10
	s_add_u32 s4, s64, s4
	s_addc_u32 s5, s65, 0
	global_load_dwordx2 v[186:187], v156, s[2:3]
	s_add_u32 s2, s2, s6
	s_addc_u32 s3, s3, s8
	global_load_dwordx2 v[188:189], v156, s[2:3]
	s_add_u32 s2, s2, s6
	s_addc_u32 s3, s3, s8
	global_load_dwordx2 v[190:191], v156, s[2:3]
	s_add_u32 s2, s2, s6
	s_addc_u32 s3, s3, s8
	global_load_dwordx2 v[192:193], v156, s[2:3]
	s_add_u32 s2, s2, s6
	s_addc_u32 s3, s3, s8
	s_and_b32 s2, s8, 0x7f
	s_add_u32 s2, s2, 4
	s_lshl_b32 s2, s2, 11
	s_add_u32 s2, s70, s2
	s_addc_u32 s3, s71, 0
	global_load_dwordx2 v[194:195], v156, s[2:3]
	s_add_u32 s2, s2, s6
	s_addc_u32 s3, s3, s8
	global_load_dwordx2 v[196:197], v156, s[2:3]
	s_add_u32 s2, s2, s6
	s_addc_u32 s3, s3, s8
	global_load_dwordx2 v[198:199], v156, s[2:3]
	s_add_u32 s2, s2, s6
	s_addc_u32 s3, s3, s8
	global_load_dwordx2 v[200:201], v156, s[2:3]
	s_add_u32 s2, s2, s6
	s_addc_u32 s3, s3, s8
	global_load_dwordx2 v[202:203], v156, s[2:3]
	s_add_u32 s2, s2, s6
	s_addc_u32 s3, s3, s8
	global_load_dwordx2 v[204:205], v156, s[2:3]
	s_add_u32 s2, s2, s6
	s_addc_u32 s3, s3, s8
	global_load_dwordx2 v[206:207], v156, s[2:3]
	s_add_u32 s2, s2, s6
	s_addc_u32 s3, s3, s8
	global_load_dwordx2 v[208:209], v156, s[2:3]
	s_add_u32 s2, s2, s6
	s_addc_u32 s3, s3, s8
	global_load_dwordx2 v[210:211], v156, s[2:3]
	s_add_u32 s2, s2, s6
	s_addc_u32 s3, s3, s8
	global_load_dwordx2 v[212:213], v156, s[2:3]
	s_add_u32 s2, s2, s6
	s_addc_u32 s3, s3, s8
	global_load_dwordx2 v[214:215], v156, s[2:3]
	s_add_u32 s2, s2, s6
	s_addc_u32 s3, s3, s8
	global_load_dwordx2 v[216:217], v156, s[2:3]
	s_add_u32 s2, s2, s6
	s_addc_u32 s3, s3, s8
	global_load_dwordx2 v[218:219], v156, s[2:3]
	s_add_u32 s2, s2, s6
	s_addc_u32 s3, s3, s8
	global_load_dwordx2 v[220:221], v156, s[2:3]
	s_add_u32 s2, s2, s6
	s_addc_u32 s3, s3, s8
	global_load_dwordx2 v[222:223], v156, s[2:3]
	s_add_u32 s2, s2, s6
	s_addc_u32 s3, s3, s8
	global_load_dwordx2 v[224:225], v156, s[2:3]
	s_add_u32 s2, s2, s6
	s_addc_u32 s3, s3, s8
	global_load_dwordx2 v[226:227], v156, s[2:3]
	s_add_u32 s2, s2, s6
	s_addc_u32 s3, s3, s8
	global_load_dwordx2 v[228:229], v156, s[2:3]
	s_add_u32 s2, s2, s6
	s_addc_u32 s3, s3, s8
	global_load_dwordx2 v[230:231], v156, s[2:3]
	s_add_u32 s2, s2, s6
	s_addc_u32 s3, s3, s8
	global_load_dwordx2 v[232:233], v156, s[2:3]
	s_add_u32 s2, s2, s6
	s_addc_u32 s3, s3, s8
	global_load_dwordx2 v[234:235], v156, s[2:3]
	s_add_u32 s2, s2, s6
	s_addc_u32 s3, s3, s8
	global_load_dwordx2 v[236:237], v156, s[2:3]
	s_add_u32 s2, s2, s6
	s_addc_u32 s3, s3, s8
	global_load_dwordx2 v[238:239], v156, s[2:3]
	s_add_u32 s2, s2, s6
	s_addc_u32 s3, s3, s8
	global_load_dwordx2 v[240:241], v156, s[2:3]
	s_add_u32 s2, s2, s6
	s_addc_u32 s3, s3, s8
	global_load_dwordx2 v[242:243], v156, s[2:3]
	s_add_u32 s2, s2, s6
	s_addc_u32 s3, s3, s8
	global_load_dwordx2 v[244:245], v156, s[2:3]
	s_add_u32 s2, s2, s6
	s_addc_u32 s3, s3, s8
	global_load_dwordx2 v[246:247], v156, s[2:3]
	s_add_u32 s2, s2, s6
	s_addc_u32 s3, s3, s8
	global_load_dwordx2 v[248:249], v156, s[2:3]
	s_add_u32 s2, s2, s6
	s_addc_u32 s3, s3, s8
	global_load_dwordx2 v[250:251], v156, s[2:3]
	s_add_u32 s2, s2, s6
	s_addc_u32 s3, s3, s8
	s_waitcnt vmcnt(32)
	global_store_dword v157, v3, s[4:5]
	v_fma_f32 v158, v186, v3, v187
	s_add_u32 s4, s4, s7
	s_addc_u32 s5, s5, s8
	s_waitcnt vmcnt(32)
	global_store_dword v157, v158, s[4:5]
	v_fma_f32 v3, v188, v158, v189
	s_add_u32 s4, s4, s7
	s_addc_u32 s5, s5, s8
	s_waitcnt vmcnt(32)
	global_store_dword v157, v3, s[4:5]
	v_fma_f32 v158, v190, v3, v191
	s_add_u32 s4, s4, s7
	s_addc_u32 s5, s5, s8
	s_waitcnt vmcnt(32)
	global_store_dword v157, v158, s[4:5]
	v_fma_f32 v3, v192, v158, v193
	s_add_u32 s4, s4, s7
	s_addc_u32 s5, s5, s8
	s_and_b32 s4, s8, 0x7f
	s_add_u32 s4, s4, 4
	s_lshl_b32 s4, s4, 10
	s_add_u32 s4, s64, s4
	s_addc_u32 s5, s65, 0
	s_waitcnt vmcnt(32)
	global_store_dword v157, v3, s[4:5]
	v_fma_f32 v158, v194, v3, v195
	s_add_u32 s4, s4, s7
	s_addc_u32 s5, s5, s8
	s_waitcnt vmcnt(32)
	global_store_dword v157, v158, s[4:5]
	v_fma_f32 v3, v196, v158, v197
	s_add_u32 s4, s4, s7
	s_addc_u32 s5, s5, s8
	s_waitcnt vmcnt(32)
	global_store_dword v157, v3, s[4:5]
	v_fma_f32 v158, v198, v3, v199
	s_add_u32 s4, s4, s7
	s_addc_u32 s5, s5, s8
	s_waitcnt vmcnt(32)
	global_store_dword v157, v158, s[4:5]
	v_fma_f32 v3, v200, v158, v201
	s_add_u32 s4, s4, s7
	s_addc_u32 s5, s5, s8
	s_waitcnt vmcnt(32)
	global_store_dword v157, v3, s[4:5]
	v_fma_f32 v158, v202, v3, v203
	s_add_u32 s4, s4, s7
	s_addc_u32 s5, s5, s8
	s_waitcnt vmcnt(32)
	global_store_dword v157, v158, s[4:5]
	v_fma_f32 v3, v204, v158, v205
	s_add_u32 s4, s4, s7
	s_addc_u32 s5, s5, s8
	s_waitcnt vmcnt(32)
	global_store_dword v157, v3, s[4:5]
	v_fma_f32 v158, v206, v3, v207
	s_add_u32 s4, s4, s7
	s_addc_u32 s5, s5, s8
	s_waitcnt vmcnt(32)
	global_store_dword v157, v158, s[4:5]
	v_fma_f32 v3, v208, v158, v209
	s_add_u32 s4, s4, s7
	s_addc_u32 s5, s5, s8
	s_waitcnt vmcnt(32)
	global_store_dword v157, v3, s[4:5]
	v_fma_f32 v158, v210, v3, v211
	s_add_u32 s4, s4, s7
	s_addc_u32 s5, s5, s8
	s_waitcnt vmcnt(32)
	global_store_dword v157, v158, s[4:5]
	v_fma_f32 v3, v212, v158, v213
	s_add_u32 s4, s4, s7
	s_addc_u32 s5, s5, s8
	s_waitcnt vmcnt(32)
	global_store_dword v157, v3, s[4:5]
	v_fma_f32 v158, v214, v3, v215
	s_add_u32 s4, s4, s7
	s_addc_u32 s5, s5, s8
	s_waitcnt vmcnt(32)
; #define TIDX tid_opaque()
; DI void lru_carry_item(const Params& P, int it) {
;   const int ch = TIDX, dir = it & 1;
;   const size_t base = (size_t)it * 132 * 256 + ch;
;   float c = 0.f;
; #pragma unroll 4
;   for (int k = 0; k < 132; k++) {
;     int tile = dir == 0 ? k : (k < 4 ? 3 - k : 135 - k);
;     float2 s = P.lsum[base + (size_t)tile * 256];
;     P.lcar[base + (size_t)tile * 256] = c;
;     c = s.x * c + s.y;
;   }
; }
	global_store_dword v157, v158, s[4:5]
	v_fma_f32 v3, v216, v158, v217
	s_add_u32 s4, s4, s7
	s_addc_u32 s5, s5, s8
	s_waitcnt vmcnt(32)
	global_store_dword v157, v3, s[4:5]
	v_fma_f32 v158, v218, v3, v219
	s_add_u32 s4, s4, s7
	s_addc_u32 s5, s5, s8
	s_waitcnt vmcnt(32)
	global_store_dword v157, v158, s[4:5]
	v_fma_f32 v3, v220, v158, v221
	s_add_u32 s4, s4, s7
	s_addc_u32 s5, s5, s8
	s_waitcnt vmcnt(32)
	global_store_dword v157, v3, s[4:5]
	v_fma_f32 v158, v222, v3, v223
	s_add_u32 s4, s4, s7
	s_addc_u32 s5, s5, s8
	s_waitcnt vmcnt(32)
	global_store_dword v157, v158, s[4:5]
	v_fma_f32 v3, v224, v158, v225
	s_add_u32 s4, s4, s7
	s_addc_u32 s5, s5, s8
	s_waitcnt vmcnt(32)
	global_store_dword v157, v3, s[4:5]
	v_fma_f32 v158, v226, v3, v227
	s_add_u32 s4, s4, s7
	s_addc_u32 s5, s5, s8
	s_waitcnt vmcnt(32)
	global_store_dword v157, v158, s[4:5]
	v_fma_f32 v3, v228, v158, v229
	s_add_u32 s4, s4, s7
	s_addc_u32 s5, s5, s8
	s_waitcnt vmcnt(32)
	global_store_dword v157, v3, s[4:5]
	v_fma_f32 v158, v230, v3, v231
	s_add_u32 s4, s4, s7
	s_addc_u32 s5, s5, s8
	s_waitcnt vmcnt(32)
	global_store_dword v157, v158, s[4:5]
	v_fma_f32 v3, v232, v158, v233
	s_add_u32 s4, s4, s7
	s_addc_u32 s5, s5, s8
	s_waitcnt vmcnt(32)
	global_store_dword v157, v3, s[4:5]
	v_fma_f32 v158, v234, v3, v235
	s_add_u32 s4, s4, s7
	s_addc_u32 s5, s5, s8
	s_waitcnt vmcnt(32)
	global_store_dword v157, v158, s[4:5]
	v_fma_f32 v3, v236, v158, v237
	s_add_u32 s4, s4, s7
	s_addc_u32 s5, s5, s8
	s_waitcnt vmcnt(32)
	global_store_dword v157, v3, s[4:5]
	v_fma_f32 v158, v238, v3, v239
	s_add_u32 s4, s4, s7
	s_addc_u32 s5, s5, s8
	s_waitcnt vmcnt(32)
	global_store_dword v157, v158, s[4:5]
	v_fma_f32 v3, v240, v158, v241
	s_add_u32 s4, s4, s7
	s_addc_u32 s5, s5, s8
	s_waitcnt vmcnt(32)
	global_store_dword v157, v3, s[4:5]
	v_fma_f32 v158, v242, v3, v243
	s_add_u32 s4, s4, s7
	s_addc_u32 s5, s5, s8
	s_waitcnt vmcnt(32)
	global_store_dword v157, v158, s[4:5]
	v_fma_f32 v3, v244, v158, v245
	s_add_u32 s4, s4, s7
	s_addc_u32 s5, s5, s8
	s_waitcnt vmcnt(32)
	global_store_dword v157, v3, s[4:5]
	v_fma_f32 v158, v246, v3, v247
	s_add_u32 s4, s4, s7
	s_addc_u32 s5, s5, s8
	s_waitcnt vmcnt(32)
	global_store_dword v157, v158, s[4:5]
	v_fma_f32 v3, v248, v158, v249
	s_add_u32 s4, s4, s7
	s_addc_u32 s5, s5, s8
	s_waitcnt vmcnt(32)
	global_store_dword v157, v3, s[4:5]
	v_fma_f32 v158, v250, v3, v251
	s_add_u32 s4, s4, s7
	s_addc_u32 s5, s5, s8
	global_load_dwordx2 v[186:187], v156, s[2:3]
	s_add_u32 s2, s2, s6
	s_addc_u32 s3, s3, s8
	global_load_dwordx2 v[188:189], v156, s[2:3]
	s_add_u32 s2, s2, s6
	s_addc_u32 s3, s3, s8
	global_load_dwordx2 v[190:191], v156, s[2:3]
	s_add_u32 s2, s2, s6
	s_addc_u32 s3, s3, s8
	global_load_dwordx2 v[192:193], v156, s[2:3]
	s_add_u32 s2, s2, s6
	s_addc_u32 s3, s3, s8
	global_load_dwordx2 v[194:195], v156, s[2:3]
	s_add_u32 s2, s2, s6
	s_addc_u32 s3, s3, s8
	global_load_dwordx2 v[196:197], v156, s[2:3]
	s_add_u32 s2, s2, s6
	s_addc_u32 s3, s3, s8
	global_load_dwordx2 v[198:199], v156, s[2:3]
	s_add_u32 s2, s2, s6
	s_addc_u32 s3, s3, s8
	global_load_dwordx2 v[200:201], v156, s[2:3]
	s_add_u32 s2, s2, s6
	s_addc_u32 s3, s3, s8
	global_load_dwordx2 v[202:203], v156, s[2:3]
	s_add_u32 s2, s2, s6
	s_addc_u32 s3, s3, s8
	global_load_dwordx2 v[204:205], v156, s[2:3]
	s_add_u32 s2, s2, s6
	s_addc_u32 s3, s3, s8
	global_load_dwordx2 v[206:207], v156, s[2:3]
	s_add_u32 s2, s2, s6
	s_addc_u32 s3, s3, s8
	global_load_dwordx2 v[208:209], v156, s[2:3]
	s_add_u32 s2, s2, s6
	s_addc_u32 s3, s3, s8
	global_load_dwordx2 v[210:211], v156, s[2:3]
	s_add_u32 s2, s2, s6
	s_addc_u32 s3, s3, s8
	global_load_dwordx2 v[212:213], v156, s[2:3]
	s_add_u32 s2, s2, s6
	s_addc_u32 s3, s3, s8
	global_load_dwordx2 v[214:215], v156, s[2:3]
	s_add_u32 s2, s2, s6
	s_addc_u32 s3, s3, s8
	global_load_dwordx2 v[216:217], v156, s[2:3]
	s_add_u32 s2, s2, s6
	s_addc_u32 s3, s3, s8
	global_load_dwordx2 v[218:219], v156, s[2:3]
	s_add_u32 s2, s2, s6
	s_addc_u32 s3, s3, s8
	global_load_dwordx2 v[220:221], v156, s[2:3]
	s_add_u32 s2, s2, s6
	s_addc_u32 s3, s3, s8
	global_load_dwordx2 v[222:223], v156, s[2:3]
	s_add_u32 s2, s2, s6
	s_addc_u32 s3, s3, s8
	global_load_dwordx2 v[224:225], v156, s[2:3]
	s_add_u32 s2, s2, s6
	s_addc_u32 s3, s3, s8
	global_load_dwordx2 v[226:227], v156, s[2:3]
	s_add_u32 s2, s2, s6
	s_addc_u32 s3, s3, s8
	global_load_dwordx2 v[228:229], v156, s[2:3]
	s_add_u32 s2, s2, s6
	s_addc_u32 s3, s3, s8
	global_load_dwordx2 v[230:231], v156, s[2:3]
	s_add_u32 s2, s2, s6
	s_addc_u32 s3, s3, s8
	global_load_dwordx2 v[232:233], v156, s[2:3]
	s_add_u32 s2, s2, s6
	s_addc_u32 s3, s3, s8
	global_load_dwordx2 v[234:235], v156, s[2:3]
	s_add_u32 s2, s2, s6
	s_addc_u32 s3, s3, s8
	global_load_dwordx2 v[236:237], v156, s[2:3]
	s_add_u32 s2, s2, s6
	s_addc_u32 s3, s3, s8
	global_load_dwordx2 v[238:239], v156, s[2:3]
	s_add_u32 s2, s2, s6
	s_addc_u32 s3, s3, s8
	global_load_dwordx2 v[240:241], v156, s[2:3]
	s_add_u32 s2, s2, s6
	s_addc_u32 s3, s3, s8
	global_load_dwordx2 v[242:243], v156, s[2:3]
	s_add_u32 s2, s2, s6
	s_addc_u32 s3, s3, s8
	global_load_dwordx2 v[244:245], v156, s[2:3]
	s_add_u32 s2, s2, s6
	s_addc_u32 s3, s3, s8
	global_load_dwordx2 v[246:247], v156, s[2:3]
	s_add_u32 s2, s2, s6
	s_addc_u32 s3, s3, s8
	global_load_dwordx2 v[248:249], v156, s[2:3]
	s_add_u32 s2, s2, s6
	s_addc_u32 s3, s3, s8
	global_load_dwordx2 v[250:251], v156, s[2:3]
	s_add_u32 s2, s2, s6
	s_addc_u32 s3, s3, s8
	s_waitcnt vmcnt(32)
	global_store_dword v157, v158, s[4:5]
	v_fma_f32 v3, v186, v158, v187
	s_add_u32 s4, s4, s7
	s_addc_u32 s5, s5, s8
	s_waitcnt vmcnt(32)
; #define TIDX tid_opaque()
; DI void lru_carry_item(const Params& P, int it) {
;   const int ch = TIDX, dir = it & 1;
;   const size_t base = (size_t)it * 132 * 256 + ch;
;   float c = 0.f;
; #pragma unroll 4
;   for (int k = 0; k < 132; k++) {
;     int tile = dir == 0 ? k : (k < 4 ? 3 - k : 135 - k);
;     float2 s = P.lsum[base + (size_t)tile * 256];
;     P.lcar[base + (size_t)tile * 256] = c;
;     c = s.x * c + s.y;
;   }
; }
	global_store_dword v157, v3, s[4:5]
	v_fma_f32 v158, v188, v3, v189
	s_add_u32 s4, s4, s7
	s_addc_u32 s5, s5, s8
	s_waitcnt vmcnt(32)
	global_store_dword v157, v158, s[4:5]
	v_fma_f32 v3, v190, v158, v191
	s_add_u32 s4, s4, s7
	s_addc_u32 s5, s5, s8
	s_waitcnt vmcnt(32)
	global_store_dword v157, v3, s[4:5]
	v_fma_f32 v158, v192, v3, v193
	s_add_u32 s4, s4, s7
	s_addc_u32 s5, s5, s8
	s_waitcnt vmcnt(32)
	global_store_dword v157, v158, s[4:5]
	v_fma_f32 v3, v194, v158, v195
	s_add_u32 s4, s4, s7
	s_addc_u32 s5, s5, s8
	s_waitcnt vmcnt(32)
	global_store_dword v157, v3, s[4:5]
	v_fma_f32 v158, v196, v3, v197
	s_add_u32 s4, s4, s7
	s_addc_u32 s5, s5, s8
	s_waitcnt vmcnt(32)
	global_store_dword v157, v158, s[4:5]
	v_fma_f32 v3, v198, v158, v199
	s_add_u32 s4, s4, s7
	s_addc_u32 s5, s5, s8
	s_waitcnt vmcnt(32)
	global_store_dword v157, v3, s[4:5]
	v_fma_f32 v158, v200, v3, v201
	s_add_u32 s4, s4, s7
	s_addc_u32 s5, s5, s8
	s_waitcnt vmcnt(32)
	global_store_dword v157, v158, s[4:5]
	v_fma_f32 v3, v202, v158, v203
	s_add_u32 s4, s4, s7
	s_addc_u32 s5, s5, s8
	s_waitcnt vmcnt(32)
	global_store_dword v157, v3, s[4:5]
	v_fma_f32 v158, v204, v3, v205
	s_add_u32 s4, s4, s7
	s_addc_u32 s5, s5, s8
	s_waitcnt vmcnt(32)
	global_store_dword v157, v158, s[4:5]
	v_fma_f32 v3, v206, v158, v207
	s_add_u32 s4, s4, s7
	s_addc_u32 s5, s5, s8
	s_waitcnt vmcnt(32)
	global_store_dword v157, v3, s[4:5]
	v_fma_f32 v158, v208, v3, v209
	s_add_u32 s4, s4, s7
	s_addc_u32 s5, s5, s8
	s_waitcnt vmcnt(32)
	global_store_dword v157, v158, s[4:5]
	v_fma_f32 v3, v210, v158, v211
	s_add_u32 s4, s4, s7
	s_addc_u32 s5, s5, s8
	s_waitcnt vmcnt(32)
	global_store_dword v157, v3, s[4:5]
	v_fma_f32 v158, v212, v3, v213
	s_add_u32 s4, s4, s7
	s_addc_u32 s5, s5, s8
	s_waitcnt vmcnt(32)
	global_store_dword v157, v158, s[4:5]
	v_fma_f32 v3, v214, v158, v215
	s_add_u32 s4, s4, s7
	s_addc_u32 s5, s5, s8
	s_waitcnt vmcnt(32)
	global_store_dword v157, v3, s[4:5]
	v_fma_f32 v158, v216, v3, v217
	s_add_u32 s4, s4, s7
	s_addc_u32 s5, s5, s8
	s_waitcnt vmcnt(32)
	global_store_dword v157, v158, s[4:5]
	v_fma_f32 v3, v218, v158, v219
	s_add_u32 s4, s4, s7
	s_addc_u32 s5, s5, s8
	s_waitcnt vmcnt(32)
	global_store_dword v157, v3, s[4:5]
	v_fma_f32 v158, v220, v3, v221
	s_add_u32 s4, s4, s7
	s_addc_u32 s5, s5, s8
	s_waitcnt vmcnt(32)
	global_store_dword v157, v158, s[4:5]
	v_fma_f32 v3, v222, v158, v223
	s_add_u32 s4, s4, s7
	s_addc_u32 s5, s5, s8
	s_waitcnt vmcnt(32)
	global_store_dword v157, v3, s[4:5]
	v_fma_f32 v158, v224, v3, v225
	s_add_u32 s4, s4, s7
	s_addc_u32 s5, s5, s8
	s_waitcnt vmcnt(32)
	global_store_dword v157, v158, s[4:5]
	v_fma_f32 v3, v226, v158, v227
	s_add_u32 s4, s4, s7
	s_addc_u32 s5, s5, s8
	s_waitcnt vmcnt(32)
	global_store_dword v157, v3, s[4:5]
	v_fma_f32 v158, v228, v3, v229
	s_add_u32 s4, s4, s7
	s_addc_u32 s5, s5, s8
	s_waitcnt vmcnt(32)
	global_store_dword v157, v158, s[4:5]
	v_fma_f32 v3, v230, v158, v231
	s_add_u32 s4, s4, s7
	s_addc_u32 s5, s5, s8
	s_waitcnt vmcnt(32)
	global_store_dword v157, v3, s[4:5]
	v_fma_f32 v158, v232, v3, v233
	s_add_u32 s4, s4, s7
	s_addc_u32 s5, s5, s8
	s_waitcnt vmcnt(32)
	global_store_dword v157, v158, s[4:5]
	v_fma_f32 v3, v234, v158, v235
	s_add_u32 s4, s4, s7
	s_addc_u32 s5, s5, s8
	s_waitcnt vmcnt(32)
	global_store_dword v157, v3, s[4:5]
	v_fma_f32 v158, v236, v3, v237
	s_add_u32 s4, s4, s7
	s_addc_u32 s5, s5, s8
	s_waitcnt vmcnt(32)
	global_store_dword v157, v158, s[4:5]
	v_fma_f32 v3, v238, v158, v239
	s_add_u32 s4, s4, s7
	s_addc_u32 s5, s5, s8
	s_waitcnt vmcnt(32)
	global_store_dword v157, v3, s[4:5]
	v_fma_f32 v158, v240, v3, v241
	s_add_u32 s4, s4, s7
	s_addc_u32 s5, s5, s8
	s_waitcnt vmcnt(32)
	global_store_dword v157, v158, s[4:5]
	v_fma_f32 v3, v242, v158, v243
	s_add_u32 s4, s4, s7
	s_addc_u32 s5, s5, s8
	s_waitcnt vmcnt(32)
	global_store_dword v157, v3, s[4:5]
	v_fma_f32 v158, v244, v3, v245
	s_add_u32 s4, s4, s7
	s_addc_u32 s5, s5, s8
	s_waitcnt vmcnt(32)
	global_store_dword v157, v158, s[4:5]
	v_fma_f32 v3, v246, v158, v247
	s_add_u32 s4, s4, s7
	s_addc_u32 s5, s5, s8
	s_waitcnt vmcnt(32)
	global_store_dword v157, v3, s[4:5]
	v_fma_f32 v158, v248, v3, v249
	s_add_u32 s4, s4, s7
	s_addc_u32 s5, s5, s8
	s_waitcnt vmcnt(32)
	global_store_dword v157, v158, s[4:5]
	v_fma_f32 v3, v250, v158, v251
	s_add_u32 s4, s4, s7
	s_addc_u32 s5, s5, s8
	global_load_dwordx2 v[186:187], v156, s[2:3]
	s_add_u32 s2, s2, s6
	s_addc_u32 s3, s3, s8
	global_load_dwordx2 v[188:189], v156, s[2:3]
	s_add_u32 s2, s2, s6
	s_addc_u32 s3, s3, s8
	global_load_dwordx2 v[190:191], v156, s[2:3]
	s_add_u32 s2, s2, s6
	s_addc_u32 s3, s3, s8
	global_load_dwordx2 v[192:193], v156, s[2:3]
	s_add_u32 s2, s2, s6
	s_addc_u32 s3, s3, s8
	global_load_dwordx2 v[194:195], v156, s[2:3]
	s_add_u32 s2, s2, s6
	s_addc_u32 s3, s3, s8
	global_load_dwordx2 v[196:197], v156, s[2:3]
	s_add_u32 s2, s2, s6
	s_addc_u32 s3, s3, s8
	global_load_dwordx2 v[198:199], v156, s[2:3]
	s_add_u32 s2, s2, s6
	s_addc_u32 s3, s3, s8
	global_load_dwordx2 v[200:201], v156, s[2:3]
	s_add_u32 s2, s2, s6
	s_addc_u32 s3, s3, s8
	global_load_dwordx2 v[202:203], v156, s[2:3]
	s_add_u32 s2, s2, s6
	s_addc_u32 s3, s3, s8
	global_load_dwordx2 v[204:205], v156, s[2:3]
	s_add_u32 s2, s2, s6
	s_addc_u32 s3, s3, s8
	global_load_dwordx2 v[206:207], v156, s[2:3]
	s_add_u32 s2, s2, s6
	s_addc_u32 s3, s3, s8
	global_load_dwordx2 v[208:209], v156, s[2:3]
	s_add_u32 s2, s2, s6
	s_addc_u32 s3, s3, s8
	global_load_dwordx2 v[210:211], v156, s[2:3]
	s_add_u32 s2, s2, s6
	s_addc_u32 s3, s3, s8
	global_load_dwordx2 v[212:213], v156, s[2:3]
	s_add_u32 s2, s2, s6
	s_addc_u32 s3, s3, s8
	global_load_dwordx2 v[214:215], v156, s[2:3]
; #define TIDX tid_opaque()
; DI void lru_carry_item(const Params& P, int it) {
;   const int ch = TIDX, dir = it & 1;
;   const size_t base = (size_t)it * 132 * 256 + ch;
;   float c = 0.f;
; #pragma unroll 4
;   for (int k = 0; k < 132; k++) {
;     int tile = dir == 0 ? k : (k < 4 ? 3 - k : 135 - k);
;     float2 s = P.lsum[base + (size_t)tile * 256];
;     P.lcar[base + (size_t)tile * 256] = c;
;     c = s.x * c + s.y;
;   }
; }
	s_add_u32 s2, s2, s6
	s_addc_u32 s3, s3, s8
	global_load_dwordx2 v[216:217], v156, s[2:3]
	s_add_u32 s2, s2, s6
	s_addc_u32 s3, s3, s8
	global_load_dwordx2 v[218:219], v156, s[2:3]
	s_add_u32 s2, s2, s6
	s_addc_u32 s3, s3, s8
	global_load_dwordx2 v[220:221], v156, s[2:3]
	s_add_u32 s2, s2, s6
	s_addc_u32 s3, s3, s8
	global_load_dwordx2 v[222:223], v156, s[2:3]
	s_add_u32 s2, s2, s6
	s_addc_u32 s3, s3, s8
	global_load_dwordx2 v[224:225], v156, s[2:3]
	s_add_u32 s2, s2, s6
	s_addc_u32 s3, s3, s8
	global_load_dwordx2 v[226:227], v156, s[2:3]
	s_add_u32 s2, s2, s6
	s_addc_u32 s3, s3, s8
	global_load_dwordx2 v[228:229], v156, s[2:3]
	s_add_u32 s2, s2, s6
	s_addc_u32 s3, s3, s8
	global_load_dwordx2 v[230:231], v156, s[2:3]
	s_add_u32 s2, s2, s6
	s_addc_u32 s3, s3, s8
	global_load_dwordx2 v[232:233], v156, s[2:3]
	s_add_u32 s2, s2, s6
	s_addc_u32 s3, s3, s8
	global_load_dwordx2 v[234:235], v156, s[2:3]
	s_add_u32 s2, s2, s6
	s_addc_u32 s3, s3, s8
	global_load_dwordx2 v[236:237], v156, s[2:3]
	s_add_u32 s2, s2, s6
	s_addc_u32 s3, s3, s8
	global_load_dwordx2 v[238:239], v156, s[2:3]
	s_add_u32 s2, s2, s6
	s_addc_u32 s3, s3, s8
	global_load_dwordx2 v[240:241], v156, s[2:3]
	s_add_u32 s2, s2, s6
	s_addc_u32 s3, s3, s8
	global_load_dwordx2 v[242:243], v156, s[2:3]
	s_add_u32 s2, s2, s6
	s_addc_u32 s3, s3, s8
	global_load_dwordx2 v[244:245], v156, s[2:3]
	s_add_u32 s2, s2, s6
	s_addc_u32 s3, s3, s8
	global_load_dwordx2 v[246:247], v156, s[2:3]
	s_add_u32 s2, s2, s6
	s_addc_u32 s3, s3, s8
	global_load_dwordx2 v[248:249], v156, s[2:3]
	s_add_u32 s2, s2, s6
	s_addc_u32 s3, s3, s8
	global_load_dwordx2 v[250:251], v156, s[2:3]
	s_add_u32 s2, s2, s6
	s_addc_u32 s3, s3, s8
	s_waitcnt vmcnt(32)
	global_store_dword v157, v3, s[4:5]
	v_fma_f32 v158, v186, v3, v187
	s_add_u32 s4, s4, s7
	s_addc_u32 s5, s5, s8
	s_waitcnt vmcnt(32)
	global_store_dword v157, v158, s[4:5]
	v_fma_f32 v3, v188, v158, v189
	s_add_u32 s4, s4, s7
	s_addc_u32 s5, s5, s8
	s_waitcnt vmcnt(32)
	global_store_dword v157, v3, s[4:5]
	v_fma_f32 v158, v190, v3, v191
	s_add_u32 s4, s4, s7
	s_addc_u32 s5, s5, s8
	s_waitcnt vmcnt(32)
	global_store_dword v157, v158, s[4:5]
	v_fma_f32 v3, v192, v158, v193
	s_add_u32 s4, s4, s7
	s_addc_u32 s5, s5, s8
	s_waitcnt vmcnt(32)
	global_store_dword v157, v3, s[4:5]
	v_fma_f32 v158, v194, v3, v195
	s_add_u32 s4, s4, s7
	s_addc_u32 s5, s5, s8
	s_waitcnt vmcnt(32)
	global_store_dword v157, v158, s[4:5]
	v_fma_f32 v3, v196, v158, v197
	s_add_u32 s4, s4, s7
	s_addc_u32 s5, s5, s8
	s_waitcnt vmcnt(32)
	global_store_dword v157, v3, s[4:5]
	v_fma_f32 v158, v198, v3, v199
	s_add_u32 s4, s4, s7
	s_addc_u32 s5, s5, s8
	s_waitcnt vmcnt(32)
	global_store_dword v157, v158, s[4:5]
	v_fma_f32 v3, v200, v158, v201
	s_add_u32 s4, s4, s7
	s_addc_u32 s5, s5, s8
	s_waitcnt vmcnt(32)
	global_store_dword v157, v3, s[4:5]
	v_fma_f32 v158, v202, v3, v203
	s_add_u32 s4, s4, s7
	s_addc_u32 s5, s5, s8
	s_waitcnt vmcnt(32)
	global_store_dword v157, v158, s[4:5]
	v_fma_f32 v3, v204, v158, v205
	s_add_u32 s4, s4, s7
	s_addc_u32 s5, s5, s8
	s_waitcnt vmcnt(32)
	global_store_dword v157, v3, s[4:5]
	v_fma_f32 v158, v206, v3, v207
	s_add_u32 s4, s4, s7
	s_addc_u32 s5, s5, s8
	s_waitcnt vmcnt(32)
	global_store_dword v157, v158, s[4:5]
	v_fma_f32 v3, v208, v158, v209
	s_add_u32 s4, s4, s7
	s_addc_u32 s5, s5, s8
	s_waitcnt vmcnt(32)
	global_store_dword v157, v3, s[4:5]
	v_fma_f32 v158, v210, v3, v211
	s_add_u32 s4, s4, s7
	s_addc_u32 s5, s5, s8
	s_waitcnt vmcnt(32)
	global_store_dword v157, v158, s[4:5]
	v_fma_f32 v3, v212, v158, v213
	s_add_u32 s4, s4, s7
	s_addc_u32 s5, s5, s8
	s_waitcnt vmcnt(32)
	global_store_dword v157, v3, s[4:5]
	v_fma_f32 v158, v214, v3, v215
	s_add_u32 s4, s4, s7
	s_addc_u32 s5, s5, s8
	s_waitcnt vmcnt(32)
	global_store_dword v157, v158, s[4:5]
	v_fma_f32 v3, v216, v158, v217
	s_add_u32 s4, s4, s7
	s_addc_u32 s5, s5, s8
	s_waitcnt vmcnt(32)
	global_store_dword v157, v3, s[4:5]
	v_fma_f32 v158, v218, v3, v219
	s_add_u32 s4, s4, s7
	s_addc_u32 s5, s5, s8
	s_waitcnt vmcnt(32)
	global_store_dword v157, v158, s[4:5]
	v_fma_f32 v3, v220, v158, v221
	s_add_u32 s4, s4, s7
	s_addc_u32 s5, s5, s8
	s_waitcnt vmcnt(32)
	global_store_dword v157, v3, s[4:5]
	v_fma_f32 v158, v222, v3, v223
	s_add_u32 s4, s4, s7
	s_addc_u32 s5, s5, s8
	s_waitcnt vmcnt(32)
	global_store_dword v157, v158, s[4:5]
	v_fma_f32 v3, v224, v158, v225
	s_add_u32 s4, s4, s7
	s_addc_u32 s5, s5, s8
	s_waitcnt vmcnt(32)
	global_store_dword v157, v3, s[4:5]
	v_fma_f32 v158, v226, v3, v227
	s_add_u32 s4, s4, s7
	s_addc_u32 s5, s5, s8
	s_waitcnt vmcnt(32)
	global_store_dword v157, v158, s[4:5]
	v_fma_f32 v3, v228, v158, v229
	s_add_u32 s4, s4, s7
	s_addc_u32 s5, s5, s8
	s_waitcnt vmcnt(32)
	global_store_dword v157, v3, s[4:5]
	v_fma_f32 v158, v230, v3, v231
	s_add_u32 s4, s4, s7
	s_addc_u32 s5, s5, s8
	s_waitcnt vmcnt(32)
	global_store_dword v157, v158, s[4:5]
	v_fma_f32 v3, v232, v158, v233
	s_add_u32 s4, s4, s7
	s_addc_u32 s5, s5, s8
	s_waitcnt vmcnt(32)
	global_store_dword v157, v3, s[4:5]
	v_fma_f32 v158, v234, v3, v235
	s_add_u32 s4, s4, s7
	s_addc_u32 s5, s5, s8
	s_waitcnt vmcnt(32)
	global_store_dword v157, v158, s[4:5]
	v_fma_f32 v3, v236, v158, v237
	s_add_u32 s4, s4, s7
	s_addc_u32 s5, s5, s8
	s_waitcnt vmcnt(32)
	global_store_dword v157, v3, s[4:5]
	v_fma_f32 v158, v238, v3, v239
	s_add_u32 s4, s4, s7
	s_addc_u32 s5, s5, s8
	s_waitcnt vmcnt(32)
	global_store_dword v157, v158, s[4:5]
	v_fma_f32 v3, v240, v158, v241
	s_add_u32 s4, s4, s7
	s_addc_u32 s5, s5, s8
	s_waitcnt vmcnt(32)
	global_store_dword v157, v3, s[4:5]
	v_fma_f32 v158, v242, v3, v243
	s_add_u32 s4, s4, s7
	s_addc_u32 s5, s5, s8
	s_waitcnt vmcnt(32)
; #define TIDX tid_opaque()
; DI void lru_carry_item(const Params& P, int it) {
;   const int ch = TIDX, dir = it & 1;
;   const size_t base = (size_t)it * 132 * 256 + ch;
;   float c = 0.f;
; #pragma unroll 4
;   for (int k = 0; k < 132; k++) {
;     int tile = dir == 0 ? k : (k < 4 ? 3 - k : 135 - k);
;     float2 s = P.lsum[base + (size_t)tile * 256];
;     P.lcar[base + (size_t)tile * 256] = c;
;     c = s.x * c + s.y;
;   }
; }
	global_store_dword v157, v158, s[4:5]
	v_fma_f32 v3, v244, v158, v245
	s_add_u32 s4, s4, s7
	s_addc_u32 s5, s5, s8
	s_waitcnt vmcnt(32)
	global_store_dword v157, v3, s[4:5]
	v_fma_f32 v158, v246, v3, v247
	s_add_u32 s4, s4, s7
	s_addc_u32 s5, s5, s8
	s_waitcnt vmcnt(32)
	global_store_dword v157, v158, s[4:5]
	v_fma_f32 v3, v248, v158, v249
	s_add_u32 s4, s4, s7
	s_addc_u32 s5, s5, s8
	s_waitcnt vmcnt(32)
	global_store_dword v157, v3, s[4:5]
	v_fma_f32 v158, v250, v3, v251
	s_add_u32 s4, s4, s7
	s_addc_u32 s5, s5, s8
	global_load_dwordx2 v[186:187], v156, s[2:3]
	s_add_u32 s2, s2, s6
	s_addc_u32 s3, s3, s8
	global_load_dwordx2 v[188:189], v156, s[2:3]
	s_add_u32 s2, s2, s6
	s_addc_u32 s3, s3, s8
	global_load_dwordx2 v[190:191], v156, s[2:3]
	s_add_u32 s2, s2, s6
	s_addc_u32 s3, s3, s8
	global_load_dwordx2 v[192:193], v156, s[2:3]
	s_add_u32 s2, s2, s6
	s_addc_u32 s3, s3, s8
	global_load_dwordx2 v[194:195], v156, s[2:3]
	s_add_u32 s2, s2, s6
	s_addc_u32 s3, s3, s8
	global_load_dwordx2 v[196:197], v156, s[2:3]
	s_add_u32 s2, s2, s6
	s_addc_u32 s3, s3, s8
	global_load_dwordx2 v[198:199], v156, s[2:3]
	s_add_u32 s2, s2, s6
	s_addc_u32 s3, s3, s8
	global_load_dwordx2 v[200:201], v156, s[2:3]
	s_add_u32 s2, s2, s6
	s_addc_u32 s3, s3, s8
	global_load_dwordx2 v[202:203], v156, s[2:3]
	s_add_u32 s2, s2, s6
	s_addc_u32 s3, s3, s8
	global_load_dwordx2 v[204:205], v156, s[2:3]
	s_add_u32 s2, s2, s6
	s_addc_u32 s3, s3, s8
	global_load_dwordx2 v[206:207], v156, s[2:3]
	s_add_u32 s2, s2, s6
	s_addc_u32 s3, s3, s8
	global_load_dwordx2 v[208:209], v156, s[2:3]
	s_add_u32 s2, s2, s6
	s_addc_u32 s3, s3, s8
	global_load_dwordx2 v[210:211], v156, s[2:3]
	s_add_u32 s2, s2, s6
	s_addc_u32 s3, s3, s8
	global_load_dwordx2 v[212:213], v156, s[2:3]
	s_add_u32 s2, s2, s6
	s_addc_u32 s3, s3, s8
	global_load_dwordx2 v[214:215], v156, s[2:3]
	s_add_u32 s2, s2, s6
	s_addc_u32 s3, s3, s8
	global_load_dwordx2 v[216:217], v156, s[2:3]
	s_add_u32 s2, s2, s6
	s_addc_u32 s3, s3, s8
	global_load_dwordx2 v[218:219], v156, s[2:3]
	s_add_u32 s2, s2, s6
	s_addc_u32 s3, s3, s8
	global_load_dwordx2 v[220:221], v156, s[2:3]
	s_add_u32 s2, s2, s6
	s_addc_u32 s3, s3, s8
	global_load_dwordx2 v[222:223], v156, s[2:3]
	s_add_u32 s2, s2, s6
	s_addc_u32 s3, s3, s8
	global_load_dwordx2 v[224:225], v156, s[2:3]
	s_add_u32 s2, s2, s6
	s_addc_u32 s3, s3, s8
	global_load_dwordx2 v[226:227], v156, s[2:3]
	s_add_u32 s2, s2, s6
	s_addc_u32 s3, s3, s8
	global_load_dwordx2 v[228:229], v156, s[2:3]
	s_add_u32 s2, s2, s6
	s_addc_u32 s3, s3, s8
	global_load_dwordx2 v[230:231], v156, s[2:3]
	s_add_u32 s2, s2, s6
	s_addc_u32 s3, s3, s8
	global_load_dwordx2 v[232:233], v156, s[2:3]
	s_add_u32 s2, s2, s6
	s_addc_u32 s3, s3, s8
	global_load_dwordx2 v[234:235], v156, s[2:3]
	s_add_u32 s2, s2, s6
	s_addc_u32 s3, s3, s8
	global_load_dwordx2 v[236:237], v156, s[2:3]
	s_add_u32 s2, s2, s6
	s_addc_u32 s3, s3, s8
	global_load_dwordx2 v[238:239], v156, s[2:3]
	s_add_u32 s2, s2, s6
	s_addc_u32 s3, s3, s8
	global_load_dwordx2 v[240:241], v156, s[2:3]
	s_add_u32 s2, s2, s6
	s_addc_u32 s3, s3, s8
	global_load_dwordx2 v[242:243], v156, s[2:3]
	s_add_u32 s2, s2, s6
	s_addc_u32 s3, s3, s8
	global_load_dwordx2 v[244:245], v156, s[2:3]
	s_add_u32 s2, s2, s6
	s_addc_u32 s3, s3, s8
	global_load_dwordx2 v[246:247], v156, s[2:3]
	s_add_u32 s2, s2, s6
	s_addc_u32 s3, s3, s8
	global_load_dwordx2 v[248:249], v156, s[2:3]
	s_add_u32 s2, s2, s6
	s_addc_u32 s3, s3, s8
	global_load_dwordx2 v[250:251], v156, s[2:3]
	s_add_u32 s2, s2, s6
	s_addc_u32 s3, s3, s8
	s_waitcnt vmcnt(32)
	global_store_dword v157, v158, s[4:5]
	v_fma_f32 v3, v186, v158, v187
	s_add_u32 s4, s4, s7
	s_addc_u32 s5, s5, s8
	s_waitcnt vmcnt(32)
	global_store_dword v157, v3, s[4:5]
	v_fma_f32 v158, v188, v3, v189
	s_add_u32 s4, s4, s7
	s_addc_u32 s5, s5, s8
	s_waitcnt vmcnt(32)
	global_store_dword v157, v158, s[4:5]
	v_fma_f32 v3, v190, v158, v191
	s_add_u32 s4, s4, s7
	s_addc_u32 s5, s5, s8
	s_waitcnt vmcnt(32)
; #define TIDX tid_opaque()
; DI void lru_carry_item(const Params& P, int it) {
;   const int ch = TIDX, dir = it & 1;
;   const size_t base = (size_t)it * 132 * 256 + ch;
;   float c = 0.f;
; #pragma unroll 4
;   for (int k = 0; k < 132; k++) {
;     int tile = dir == 0 ? k : (k < 4 ? 3 - k : 135 - k);
;     float2 s = P.lsum[base + (size_t)tile * 256];
;     P.lcar[base + (size_t)tile * 256] = c;
;     c = s.x * c + s.y;
;   }
; }
	global_store_dword v157, v3, s[4:5]
	v_fma_f32 v158, v192, v3, v193
	s_add_u32 s4, s4, s7
	s_addc_u32 s5, s5, s8
	s_waitcnt vmcnt(32)
	global_store_dword v157, v158, s[4:5]
	v_fma_f32 v3, v194, v158, v195
	s_add_u32 s4, s4, s7
	s_addc_u32 s5, s5, s8
	s_waitcnt vmcnt(32)
	global_store_dword v157, v3, s[4:5]
	v_fma_f32 v158, v196, v3, v197
	s_add_u32 s4, s4, s7
	s_addc_u32 s5, s5, s8
	s_waitcnt vmcnt(32)
	global_store_dword v157, v158, s[4:5]
	v_fma_f32 v3, v198, v158, v199
	s_add_u32 s4, s4, s7
	s_addc_u32 s5, s5, s8
	s_waitcnt vmcnt(32)
	global_store_dword v157, v3, s[4:5]
	v_fma_f32 v158, v200, v3, v201
	s_add_u32 s4, s4, s7
	s_addc_u32 s5, s5, s8
	s_waitcnt vmcnt(32)
	global_store_dword v157, v158, s[4:5]
	v_fma_f32 v3, v202, v158, v203
	s_add_u32 s4, s4, s7
	s_addc_u32 s5, s5, s8
	s_waitcnt vmcnt(32)
	global_store_dword v157, v3, s[4:5]
	v_fma_f32 v158, v204, v3, v205
	s_add_u32 s4, s4, s7
	s_addc_u32 s5, s5, s8
	s_waitcnt vmcnt(32)
	global_store_dword v157, v158, s[4:5]
	v_fma_f32 v3, v206, v158, v207
	s_add_u32 s4, s4, s7
	s_addc_u32 s5, s5, s8
	s_waitcnt vmcnt(32)
	global_store_dword v157, v3, s[4:5]
	v_fma_f32 v158, v208, v3, v209
	s_add_u32 s4, s4, s7
	s_addc_u32 s5, s5, s8
	s_waitcnt vmcnt(32)
	global_store_dword v157, v158, s[4:5]
	v_fma_f32 v3, v210, v158, v211
	s_add_u32 s4, s4, s7
	s_addc_u32 s5, s5, s8
	s_waitcnt vmcnt(32)
	global_store_dword v157, v3, s[4:5]
	v_fma_f32 v158, v212, v3, v213
	s_add_u32 s4, s4, s7
	s_addc_u32 s5, s5, s8
	s_waitcnt vmcnt(32)
	global_store_dword v157, v158, s[4:5]
	v_fma_f32 v3, v214, v158, v215
	s_add_u32 s4, s4, s7
	s_addc_u32 s5, s5, s8
	s_waitcnt vmcnt(32)
	global_store_dword v157, v3, s[4:5]
	v_fma_f32 v158, v216, v3, v217
	s_add_u32 s4, s4, s7
	s_addc_u32 s5, s5, s8
	s_waitcnt vmcnt(32)
	global_store_dword v157, v158, s[4:5]
	v_fma_f32 v3, v218, v158, v219
	s_add_u32 s4, s4, s7
	s_addc_u32 s5, s5, s8
	s_waitcnt vmcnt(32)
	global_store_dword v157, v3, s[4:5]
	v_fma_f32 v158, v220, v3, v221
	s_add_u32 s4, s4, s7
	s_addc_u32 s5, s5, s8
	s_waitcnt vmcnt(32)
	global_store_dword v157, v158, s[4:5]
	v_fma_f32 v3, v222, v158, v223
	s_add_u32 s4, s4, s7
	s_addc_u32 s5, s5, s8
	s_waitcnt vmcnt(32)
	global_store_dword v157, v3, s[4:5]
	v_fma_f32 v158, v224, v3, v225
	s_add_u32 s4, s4, s7
	s_addc_u32 s5, s5, s8
	s_waitcnt vmcnt(32)
	global_store_dword v157, v158, s[4:5]
	v_fma_f32 v3, v226, v158, v227
	s_add_u32 s4, s4, s7
	s_addc_u32 s5, s5, s8
	s_waitcnt vmcnt(32)
	global_store_dword v157, v3, s[4:5]
	v_fma_f32 v158, v228, v3, v229
	s_add_u32 s4, s4, s7
	s_addc_u32 s5, s5, s8
	s_waitcnt vmcnt(32)
	global_store_dword v157, v158, s[4:5]
	v_fma_f32 v3, v230, v158, v231
	s_add_u32 s4, s4, s7
	s_addc_u32 s5, s5, s8
	s_waitcnt vmcnt(32)
	global_store_dword v157, v3, s[4:5]
	v_fma_f32 v158, v232, v3, v233
	s_add_u32 s4, s4, s7
	s_addc_u32 s5, s5, s8
	s_waitcnt vmcnt(32)
	global_store_dword v157, v158, s[4:5]
	v_fma_f32 v3, v234, v158, v235
	s_add_u32 s4, s4, s7
	s_addc_u32 s5, s5, s8
	s_waitcnt vmcnt(32)
	global_store_dword v157, v3, s[4:5]
	v_fma_f32 v158, v236, v3, v237
	s_add_u32 s4, s4, s7
	s_addc_u32 s5, s5, s8
	s_waitcnt vmcnt(32)
	global_store_dword v157, v158, s[4:5]
	v_fma_f32 v3, v238, v158, v239
	s_add_u32 s4, s4, s7
	s_addc_u32 s5, s5, s8
	s_waitcnt vmcnt(32)
	global_store_dword v157, v3, s[4:5]
	v_fma_f32 v158, v240, v3, v241
	s_add_u32 s4, s4, s7
	s_addc_u32 s5, s5, s8
	s_waitcnt vmcnt(32)
	global_store_dword v157, v158, s[4:5]
	v_fma_f32 v3, v242, v158, v243
	s_add_u32 s4, s4, s7
	s_addc_u32 s5, s5, s8
	s_waitcnt vmcnt(32)
	global_store_dword v157, v3, s[4:5]
	v_fma_f32 v158, v244, v3, v245
	s_add_u32 s4, s4, s7
	s_addc_u32 s5, s5, s8
	s_waitcnt vmcnt(32)
	global_store_dword v157, v158, s[4:5]
	v_fma_f32 v3, v246, v158, v247
	s_add_u32 s4, s4, s7
	s_addc_u32 s5, s5, s8
	s_waitcnt vmcnt(32)
	global_store_dword v157, v3, s[4:5]
	v_fma_f32 v158, v248, v3, v249
	s_add_u32 s4, s4, s7
	s_addc_u32 s5, s5, s8
	s_waitcnt vmcnt(32)
	global_store_dword v157, v158, s[4:5]
	v_fma_f32 v3, v250, v158, v251
	s_add_u32 s4, s4, s7
	s_addc_u32 s5, s5, s8
	s_branch .LBB0_410

; DI void gemm_out_phase(const Params& P, int l, char* smem) {
;     ...
; #pragma unroll
;         for (int i = 0; i < 8; i++) {
;           const int row = i * 4 + fq2;
;           const float4 a = *(const float4*)(stg + row * 68 + fr2 * 4);
;           float4 r = rres[q][i];
;           r.x += g4.x * a.x; r.y += g4.y * a.y; r.z += g4.z * a.z; r.w += g4.w * a.w;
;           *(float4*)(dst + (size_t)(q * 32 + row) * D) = r;
;         }
.LBB0_512:
	v_lshl_add_u64 v[144:145], v[144:145], 2, v[140:141]
	s_nop 1
	v_readfirstlane_b32 s48, v144
	v_readfirstlane_b32 s49, v145
	s_add_u32 s50, s90, 0xf05c700
	s_addc_u32 s51, s91, 0
	s_sub_u32 s52, s48, s50
	s_subb_u32 s53, s49, s51
	s_cmp_eq_u32 s53, 0
	s_cselect_b32 s52, s52, -1
	v_readlane_b32 s55, v253, 49
	s_cmp_lt_u32 s52, 0x800000
	s_cselect_b32 s50, s50, s55
	s_cselect_b32 s54, 0x400000, 0
	s_cselect_b32 s60, 13, 18
	s_add_u32 s52, s90, 0x200bc700
	s_addc_u32 s53, s91, 0
	s_add_u32 s52, s52, s54
	s_addc_u32 s53, s53, 0
	s_mov_b32 s58, 0x10001
	s_mov_b32 s59, 0x10001
	v_lshrrev_b32_e32 v140, 6, v150
	s_movk_i32 s2, 0x3000
	v_mul_lo_u32 v140, v140, s2
	v_lshl_or_b32 v140, v152, 2, v140
	v_add_u32_e32 v140, 0x18000, v140
	v_mad_u32_u24 v156, v152, 12, v140
	s_movk_i32 s3, 0x110
	s_movk_i32 s2, 0x440
	v_mad_u32_u24 v143, v151, s3, v156
	v_mad_u32_u24 v150, v151, s2, v140
	s_waitcnt vmcnt(0)
	ds_write_b32 v150, a124
	ds_write_b32 v150, a125 offset:272
	ds_write_b32 v150, a126 offset:544
	ds_write_b32 v150, a127 offset:816
	ds_write_b32 v150, a120 offset:64
	ds_write_b32 v150, a121 offset:336
	ds_write_b32 v150, a122 offset:608
	ds_write_b32 v150, a123 offset:880
	ds_write_b32 v150, a116 offset:128
	ds_write_b32 v150, a117 offset:400
	ds_write_b32 v150, a118 offset:672
	ds_write_b32 v150, a119 offset:944
	ds_write_b32 v150, a112 offset:192
	ds_write_b32 v150, a113 offset:464
	ds_write_b32 v150, a114 offset:736
	ds_write_b32 v150, a115 offset:1008
	ds_write_b32 v150, a108 offset:4352
	ds_write_b32 v150, a109 offset:4624
	ds_write_b32 v150, a110 offset:4896
	ds_write_b32 v150, a111 offset:5168
	ds_write_b32 v150, a104 offset:4416
	ds_write_b32 v150, a105 offset:4688
	ds_write_b32 v150, a106 offset:4960
	ds_write_b32 v150, a107 offset:5232
	ds_write_b32 v150, a100 offset:4480
	ds_write_b32 v150, a101 offset:4752
	ds_write_b32 v150, a102 offset:5024
	ds_write_b32 v150, a103 offset:5296
	ds_write_b32 v150, a96 offset:4544
	ds_write_b32 v150, a97 offset:4816
	ds_write_b32 v150, a98 offset:5088
	ds_write_b32 v150, a99 offset:5360
	ds_read_b128 v[152:155], v143
	v_lshlrev_b32_e32 v148, 2, v146
	v_lshl_add_u64 v[140:141], v[144:145], 0, v[148:149]
	s_mov_b32 s2, 0x60000
	s_waitcnt lgkmcnt(0)
	v_pk_fma_f32 v[128:129], v[0:1], v[152:153], v[128:129]
	v_pk_fma_f32 v[130:131], v[2:3], v[154:155], v[130:131]
	v_mul_f32_e32 v186, v128, v128
	v_fmac_f32_e32 v186, v129, v129
	v_fmac_f32_e32 v186, v130, v130
	v_fmac_f32_e32 v186, v131, v131
	v_subrev_u32_e32 v187, s50, v140
	v_bfe_u32 v188, v187, 8, 4
	s_nop 1
	v_add_f32_dpp v186, v186, v186 row_ror:8 row_mask:0xf bank_mask:0xf
	s_nop 1
	v_add_f32_dpp v186, v186, v186 row_ror:4 row_mask:0xf bank_mask:0xf
	s_nop 1
	v_add_f32_dpp v186, v186, v186 row_ror:2 row_mask:0xf bank_mask:0xf
	s_nop 1
	v_add_f32_dpp v186, v186, v186 row_ror:1 row_mask:0xf bank_mask:0xf
	v_lshrrev_b32_e32 v187, 12, v187
	v_lshlrev_b32_e32 v187, 2, v187
	v_lshl_add_u32 v187, v188, s60, v187
	s_mov_b64 s[56:57], exec
	s_mov_b64 exec, s[58:59]
	global_store_dword v187, v186, s[52:53]
	s_mov_b64 exec, s[56:57]
	global_store_dwordx4 v[140:141], v[128:131], off
	s_nop 1
	v_or_b32_e32 v128, 4, v151
	v_mad_u32_u24 v130, v128, s3, v156
	ds_read_b128 v[152:155], v130
	v_lshlrev_b32_e32 v148, 12, v128
	v_lshl_add_u64 v[128:129], v[144:145], 0, v[148:149]
	v_or_b32_e32 v148, 0x8000, v142
	s_waitcnt lgkmcnt(0)
	v_pk_fma_f32 v[124:125], v[0:1], v[152:153], v[124:125]
	v_pk_fma_f32 v[126:127], v[2:3], v[154:155], v[126:127]
	ds_read_b128 v[152:155], v130 offset:1088
	v_mul_f32_e32 v186, v124, v124
	v_fmac_f32_e32 v186, v125, v125
	v_fmac_f32_e32 v186, v126, v126
	v_fmac_f32_e32 v186, v127, v127
	v_subrev_u32_e32 v187, s50, v128
	v_bfe_u32 v188, v187, 8, 4
	s_nop 1
	v_add_f32_dpp v186, v186, v186 row_ror:8 row_mask:0xf bank_mask:0xf
	s_nop 1
	v_add_f32_dpp v186, v186, v186 row_ror:4 row_mask:0xf bank_mask:0xf
	s_nop 1
	v_add_f32_dpp v186, v186, v186 row_ror:2 row_mask:0xf bank_mask:0xf
	s_nop 1
	v_add_f32_dpp v186, v186, v186 row_ror:1 row_mask:0xf bank_mask:0xf
	v_lshrrev_b32_e32 v187, 12, v187
	v_lshlrev_b32_e32 v187, 2, v187
	v_lshl_add_u32 v187, v188, s60, v187
	s_mov_b64 s[56:57], exec
	s_mov_b64 exec, s[58:59]
	global_store_dword v187, v186, s[52:53]
	s_mov_b64 exec, s[56:57]
	global_store_dwordx4 v[128:129], v[124:127], off
	s_waitcnt lgkmcnt(0)
	v_pk_fma_f32 v[120:121], v[0:1], v[152:153], v[120:121]
	v_pk_fma_f32 v[122:123], v[2:3], v[154:155], v[122:123]
	ds_read_b128 v[152:155], v130 offset:2176
	v_lshl_add_u64 v[124:125], v[144:145], 0, v[148:149]
	v_or_b32_e32 v148, 0xc000, v142
	v_mul_f32_e32 v186, v120, v120
	v_fmac_f32_e32 v186, v121, v121
	v_fmac_f32_e32 v186, v122, v122
	v_fmac_f32_e32 v186, v123, v123
	v_subrev_u32_e32 v187, s50, v124
	v_bfe_u32 v188, v187, 8, 4
	s_nop 1
	v_add_f32_dpp v186, v186, v186 row_ror:8 row_mask:0xf bank_mask:0xf
	s_nop 1
	v_add_f32_dpp v186, v186, v186 row_ror:4 row_mask:0xf bank_mask:0xf
	s_nop 1
	v_add_f32_dpp v186, v186, v186 row_ror:2 row_mask:0xf bank_mask:0xf
	s_nop 1
	v_add_f32_dpp v186, v186, v186 row_ror:1 row_mask:0xf bank_mask:0xf
	v_lshrrev_b32_e32 v187, 12, v187
	v_lshlrev_b32_e32 v187, 2, v187
	v_lshl_add_u32 v187, v188, s60, v187
	s_mov_b64 s[56:57], exec
	s_mov_b64 exec, s[58:59]
	global_store_dword v187, v186, s[52:53]
	s_mov_b64 exec, s[56:57]
	global_store_dwordx4 v[124:125], v[120:123], off
	s_waitcnt lgkmcnt(0)
; DI void gemm_out_phase(const Params& P, int l, char* smem) {
;     ...
; #pragma unroll
;         for (int i = 0; i < 8; i++) {
;           const int row = i * 4 + fq2;
;           const float4 a = *(const float4*)(stg + row * 68 + fr2 * 4);
;           float4 r = rres[q][i];
;           r.x += g4.x * a.x; r.y += g4.y * a.y; r.z += g4.z * a.z; r.w += g4.w * a.w;
;           *(float4*)(dst + (size_t)(q * 32 + row) * D) = r;
;         }
	v_pk_fma_f32 v[116:117], v[0:1], v[152:153], v[116:117]
	v_pk_fma_f32 v[118:119], v[2:3], v[154:155], v[118:119]
	ds_read_b128 v[152:155], v130 offset:3264
	v_lshl_add_u64 v[120:121], v[144:145], 0, v[148:149]
	v_or_b32_e32 v148, 0x10000, v142
	v_mul_f32_e32 v186, v116, v116
	v_fmac_f32_e32 v186, v117, v117
	v_fmac_f32_e32 v186, v118, v118
	v_fmac_f32_e32 v186, v119, v119
	v_subrev_u32_e32 v187, s50, v120
	v_bfe_u32 v188, v187, 8, 4
	s_nop 1
	v_add_f32_dpp v186, v186, v186 row_ror:8 row_mask:0xf bank_mask:0xf
	s_nop 1
	v_add_f32_dpp v186, v186, v186 row_ror:4 row_mask:0xf bank_mask:0xf
	s_nop 1
	v_add_f32_dpp v186, v186, v186 row_ror:2 row_mask:0xf bank_mask:0xf
	s_nop 1
	v_add_f32_dpp v186, v186, v186 row_ror:1 row_mask:0xf bank_mask:0xf
	v_lshrrev_b32_e32 v187, 12, v187
	v_lshlrev_b32_e32 v187, 2, v187
	v_lshl_add_u32 v187, v188, s60, v187
	s_mov_b64 s[56:57], exec
	s_mov_b64 exec, s[58:59]
	global_store_dword v187, v186, s[52:53]
	s_mov_b64 exec, s[56:57]
	global_store_dwordx4 v[120:121], v[116:119], off
	s_waitcnt lgkmcnt(0)
	v_pk_fma_f32 v[112:113], v[0:1], v[152:153], v[112:113]
	v_pk_fma_f32 v[114:115], v[2:3], v[154:155], v[114:115]
	ds_read_b128 v[152:155], v130 offset:4352
	v_lshl_add_u64 v[116:117], v[144:145], 0, v[148:149]
	v_or_b32_e32 v148, 0x14000, v142
	v_mul_f32_e32 v186, v112, v112
	v_fmac_f32_e32 v186, v113, v113
	v_fmac_f32_e32 v186, v114, v114
	v_fmac_f32_e32 v186, v115, v115
	v_subrev_u32_e32 v187, s50, v116
	v_bfe_u32 v188, v187, 8, 4
	s_nop 1
	v_add_f32_dpp v186, v186, v186 row_ror:8 row_mask:0xf bank_mask:0xf
	s_nop 1
	v_add_f32_dpp v186, v186, v186 row_ror:4 row_mask:0xf bank_mask:0xf
	s_nop 1
	v_add_f32_dpp v186, v186, v186 row_ror:2 row_mask:0xf bank_mask:0xf
	s_nop 1
	v_add_f32_dpp v186, v186, v186 row_ror:1 row_mask:0xf bank_mask:0xf
	v_lshrrev_b32_e32 v187, 12, v187
	v_lshlrev_b32_e32 v187, 2, v187
	v_lshl_add_u32 v187, v188, s60, v187
	s_mov_b64 s[56:57], exec
	s_mov_b64 exec, s[58:59]
	global_store_dword v187, v186, s[52:53]
	s_mov_b64 exec, s[56:57]
	global_store_dwordx4 v[116:117], v[112:115], off
	s_waitcnt lgkmcnt(0)
	v_pk_fma_f32 v[108:109], v[0:1], v[152:153], v[108:109]
	v_pk_fma_f32 v[110:111], v[2:3], v[154:155], v[110:111]
	ds_read_b128 v[152:155], v130 offset:5440
	v_lshl_add_u64 v[112:113], v[144:145], 0, v[148:149]
	v_or_b32_e32 v148, 0x18000, v142
	v_mul_f32_e32 v186, v108, v108
	v_fmac_f32_e32 v186, v109, v109
	v_fmac_f32_e32 v186, v110, v110
	v_fmac_f32_e32 v186, v111, v111
	v_subrev_u32_e32 v187, s50, v112
	v_bfe_u32 v188, v187, 8, 4
	s_nop 1
	v_add_f32_dpp v186, v186, v186 row_ror:8 row_mask:0xf bank_mask:0xf
	s_nop 1
	v_add_f32_dpp v186, v186, v186 row_ror:4 row_mask:0xf bank_mask:0xf
	s_nop 1
	v_add_f32_dpp v186, v186, v186 row_ror:2 row_mask:0xf bank_mask:0xf
	s_nop 1
	v_add_f32_dpp v186, v186, v186 row_ror:1 row_mask:0xf bank_mask:0xf
	v_lshrrev_b32_e32 v187, 12, v187
	v_lshlrev_b32_e32 v187, 2, v187
	v_lshl_add_u32 v187, v188, s60, v187
	s_mov_b64 s[56:57], exec
	s_mov_b64 exec, s[58:59]
	global_store_dword v187, v186, s[52:53]
	s_mov_b64 exec, s[56:57]
	global_store_dwordx4 v[112:113], v[108:111], off
	s_waitcnt lgkmcnt(0)
	v_pk_fma_f32 v[104:105], v[0:1], v[152:153], v[104:105]
	v_pk_fma_f32 v[106:107], v[2:3], v[154:155], v[106:107]
	ds_read_b128 v[152:155], v130 offset:6528
	v_lshl_add_u64 v[108:109], v[144:145], 0, v[148:149]
	v_or_b32_e32 v148, 0x1c000, v142
	v_mul_f32_e32 v186, v104, v104
	v_fmac_f32_e32 v186, v105, v105
	v_fmac_f32_e32 v186, v106, v106
	v_fmac_f32_e32 v186, v107, v107
	v_subrev_u32_e32 v187, s50, v108
	v_bfe_u32 v188, v187, 8, 4
	s_nop 1
	v_add_f32_dpp v186, v186, v186 row_ror:8 row_mask:0xf bank_mask:0xf
	s_nop 1
	v_add_f32_dpp v186, v186, v186 row_ror:4 row_mask:0xf bank_mask:0xf
	s_nop 1
	v_add_f32_dpp v186, v186, v186 row_ror:2 row_mask:0xf bank_mask:0xf
	s_nop 1
	v_add_f32_dpp v186, v186, v186 row_ror:1 row_mask:0xf bank_mask:0xf
	v_lshrrev_b32_e32 v187, 12, v187
	v_lshlrev_b32_e32 v187, 2, v187
	v_lshl_add_u32 v187, v188, s60, v187
	s_mov_b64 s[56:57], exec
	s_mov_b64 exec, s[58:59]
	global_store_dword v187, v186, s[52:53]
	s_mov_b64 exec, s[56:57]
	global_store_dwordx4 v[108:109], v[104:107], off
	s_waitcnt lgkmcnt(0)
	v_pk_fma_f32 v[100:101], v[0:1], v[152:153], v[100:101]
	v_lshl_add_u64 v[104:105], v[144:145], 0, v[148:149]
	v_pk_fma_f32 v[102:103], v[2:3], v[154:155], v[102:103]
	v_mul_f32_e32 v186, v100, v100
	v_fmac_f32_e32 v186, v101, v101
	v_fmac_f32_e32 v186, v102, v102
	v_fmac_f32_e32 v186, v103, v103
	v_subrev_u32_e32 v187, s50, v104
	v_bfe_u32 v188, v187, 8, 4
	s_nop 1
	v_add_f32_dpp v186, v186, v186 row_ror:8 row_mask:0xf bank_mask:0xf
	s_nop 1
	v_add_f32_dpp v186, v186, v186 row_ror:4 row_mask:0xf bank_mask:0xf
	s_nop 1
	v_add_f32_dpp v186, v186, v186 row_ror:2 row_mask:0xf bank_mask:0xf
	s_nop 1
	v_add_f32_dpp v186, v186, v186 row_ror:1 row_mask:0xf bank_mask:0xf
	v_lshrrev_b32_e32 v187, 12, v187
	v_lshlrev_b32_e32 v187, 2, v187
	v_lshl_add_u32 v187, v188, s60, v187
	s_mov_b64 s[56:57], exec
	s_mov_b64 exec, s[58:59]
	global_store_dword v187, v186, s[52:53]
	s_mov_b64 exec, s[56:57]
	global_store_dwordx4 v[104:105], v[100:103], off
	ds_write_b32 v150, a92
	ds_write_b32 v150, a93 offset:272
	ds_write_b32 v150, a94 offset:544
	ds_write_b32 v150, a95 offset:816
	ds_write_b32 v150, a88 offset:64
	ds_write_b32 v150, a89 offset:336
	ds_write_b32 v150, a90 offset:608
	ds_write_b32 v150, a91 offset:880
	ds_write_b32 v150, a84 offset:128
	ds_write_b32 v150, a85 offset:400
	ds_write_b32 v150, a86 offset:672
	ds_write_b32 v150, a87 offset:944
	ds_write_b32 v150, a80 offset:192
	ds_write_b32 v150, a81 offset:464
	ds_write_b32 v150, a82 offset:736
	ds_write_b32 v150, a83 offset:1008
	ds_write_b32 v150, a76 offset:4352
	ds_write_b32 v150, a77 offset:4624
	ds_write_b32 v150, a78 offset:4896
	ds_write_b32 v150, a79 offset:5168
	ds_write_b32 v150, a72 offset:4416
	ds_write_b32 v150, a73 offset:4688
	ds_write_b32 v150, a74 offset:4960
	ds_write_b32 v150, a75 offset:5232
	ds_write_b32 v150, a68 offset:4480
	ds_write_b32 v150, a69 offset:4752
	ds_write_b32 v150, a70 offset:5024
	ds_write_b32 v150, a71 offset:5296
	ds_write_b32 v150, a64 offset:4544
	ds_write_b32 v150, a65 offset:4816
	ds_write_b32 v150, a66 offset:5088
	ds_write_b32 v150, a67 offset:5360
	ds_read_b128 v[100:103], v143
	s_waitcnt lgkmcnt(0)
; DI void gemm_out_phase(const Params& P, int l, char* smem) {
;     ...
; #pragma unroll
;         for (int i = 0; i < 8; i++) {
;           const int row = i * 4 + fq2;
;           const float4 a = *(const float4*)(stg + row * 68 + fr2 * 4);
;           float4 r = rres[q][i];
;           r.x += g4.x * a.x; r.y += g4.y * a.y; r.z += g4.z * a.z; r.w += g4.w * a.w;
;           *(float4*)(dst + (size_t)(q * 32 + row) * D) = r;
;         }
	v_pk_fma_f32 v[96:97], v[0:1], v[100:101], v[96:97]
	v_add_co_u32_e32 v100, vcc, s31, v140
	v_pk_fma_f32 v[98:99], v[2:3], v[102:103], v[98:99]
	s_nop 0
	v_addc_co_u32_e32 v101, vcc, 0, v141, vcc
	v_mul_f32_e32 v186, v96, v96
	v_fmac_f32_e32 v186, v97, v97
	v_fmac_f32_e32 v186, v98, v98
	v_fmac_f32_e32 v186, v99, v99
	v_subrev_u32_e32 v187, s50, v100
	v_bfe_u32 v188, v187, 8, 4
	s_nop 1
	v_add_f32_dpp v186, v186, v186 row_ror:8 row_mask:0xf bank_mask:0xf
	s_nop 1
	v_add_f32_dpp v186, v186, v186 row_ror:4 row_mask:0xf bank_mask:0xf
	s_nop 1
	v_add_f32_dpp v186, v186, v186 row_ror:2 row_mask:0xf bank_mask:0xf
	s_nop 1
	v_add_f32_dpp v186, v186, v186 row_ror:1 row_mask:0xf bank_mask:0xf
	v_lshrrev_b32_e32 v187, 12, v187
	v_lshlrev_b32_e32 v187, 2, v187
	v_lshl_add_u32 v187, v188, s60, v187
	s_mov_b64 s[56:57], exec
	s_mov_b64 exec, s[58:59]
	global_store_dword v187, v186, s[52:53]
	s_mov_b64 exec, s[56:57]
	global_store_dwordx4 v[100:101], v[96:99], off
	ds_read_b128 v[96:99], v130
	s_waitcnt lgkmcnt(0)
	v_pk_fma_f32 v[92:93], v[0:1], v[96:97], v[92:93]
	v_add_co_u32_e32 v96, vcc, s31, v128
	v_pk_fma_f32 v[94:95], v[2:3], v[98:99], v[94:95]
	s_nop 0
	v_addc_co_u32_e32 v97, vcc, 0, v129, vcc
	v_mul_f32_e32 v186, v92, v92
	v_fmac_f32_e32 v186, v93, v93
	v_fmac_f32_e32 v186, v94, v94
	v_fmac_f32_e32 v186, v95, v95
	v_subrev_u32_e32 v187, s50, v96
	v_bfe_u32 v188, v187, 8, 4
	s_nop 1
	v_add_f32_dpp v186, v186, v186 row_ror:8 row_mask:0xf bank_mask:0xf
	s_nop 1
	v_add_f32_dpp v186, v186, v186 row_ror:4 row_mask:0xf bank_mask:0xf
	s_nop 1
	v_add_f32_dpp v186, v186, v186 row_ror:2 row_mask:0xf bank_mask:0xf
	s_nop 1
	v_add_f32_dpp v186, v186, v186 row_ror:1 row_mask:0xf bank_mask:0xf
	v_lshrrev_b32_e32 v187, 12, v187
	v_lshlrev_b32_e32 v187, 2, v187
	v_lshl_add_u32 v187, v188, s60, v187
	s_mov_b64 s[56:57], exec
	s_mov_b64 exec, s[58:59]
	global_store_dword v187, v186, s[52:53]
	s_mov_b64 exec, s[56:57]
	global_store_dwordx4 v[96:97], v[92:95], off
	ds_read_b128 v[92:95], v130 offset:1088
	s_waitcnt lgkmcnt(0)
	v_pk_fma_f32 v[88:89], v[0:1], v[92:93], v[88:89]
	v_add_co_u32_e32 v92, vcc, s31, v124
	v_pk_fma_f32 v[90:91], v[2:3], v[94:95], v[90:91]
	s_nop 0
	v_addc_co_u32_e32 v93, vcc, 0, v125, vcc
	v_mul_f32_e32 v186, v88, v88
	v_fmac_f32_e32 v186, v89, v89
	v_fmac_f32_e32 v186, v90, v90
	v_fmac_f32_e32 v186, v91, v91
	v_subrev_u32_e32 v187, s50, v92
	v_bfe_u32 v188, v187, 8, 4
	s_nop 1
	v_add_f32_dpp v186, v186, v186 row_ror:8 row_mask:0xf bank_mask:0xf
	s_nop 1
	v_add_f32_dpp v186, v186, v186 row_ror:4 row_mask:0xf bank_mask:0xf
	s_nop 1
	v_add_f32_dpp v186, v186, v186 row_ror:2 row_mask:0xf bank_mask:0xf
	s_nop 1
	v_add_f32_dpp v186, v186, v186 row_ror:1 row_mask:0xf bank_mask:0xf
	v_lshrrev_b32_e32 v187, 12, v187
	v_lshlrev_b32_e32 v187, 2, v187
	v_lshl_add_u32 v187, v188, s60, v187
	s_mov_b64 s[56:57], exec
	s_mov_b64 exec, s[58:59]
	global_store_dword v187, v186, s[52:53]
	s_mov_b64 exec, s[56:57]
	global_store_dwordx4 v[92:93], v[88:91], off
	ds_read_b128 v[88:91], v130 offset:2176
	s_waitcnt lgkmcnt(0)
	v_pk_fma_f32 v[84:85], v[0:1], v[88:89], v[84:85]
	v_add_co_u32_e32 v88, vcc, s31, v120
	v_pk_fma_f32 v[86:87], v[2:3], v[90:91], v[86:87]
	s_nop 0
	v_addc_co_u32_e32 v89, vcc, 0, v121, vcc
	v_mul_f32_e32 v186, v84, v84
	v_fmac_f32_e32 v186, v85, v85
	v_fmac_f32_e32 v186, v86, v86
	v_fmac_f32_e32 v186, v87, v87
	v_subrev_u32_e32 v187, s50, v88
	v_bfe_u32 v188, v187, 8, 4
	s_nop 1
	v_add_f32_dpp v186, v186, v186 row_ror:8 row_mask:0xf bank_mask:0xf
	s_nop 1
	v_add_f32_dpp v186, v186, v186 row_ror:4 row_mask:0xf bank_mask:0xf
	s_nop 1
	v_add_f32_dpp v186, v186, v186 row_ror:2 row_mask:0xf bank_mask:0xf
	s_nop 1
	v_add_f32_dpp v186, v186, v186 row_ror:1 row_mask:0xf bank_mask:0xf
	v_lshrrev_b32_e32 v187, 12, v187
	v_lshlrev_b32_e32 v187, 2, v187
	v_lshl_add_u32 v187, v188, s60, v187
	s_mov_b64 s[56:57], exec
	s_mov_b64 exec, s[58:59]
	global_store_dword v187, v186, s[52:53]
	s_mov_b64 exec, s[56:57]
	global_store_dwordx4 v[88:89], v[84:87], off
	ds_read_b128 v[84:87], v130 offset:3264
	s_waitcnt lgkmcnt(0)
	v_pk_fma_f32 v[80:81], v[0:1], v[84:85], v[80:81]
	v_add_co_u32_e32 v84, vcc, s31, v116
	v_pk_fma_f32 v[82:83], v[2:3], v[86:87], v[82:83]
	s_nop 0
	v_addc_co_u32_e32 v85, vcc, 0, v117, vcc
	v_mul_f32_e32 v186, v80, v80
	v_fmac_f32_e32 v186, v81, v81
	v_fmac_f32_e32 v186, v82, v82
	v_fmac_f32_e32 v186, v83, v83
	v_subrev_u32_e32 v187, s50, v84
	v_bfe_u32 v188, v187, 8, 4
	s_nop 1
	v_add_f32_dpp v186, v186, v186 row_ror:8 row_mask:0xf bank_mask:0xf
	s_nop 1
	v_add_f32_dpp v186, v186, v186 row_ror:4 row_mask:0xf bank_mask:0xf
	s_nop 1
	v_add_f32_dpp v186, v186, v186 row_ror:2 row_mask:0xf bank_mask:0xf
	s_nop 1
	v_add_f32_dpp v186, v186, v186 row_ror:1 row_mask:0xf bank_mask:0xf
	v_lshrrev_b32_e32 v187, 12, v187
	v_lshlrev_b32_e32 v187, 2, v187
	v_lshl_add_u32 v187, v188, s60, v187
	s_mov_b64 s[56:57], exec
	s_mov_b64 exec, s[58:59]
	global_store_dword v187, v186, s[52:53]
	s_mov_b64 exec, s[56:57]
	global_store_dwordx4 v[84:85], v[80:83], off
	ds_read_b128 v[80:83], v130 offset:4352
	s_waitcnt lgkmcnt(0)
	v_pk_fma_f32 v[76:77], v[0:1], v[80:81], v[76:77]
	v_add_co_u32_e32 v80, vcc, s31, v112
	v_pk_fma_f32 v[78:79], v[2:3], v[82:83], v[78:79]
	s_nop 0
	v_addc_co_u32_e32 v81, vcc, 0, v113, vcc
	v_mul_f32_e32 v186, v76, v76
	v_fmac_f32_e32 v186, v77, v77
	v_fmac_f32_e32 v186, v78, v78
	v_fmac_f32_e32 v186, v79, v79
	v_subrev_u32_e32 v187, s50, v80
	v_bfe_u32 v188, v187, 8, 4
	s_nop 1
	v_add_f32_dpp v186, v186, v186 row_ror:8 row_mask:0xf bank_mask:0xf
	s_nop 1
	v_add_f32_dpp v186, v186, v186 row_ror:4 row_mask:0xf bank_mask:0xf
	s_nop 1
	v_add_f32_dpp v186, v186, v186 row_ror:2 row_mask:0xf bank_mask:0xf
	s_nop 1
	v_add_f32_dpp v186, v186, v186 row_ror:1 row_mask:0xf bank_mask:0xf
	v_lshrrev_b32_e32 v187, 12, v187
	v_lshlrev_b32_e32 v187, 2, v187
	v_lshl_add_u32 v187, v188, s60, v187
	s_mov_b64 s[56:57], exec
	s_mov_b64 exec, s[58:59]
	global_store_dword v187, v186, s[52:53]
	s_mov_b64 exec, s[56:57]
	global_store_dwordx4 v[80:81], v[76:79], off
	ds_read_b128 v[76:79], v130 offset:5440
	s_waitcnt lgkmcnt(0)
; DI void gemm_out_phase(const Params& P, int l, char* smem) {
;     ...
; #pragma unroll
;         for (int i = 0; i < 8; i++) {
;           const int row = i * 4 + fq2;
;           const float4 a = *(const float4*)(stg + row * 68 + fr2 * 4);
;           float4 r = rres[q][i];
;           r.x += g4.x * a.x; r.y += g4.y * a.y; r.z += g4.z * a.z; r.w += g4.w * a.w;
;           *(float4*)(dst + (size_t)(q * 32 + row) * D) = r;
;         }
	v_pk_fma_f32 v[72:73], v[0:1], v[76:77], v[72:73]
	v_add_co_u32_e32 v76, vcc, s31, v108
	v_pk_fma_f32 v[74:75], v[2:3], v[78:79], v[74:75]
	s_nop 0
	v_addc_co_u32_e32 v77, vcc, 0, v109, vcc
	v_mul_f32_e32 v186, v72, v72
	v_fmac_f32_e32 v186, v73, v73
	v_fmac_f32_e32 v186, v74, v74
	v_fmac_f32_e32 v186, v75, v75
	v_subrev_u32_e32 v187, s50, v76
	v_bfe_u32 v188, v187, 8, 4
	s_nop 1
	v_add_f32_dpp v186, v186, v186 row_ror:8 row_mask:0xf bank_mask:0xf
	s_nop 1
	v_add_f32_dpp v186, v186, v186 row_ror:4 row_mask:0xf bank_mask:0xf
	s_nop 1
	v_add_f32_dpp v186, v186, v186 row_ror:2 row_mask:0xf bank_mask:0xf
	s_nop 1
	v_add_f32_dpp v186, v186, v186 row_ror:1 row_mask:0xf bank_mask:0xf
	v_lshrrev_b32_e32 v187, 12, v187
	v_lshlrev_b32_e32 v187, 2, v187
	v_lshl_add_u32 v187, v188, s60, v187
	s_mov_b64 s[56:57], exec
	s_mov_b64 exec, s[58:59]
	global_store_dword v187, v186, s[52:53]
	s_mov_b64 exec, s[56:57]
	global_store_dwordx4 v[76:77], v[72:75], off
	ds_read_b128 v[72:75], v130 offset:6528
	s_waitcnt lgkmcnt(0)
	v_pk_fma_f32 v[68:69], v[0:1], v[72:73], v[68:69]
	v_add_co_u32_e32 v72, vcc, s31, v104
	v_pk_fma_f32 v[70:71], v[2:3], v[74:75], v[70:71]
	s_nop 0
	v_addc_co_u32_e32 v73, vcc, 0, v105, vcc
	v_mul_f32_e32 v186, v68, v68
	v_fmac_f32_e32 v186, v69, v69
	v_fmac_f32_e32 v186, v70, v70
	v_fmac_f32_e32 v186, v71, v71
	v_subrev_u32_e32 v187, s50, v72
	v_bfe_u32 v188, v187, 8, 4
	s_nop 1
	v_add_f32_dpp v186, v186, v186 row_ror:8 row_mask:0xf bank_mask:0xf
	s_nop 1
	v_add_f32_dpp v186, v186, v186 row_ror:4 row_mask:0xf bank_mask:0xf
	s_nop 1
	v_add_f32_dpp v186, v186, v186 row_ror:2 row_mask:0xf bank_mask:0xf
	s_nop 1
	v_add_f32_dpp v186, v186, v186 row_ror:1 row_mask:0xf bank_mask:0xf
	v_lshrrev_b32_e32 v187, 12, v187
	v_lshlrev_b32_e32 v187, 2, v187
	v_lshl_add_u32 v187, v188, s60, v187
	s_mov_b64 s[56:57], exec
	s_mov_b64 exec, s[58:59]
	global_store_dword v187, v186, s[52:53]
	s_mov_b64 exec, s[56:57]
	global_store_dwordx4 v[72:73], v[68:71], off
	ds_write_b32 v150, a60
	ds_write_b32 v150, a61 offset:272
	ds_write_b32 v150, a62 offset:544
	ds_write_b32 v150, a63 offset:816
	ds_write_b32 v150, a56 offset:64
	ds_write_b32 v150, a57 offset:336
	ds_write_b32 v150, a58 offset:608
	ds_write_b32 v150, a59 offset:880
	ds_write_b32 v150, a52 offset:128
	ds_write_b32 v150, a53 offset:400
	ds_write_b32 v150, a54 offset:672
	ds_write_b32 v150, a55 offset:944
	ds_write_b32 v150, a48 offset:192
	ds_write_b32 v150, a49 offset:464
	ds_write_b32 v150, a50 offset:736
	ds_write_b32 v150, a51 offset:1008
	ds_write_b32 v150, a44 offset:4352
	ds_write_b32 v150, a45 offset:4624
	ds_write_b32 v150, a46 offset:4896
	ds_write_b32 v150, a47 offset:5168
	ds_write_b32 v150, a40 offset:4416
	ds_write_b32 v150, a41 offset:4688
	ds_write_b32 v150, a42 offset:4960
	ds_write_b32 v150, a43 offset:5232
	ds_write_b32 v150, a36 offset:4480
	ds_write_b32 v150, a37 offset:4752
	ds_write_b32 v150, a38 offset:5024
	ds_write_b32 v150, a39 offset:5296
	ds_write_b32 v150, a32 offset:4544
	ds_write_b32 v150, a33 offset:4816
	ds_write_b32 v150, a34 offset:5088
	ds_write_b32 v150, a35 offset:5360
	ds_read_b128 v[68:71], v143
	s_waitcnt lgkmcnt(0)
	v_pk_fma_f32 v[64:65], v[0:1], v[68:69], v[64:65]
	v_add_co_u32_e32 v68, vcc, s88, v140
	v_pk_fma_f32 v[66:67], v[2:3], v[70:71], v[66:67]
	s_nop 0
	v_addc_co_u32_e32 v69, vcc, 0, v141, vcc
	v_mul_f32_e32 v186, v64, v64
	v_fmac_f32_e32 v186, v65, v65
	v_fmac_f32_e32 v186, v66, v66
	v_fmac_f32_e32 v186, v67, v67
	v_subrev_u32_e32 v187, s50, v68
	v_bfe_u32 v188, v187, 8, 4
	s_nop 1
	v_add_f32_dpp v186, v186, v186 row_ror:8 row_mask:0xf bank_mask:0xf
	s_nop 1
	v_add_f32_dpp v186, v186, v186 row_ror:4 row_mask:0xf bank_mask:0xf
	s_nop 1
	v_add_f32_dpp v186, v186, v186 row_ror:2 row_mask:0xf bank_mask:0xf
	s_nop 1
	v_add_f32_dpp v186, v186, v186 row_ror:1 row_mask:0xf bank_mask:0xf
	v_lshrrev_b32_e32 v187, 12, v187
	v_lshlrev_b32_e32 v187, 2, v187
	v_lshl_add_u32 v187, v188, s60, v187
	s_mov_b64 s[56:57], exec
	s_mov_b64 exec, s[58:59]
	global_store_dword v187, v186, s[52:53]
	s_mov_b64 exec, s[56:57]
	global_store_dwordx4 v[68:69], v[64:67], off
	ds_read_b128 v[64:67], v130
	s_waitcnt lgkmcnt(0)
	v_pk_fma_f32 v[60:61], v[0:1], v[64:65], v[60:61]
	v_add_co_u32_e32 v64, vcc, s88, v128
	v_pk_fma_f32 v[62:63], v[2:3], v[66:67], v[62:63]
	s_nop 0
	v_addc_co_u32_e32 v65, vcc, 0, v129, vcc
	v_mul_f32_e32 v186, v60, v60
	v_fmac_f32_e32 v186, v61, v61
	v_fmac_f32_e32 v186, v62, v62
	v_fmac_f32_e32 v186, v63, v63
	v_subrev_u32_e32 v187, s50, v64
	v_bfe_u32 v188, v187, 8, 4
	s_nop 1
	v_add_f32_dpp v186, v186, v186 row_ror:8 row_mask:0xf bank_mask:0xf
	s_nop 1
	v_add_f32_dpp v186, v186, v186 row_ror:4 row_mask:0xf bank_mask:0xf
	s_nop 1
	v_add_f32_dpp v186, v186, v186 row_ror:2 row_mask:0xf bank_mask:0xf
	s_nop 1
	v_add_f32_dpp v186, v186, v186 row_ror:1 row_mask:0xf bank_mask:0xf
	v_lshrrev_b32_e32 v187, 12, v187
	v_lshlrev_b32_e32 v187, 2, v187
	v_lshl_add_u32 v187, v188, s60, v187
	s_mov_b64 s[56:57], exec
	s_mov_b64 exec, s[58:59]
	global_store_dword v187, v186, s[52:53]
	s_mov_b64 exec, s[56:57]
	global_store_dwordx4 v[64:65], v[60:63], off
	ds_read_b128 v[60:63], v130 offset:1088
	s_waitcnt lgkmcnt(0)
; DI void gemm_out_phase(const Params& P, int l, char* smem) {
;     ...
; #pragma unroll
;         for (int i = 0; i < 8; i++) {
;           const int row = i * 4 + fq2;
;           const float4 a = *(const float4*)(stg + row * 68 + fr2 * 4);
;           float4 r = rres[q][i];
;           r.x += g4.x * a.x; r.y += g4.y * a.y; r.z += g4.z * a.z; r.w += g4.w * a.w;
;           *(float4*)(dst + (size_t)(q * 32 + row) * D) = r;
;         }
	v_pk_fma_f32 v[56:57], v[0:1], v[60:61], v[56:57]
	v_add_co_u32_e32 v60, vcc, s88, v124
	v_pk_fma_f32 v[58:59], v[2:3], v[62:63], v[58:59]
	s_nop 0
	v_addc_co_u32_e32 v61, vcc, 0, v125, vcc
	v_mul_f32_e32 v186, v56, v56
	v_fmac_f32_e32 v186, v57, v57
	v_fmac_f32_e32 v186, v58, v58
	v_fmac_f32_e32 v186, v59, v59
	v_subrev_u32_e32 v187, s50, v60
	v_bfe_u32 v188, v187, 8, 4
	s_nop 1
	v_add_f32_dpp v186, v186, v186 row_ror:8 row_mask:0xf bank_mask:0xf
	s_nop 1
	v_add_f32_dpp v186, v186, v186 row_ror:4 row_mask:0xf bank_mask:0xf
	s_nop 1
	v_add_f32_dpp v186, v186, v186 row_ror:2 row_mask:0xf bank_mask:0xf
	s_nop 1
	v_add_f32_dpp v186, v186, v186 row_ror:1 row_mask:0xf bank_mask:0xf
	v_lshrrev_b32_e32 v187, 12, v187
	v_lshlrev_b32_e32 v187, 2, v187
	v_lshl_add_u32 v187, v188, s60, v187
	s_mov_b64 s[56:57], exec
	s_mov_b64 exec, s[58:59]
	global_store_dword v187, v186, s[52:53]
	s_mov_b64 exec, s[56:57]
	global_store_dwordx4 v[60:61], v[56:59], off
	ds_read_b128 v[56:59], v130 offset:2176
	s_waitcnt lgkmcnt(0)
	v_pk_fma_f32 v[52:53], v[0:1], v[56:57], v[52:53]
	v_add_co_u32_e32 v56, vcc, s88, v120
	v_pk_fma_f32 v[54:55], v[2:3], v[58:59], v[54:55]
	s_nop 0
	v_addc_co_u32_e32 v57, vcc, 0, v121, vcc
	v_mul_f32_e32 v186, v52, v52
	v_fmac_f32_e32 v186, v53, v53
	v_fmac_f32_e32 v186, v54, v54
	v_fmac_f32_e32 v186, v55, v55
	v_subrev_u32_e32 v187, s50, v56
	v_bfe_u32 v188, v187, 8, 4
	s_nop 1
	v_add_f32_dpp v186, v186, v186 row_ror:8 row_mask:0xf bank_mask:0xf
	s_nop 1
	v_add_f32_dpp v186, v186, v186 row_ror:4 row_mask:0xf bank_mask:0xf
	s_nop 1
	v_add_f32_dpp v186, v186, v186 row_ror:2 row_mask:0xf bank_mask:0xf
	s_nop 1
	v_add_f32_dpp v186, v186, v186 row_ror:1 row_mask:0xf bank_mask:0xf
	v_lshrrev_b32_e32 v187, 12, v187
	v_lshlrev_b32_e32 v187, 2, v187
	v_lshl_add_u32 v187, v188, s60, v187
	s_mov_b64 s[56:57], exec
	s_mov_b64 exec, s[58:59]
	global_store_dword v187, v186, s[52:53]
	s_mov_b64 exec, s[56:57]
	global_store_dwordx4 v[56:57], v[52:55], off
	ds_read_b128 v[52:55], v130 offset:3264
	s_waitcnt lgkmcnt(0)
	v_pk_fma_f32 v[48:49], v[0:1], v[52:53], v[48:49]
	v_add_co_u32_e32 v52, vcc, s88, v116
	v_pk_fma_f32 v[50:51], v[2:3], v[54:55], v[50:51]
	s_nop 0
	v_addc_co_u32_e32 v53, vcc, 0, v117, vcc
	v_mul_f32_e32 v186, v48, v48
	v_fmac_f32_e32 v186, v49, v49
	v_fmac_f32_e32 v186, v50, v50
	v_fmac_f32_e32 v186, v51, v51
	v_subrev_u32_e32 v187, s50, v52
	v_bfe_u32 v188, v187, 8, 4
	s_nop 1
	v_add_f32_dpp v186, v186, v186 row_ror:8 row_mask:0xf bank_mask:0xf
	s_nop 1
	v_add_f32_dpp v186, v186, v186 row_ror:4 row_mask:0xf bank_mask:0xf
	s_nop 1
	v_add_f32_dpp v186, v186, v186 row_ror:2 row_mask:0xf bank_mask:0xf
	s_nop 1
	v_add_f32_dpp v186, v186, v186 row_ror:1 row_mask:0xf bank_mask:0xf
	v_lshrrev_b32_e32 v187, 12, v187
	v_lshlrev_b32_e32 v187, 2, v187
	v_lshl_add_u32 v187, v188, s60, v187
	s_mov_b64 s[56:57], exec
	s_mov_b64 exec, s[58:59]
	global_store_dword v187, v186, s[52:53]
	s_mov_b64 exec, s[56:57]
	global_store_dwordx4 v[52:53], v[48:51], off
	ds_read_b128 v[48:51], v130 offset:4352
	s_waitcnt lgkmcnt(0)
	v_pk_fma_f32 v[44:45], v[0:1], v[48:49], v[44:45]
	v_add_co_u32_e32 v48, vcc, s88, v112
	v_pk_fma_f32 v[46:47], v[2:3], v[50:51], v[46:47]
	s_nop 0
	v_addc_co_u32_e32 v49, vcc, 0, v113, vcc
	v_mul_f32_e32 v186, v44, v44
	v_fmac_f32_e32 v186, v45, v45
	v_fmac_f32_e32 v186, v46, v46
	v_fmac_f32_e32 v186, v47, v47
	v_subrev_u32_e32 v187, s50, v48
	v_bfe_u32 v188, v187, 8, 4
	s_nop 1
	v_add_f32_dpp v186, v186, v186 row_ror:8 row_mask:0xf bank_mask:0xf
	s_nop 1
	v_add_f32_dpp v186, v186, v186 row_ror:4 row_mask:0xf bank_mask:0xf
	s_nop 1
	v_add_f32_dpp v186, v186, v186 row_ror:2 row_mask:0xf bank_mask:0xf
	s_nop 1
	v_add_f32_dpp v186, v186, v186 row_ror:1 row_mask:0xf bank_mask:0xf
	v_lshrrev_b32_e32 v187, 12, v187
	v_lshlrev_b32_e32 v187, 2, v187
	v_lshl_add_u32 v187, v188, s60, v187
	s_mov_b64 s[56:57], exec
	s_mov_b64 exec, s[58:59]
	global_store_dword v187, v186, s[52:53]
	s_mov_b64 exec, s[56:57]
	global_store_dwordx4 v[48:49], v[44:47], off
	ds_read_b128 v[44:47], v130 offset:5440
	s_waitcnt lgkmcnt(0)
	v_pk_fma_f32 v[40:41], v[0:1], v[44:45], v[40:41]
	v_add_co_u32_e32 v44, vcc, s88, v108
	v_pk_fma_f32 v[42:43], v[2:3], v[46:47], v[42:43]
	s_nop 0
	v_addc_co_u32_e32 v45, vcc, 0, v109, vcc
	v_mul_f32_e32 v186, v40, v40
	v_fmac_f32_e32 v186, v41, v41
	v_fmac_f32_e32 v186, v42, v42
	v_fmac_f32_e32 v186, v43, v43
	v_subrev_u32_e32 v187, s50, v44
	v_bfe_u32 v188, v187, 8, 4
	s_nop 1
	v_add_f32_dpp v186, v186, v186 row_ror:8 row_mask:0xf bank_mask:0xf
	s_nop 1
	v_add_f32_dpp v186, v186, v186 row_ror:4 row_mask:0xf bank_mask:0xf
	s_nop 1
	v_add_f32_dpp v186, v186, v186 row_ror:2 row_mask:0xf bank_mask:0xf
	s_nop 1
	v_add_f32_dpp v186, v186, v186 row_ror:1 row_mask:0xf bank_mask:0xf
	v_lshrrev_b32_e32 v187, 12, v187
	v_lshlrev_b32_e32 v187, 2, v187
	v_lshl_add_u32 v187, v188, s60, v187
	s_mov_b64 s[56:57], exec
	s_mov_b64 exec, s[58:59]
	global_store_dword v187, v186, s[52:53]
	s_mov_b64 exec, s[56:57]
	global_store_dwordx4 v[44:45], v[40:43], off
	ds_read_b128 v[40:43], v130 offset:6528
	s_waitcnt lgkmcnt(0)
; DI void gemm_out_phase(const Params& P, int l, char* smem) {
;     ...
; #pragma unroll
;         for (int i = 0; i < 8; i++) {
;           const int row = i * 4 + fq2;
;           const float4 a = *(const float4*)(stg + row * 68 + fr2 * 4);
;           float4 r = rres[q][i];
;           r.x += g4.x * a.x; r.y += g4.y * a.y; r.z += g4.z * a.z; r.w += g4.w * a.w;
;           *(float4*)(dst + (size_t)(q * 32 + row) * D) = r;
;         }
	v_pk_fma_f32 v[36:37], v[0:1], v[40:41], v[36:37]
	v_add_co_u32_e32 v40, vcc, s88, v104
	v_pk_fma_f32 v[38:39], v[2:3], v[42:43], v[38:39]
	s_nop 0
	v_addc_co_u32_e32 v41, vcc, 0, v105, vcc
	v_mul_f32_e32 v186, v36, v36
	v_fmac_f32_e32 v186, v37, v37
	v_fmac_f32_e32 v186, v38, v38
	v_fmac_f32_e32 v186, v39, v39
	v_subrev_u32_e32 v187, s50, v40
	v_bfe_u32 v188, v187, 8, 4
	s_nop 1
	v_add_f32_dpp v186, v186, v186 row_ror:8 row_mask:0xf bank_mask:0xf
	s_nop 1
	v_add_f32_dpp v186, v186, v186 row_ror:4 row_mask:0xf bank_mask:0xf
	s_nop 1
	v_add_f32_dpp v186, v186, v186 row_ror:2 row_mask:0xf bank_mask:0xf
	s_nop 1
	v_add_f32_dpp v186, v186, v186 row_ror:1 row_mask:0xf bank_mask:0xf
	v_lshrrev_b32_e32 v187, 12, v187
	v_lshlrev_b32_e32 v187, 2, v187
	v_lshl_add_u32 v187, v188, s60, v187
	s_mov_b64 s[56:57], exec
	s_mov_b64 exec, s[58:59]
	global_store_dword v187, v186, s[52:53]
	s_mov_b64 exec, s[56:57]
	global_store_dwordx4 v[40:41], v[36:39], off
	ds_write_b32 v150, a28
	ds_write_b32 v150, a29 offset:272
	ds_write_b32 v150, a30 offset:544
	ds_write_b32 v150, a31 offset:816
	ds_write_b32 v150, a24 offset:64
	ds_write_b32 v150, a25 offset:336
	ds_write_b32 v150, a26 offset:608
	ds_write_b32 v150, a27 offset:880
	ds_write_b32 v150, a20 offset:128
	ds_write_b32 v150, a21 offset:400
	ds_write_b32 v150, a22 offset:672
	ds_write_b32 v150, a23 offset:944
	ds_write_b32 v150, a16 offset:192
	ds_write_b32 v150, a17 offset:464
	ds_write_b32 v150, a18 offset:736
	ds_write_b32 v150, a19 offset:1008
	ds_write_b32 v150, a8 offset:4352
	ds_write_b32 v150, a9 offset:4624
	ds_write_b32 v150, a10 offset:4896
	ds_write_b32 v150, a11 offset:5168
	ds_write_b32 v150, a0 offset:4416
	ds_write_b32 v150, a1 offset:4688
	ds_write_b32 v150, a2 offset:4960
	ds_write_b32 v150, a3 offset:5232
	ds_write_b32 v150, a4 offset:4480
	ds_write_b32 v150, a5 offset:4752
	ds_write_b32 v150, a6 offset:5024
	ds_write_b32 v150, a7 offset:5296
	ds_write_b32 v150, a12 offset:4544
	ds_write_b32 v150, a13 offset:4816
	ds_write_b32 v150, a14 offset:5088
	ds_write_b32 v150, a15 offset:5360
	ds_read_b128 v[36:39], v143
	s_waitcnt lgkmcnt(0)
	v_pk_fma_f32 v[32:33], v[0:1], v[36:37], v[32:33]
	v_add_co_u32_e32 v36, vcc, s2, v140
	v_pk_fma_f32 v[34:35], v[2:3], v[38:39], v[34:35]
	s_nop 0
	v_addc_co_u32_e32 v37, vcc, 0, v141, vcc
	v_mul_f32_e32 v186, v32, v32
	v_fmac_f32_e32 v186, v33, v33
	v_fmac_f32_e32 v186, v34, v34
	v_fmac_f32_e32 v186, v35, v35
	v_subrev_u32_e32 v187, s50, v36
	v_bfe_u32 v188, v187, 8, 4
	s_nop 1
	v_add_f32_dpp v186, v186, v186 row_ror:8 row_mask:0xf bank_mask:0xf
	s_nop 1
	v_add_f32_dpp v186, v186, v186 row_ror:4 row_mask:0xf bank_mask:0xf
	s_nop 1
	v_add_f32_dpp v186, v186, v186 row_ror:2 row_mask:0xf bank_mask:0xf
	s_nop 1
	v_add_f32_dpp v186, v186, v186 row_ror:1 row_mask:0xf bank_mask:0xf
	v_lshrrev_b32_e32 v187, 12, v187
	v_lshlrev_b32_e32 v187, 2, v187
	v_lshl_add_u32 v187, v188, s60, v187
	s_mov_b64 s[56:57], exec
	s_mov_b64 exec, s[58:59]
	global_store_dword v187, v186, s[52:53]
	s_mov_b64 exec, s[56:57]
	global_store_dwordx4 v[36:37], v[32:35], off
	ds_read_b128 v[32:35], v130
	s_waitcnt lgkmcnt(0)
	v_pk_fma_f32 v[28:29], v[0:1], v[32:33], v[28:29]
	v_add_co_u32_e32 v32, vcc, s2, v128
	v_pk_fma_f32 v[30:31], v[2:3], v[34:35], v[30:31]
	s_nop 0
	v_addc_co_u32_e32 v33, vcc, 0, v129, vcc
	v_mul_f32_e32 v186, v28, v28
	v_fmac_f32_e32 v186, v29, v29
	v_fmac_f32_e32 v186, v30, v30
	v_fmac_f32_e32 v186, v31, v31
	v_subrev_u32_e32 v187, s50, v32
	v_bfe_u32 v188, v187, 8, 4
	s_nop 1
	v_add_f32_dpp v186, v186, v186 row_ror:8 row_mask:0xf bank_mask:0xf
	s_nop 1
	v_add_f32_dpp v186, v186, v186 row_ror:4 row_mask:0xf bank_mask:0xf
	s_nop 1
	v_add_f32_dpp v186, v186, v186 row_ror:2 row_mask:0xf bank_mask:0xf
	s_nop 1
	v_add_f32_dpp v186, v186, v186 row_ror:1 row_mask:0xf bank_mask:0xf
	v_lshrrev_b32_e32 v187, 12, v187
	v_lshlrev_b32_e32 v187, 2, v187
	v_lshl_add_u32 v187, v188, s60, v187
	s_mov_b64 s[56:57], exec
	s_mov_b64 exec, s[58:59]
	global_store_dword v187, v186, s[52:53]
	s_mov_b64 exec, s[56:57]
	global_store_dwordx4 v[32:33], v[28:31], off
	ds_read_b128 v[28:31], v130 offset:1088
	s_waitcnt lgkmcnt(0)
	v_pk_fma_f32 v[24:25], v[0:1], v[28:29], v[24:25]
	v_add_co_u32_e32 v28, vcc, s2, v124
	v_pk_fma_f32 v[26:27], v[2:3], v[30:31], v[26:27]
	s_nop 0
	v_addc_co_u32_e32 v29, vcc, 0, v125, vcc
	v_mul_f32_e32 v186, v24, v24
	v_fmac_f32_e32 v186, v25, v25
	v_fmac_f32_e32 v186, v26, v26
	v_fmac_f32_e32 v186, v27, v27
	v_subrev_u32_e32 v187, s50, v28
	v_bfe_u32 v188, v187, 8, 4
	s_nop 1
	v_add_f32_dpp v186, v186, v186 row_ror:8 row_mask:0xf bank_mask:0xf
	s_nop 1
	v_add_f32_dpp v186, v186, v186 row_ror:4 row_mask:0xf bank_mask:0xf
	s_nop 1
	v_add_f32_dpp v186, v186, v186 row_ror:2 row_mask:0xf bank_mask:0xf
	s_nop 1
	v_add_f32_dpp v186, v186, v186 row_ror:1 row_mask:0xf bank_mask:0xf
	v_lshrrev_b32_e32 v187, 12, v187
	v_lshlrev_b32_e32 v187, 2, v187
	v_lshl_add_u32 v187, v188, s60, v187
	s_mov_b64 s[56:57], exec
	s_mov_b64 exec, s[58:59]
	global_store_dword v187, v186, s[52:53]
	s_mov_b64 exec, s[56:57]
	global_store_dwordx4 v[28:29], v[24:27], off
	ds_read_b128 v[24:27], v130 offset:2176
	s_waitcnt lgkmcnt(0)
; DI void gemm_out_phase(const Params& P, int l, char* smem) {
;     ...
; #pragma unroll
;         for (int i = 0; i < 8; i++) {
;           const int row = i * 4 + fq2;
;           const float4 a = *(const float4*)(stg + row * 68 + fr2 * 4);
;           float4 r = rres[q][i];
;           r.x += g4.x * a.x; r.y += g4.y * a.y; r.z += g4.z * a.z; r.w += g4.w * a.w;
;           *(float4*)(dst + (size_t)(q * 32 + row) * D) = r;
;         }
	v_pk_fma_f32 v[20:21], v[0:1], v[24:25], v[20:21]
	v_add_co_u32_e32 v24, vcc, s2, v120
	v_pk_fma_f32 v[22:23], v[2:3], v[26:27], v[22:23]
	s_nop 0
	v_addc_co_u32_e32 v25, vcc, 0, v121, vcc
	v_mul_f32_e32 v186, v20, v20
	v_fmac_f32_e32 v186, v21, v21
	v_fmac_f32_e32 v186, v22, v22
	v_fmac_f32_e32 v186, v23, v23
	v_subrev_u32_e32 v187, s50, v24
	v_bfe_u32 v188, v187, 8, 4
	s_nop 1
	v_add_f32_dpp v186, v186, v186 row_ror:8 row_mask:0xf bank_mask:0xf
	s_nop 1
	v_add_f32_dpp v186, v186, v186 row_ror:4 row_mask:0xf bank_mask:0xf
	s_nop 1
	v_add_f32_dpp v186, v186, v186 row_ror:2 row_mask:0xf bank_mask:0xf
	s_nop 1
	v_add_f32_dpp v186, v186, v186 row_ror:1 row_mask:0xf bank_mask:0xf
	v_lshrrev_b32_e32 v187, 12, v187
	v_lshlrev_b32_e32 v187, 2, v187
	v_lshl_add_u32 v187, v188, s60, v187
	s_mov_b64 s[56:57], exec
	s_mov_b64 exec, s[58:59]
	global_store_dword v187, v186, s[52:53]
	s_mov_b64 exec, s[56:57]
	global_store_dwordx4 v[24:25], v[20:23], off
	ds_read_b128 v[20:23], v130 offset:3264
	s_waitcnt lgkmcnt(0)
	v_pk_fma_f32 v[16:17], v[0:1], v[20:21], v[16:17]
	v_add_co_u32_e32 v20, vcc, s2, v116
	v_pk_fma_f32 v[18:19], v[2:3], v[22:23], v[18:19]
	s_nop 0
	v_addc_co_u32_e32 v21, vcc, 0, v117, vcc
	v_mul_f32_e32 v186, v16, v16
	v_fmac_f32_e32 v186, v17, v17
	v_fmac_f32_e32 v186, v18, v18
	v_fmac_f32_e32 v186, v19, v19
	v_subrev_u32_e32 v187, s50, v20
	v_bfe_u32 v188, v187, 8, 4
	s_nop 1
	v_add_f32_dpp v186, v186, v186 row_ror:8 row_mask:0xf bank_mask:0xf
	s_nop 1
	v_add_f32_dpp v186, v186, v186 row_ror:4 row_mask:0xf bank_mask:0xf
	s_nop 1
	v_add_f32_dpp v186, v186, v186 row_ror:2 row_mask:0xf bank_mask:0xf
	s_nop 1
	v_add_f32_dpp v186, v186, v186 row_ror:1 row_mask:0xf bank_mask:0xf
	v_lshrrev_b32_e32 v187, 12, v187
	v_lshlrev_b32_e32 v187, 2, v187
	v_lshl_add_u32 v187, v188, s60, v187
	s_mov_b64 s[56:57], exec
	s_mov_b64 exec, s[58:59]
	global_store_dword v187, v186, s[52:53]
	s_mov_b64 exec, s[56:57]
	global_store_dwordx4 v[20:21], v[16:19], off
	ds_read_b128 v[16:19], v130 offset:4352
	s_waitcnt lgkmcnt(0)
	v_pk_fma_f32 v[12:13], v[0:1], v[16:17], v[12:13]
	v_add_co_u32_e32 v16, vcc, s2, v112
	v_pk_fma_f32 v[14:15], v[2:3], v[18:19], v[14:15]
	s_nop 0
	v_addc_co_u32_e32 v17, vcc, 0, v113, vcc
	v_mul_f32_e32 v186, v12, v12
	v_fmac_f32_e32 v186, v13, v13
	v_fmac_f32_e32 v186, v14, v14
	v_fmac_f32_e32 v186, v15, v15
	v_subrev_u32_e32 v187, s50, v16
	v_bfe_u32 v188, v187, 8, 4
	s_nop 1
	v_add_f32_dpp v186, v186, v186 row_ror:8 row_mask:0xf bank_mask:0xf
	s_nop 1
	v_add_f32_dpp v186, v186, v186 row_ror:4 row_mask:0xf bank_mask:0xf
	s_nop 1
	v_add_f32_dpp v186, v186, v186 row_ror:2 row_mask:0xf bank_mask:0xf
	s_nop 1
	v_add_f32_dpp v186, v186, v186 row_ror:1 row_mask:0xf bank_mask:0xf
	v_lshrrev_b32_e32 v187, 12, v187
	v_lshlrev_b32_e32 v187, 2, v187
	v_lshl_add_u32 v187, v188, s60, v187
	s_mov_b64 s[56:57], exec
	s_mov_b64 exec, s[58:59]
	global_store_dword v187, v186, s[52:53]
	s_mov_b64 exec, s[56:57]
	global_store_dwordx4 v[16:17], v[12:15], off
	ds_read_b128 v[12:15], v130 offset:5440
	s_waitcnt lgkmcnt(0)
	v_pk_fma_f32 v[8:9], v[0:1], v[12:13], v[8:9]
	v_add_co_u32_e32 v12, vcc, s2, v108
	v_pk_fma_f32 v[10:11], v[2:3], v[14:15], v[10:11]
	s_nop 0
	v_addc_co_u32_e32 v13, vcc, 0, v109, vcc
	v_mul_f32_e32 v186, v8, v8
	v_fmac_f32_e32 v186, v9, v9
	v_fmac_f32_e32 v186, v10, v10
	v_fmac_f32_e32 v186, v11, v11
	v_subrev_u32_e32 v187, s50, v12
	v_bfe_u32 v188, v187, 8, 4
	s_nop 1
	v_add_f32_dpp v186, v186, v186 row_ror:8 row_mask:0xf bank_mask:0xf
	s_nop 1
	v_add_f32_dpp v186, v186, v186 row_ror:4 row_mask:0xf bank_mask:0xf
	s_nop 1
	v_add_f32_dpp v186, v186, v186 row_ror:2 row_mask:0xf bank_mask:0xf
	s_nop 1
	v_add_f32_dpp v186, v186, v186 row_ror:1 row_mask:0xf bank_mask:0xf
	v_lshrrev_b32_e32 v187, 12, v187
	v_lshlrev_b32_e32 v187, 2, v187
	v_lshl_add_u32 v187, v188, s60, v187
	s_mov_b64 s[56:57], exec
	s_mov_b64 exec, s[58:59]
	global_store_dword v187, v186, s[52:53]
	s_mov_b64 exec, s[56:57]
	global_store_dwordx4 v[12:13], v[8:11], off
	ds_read_b128 v[8:11], v130 offset:6528
	s_waitcnt lgkmcnt(0)
	v_pk_fma_f32 v[0:1], v[0:1], v[8:9], v[4:5]
	v_add_co_u32_e32 v4, vcc, 0x60000, v104
	v_pk_fma_f32 v[2:3], v[2:3], v[10:11], v[6:7]
	s_nop 0
	v_addc_co_u32_e32 v5, vcc, 0, v105, vcc
	s_andn2_b64 vcc, exec, s[0:1]
	v_mul_f32_e32 v186, v0, v0
	v_fmac_f32_e32 v186, v1, v1
	v_fmac_f32_e32 v186, v2, v2
	v_fmac_f32_e32 v186, v3, v3
	v_subrev_u32_e32 v187, s50, v4
	v_bfe_u32 v188, v187, 8, 4
	s_nop 1
	v_add_f32_dpp v186, v186, v186 row_ror:8 row_mask:0xf bank_mask:0xf
	s_nop 1
	v_add_f32_dpp v186, v186, v186 row_ror:4 row_mask:0xf bank_mask:0xf
	s_nop 1
	v_add_f32_dpp v186, v186, v186 row_ror:2 row_mask:0xf bank_mask:0xf
	s_nop 1
	v_add_f32_dpp v186, v186, v186 row_ror:1 row_mask:0xf bank_mask:0xf
	v_lshrrev_b32_e32 v187, 12, v187
	v_lshlrev_b32_e32 v187, 2, v187
	v_lshl_add_u32 v187, v188, s60, v187
	s_mov_b64 s[56:57], exec
	s_mov_b64 exec, s[58:59]
	global_store_dword v187, v186, s[52:53]
	s_mov_b64 exec, s[56:57]
	global_store_dwordx4 v[4:5], v[0:3], off
	s_cbranch_vccz .LBB0_533

; #define TIDX tid_opaque()
; DI void row2_phase(const Params& P, int l, int r_begin, char* smem) {
;   const int tid = TIDX, lane = tid & 63, wave = tid >> 6, fr = lane & 15, fq = lane >> 4;
;   float* lg = (float*)smem + wave * 16 * 48;
;   const half_t* Whi = P.WrH + (size_t)(l * 2) * 49152; const half_t* Wlo = Whi + 49152;
;   const int ngroups = (TA - r_begin) >> 4, gw = blockIdx.x * 4 + wave, nw = gridDim.x * 4;
;   const float* gam = P.norm2_g + l * 1024;
;   const int gper = (ngroups + nw - 1) / nw;
; #pragma unroll 1
;   for (int grp = gw * gper; grp < min((gw + 1) * gper, ngroups); grp++) {
.LBB0_542:
	s_or_b64 exec, exec, s[0:1]
	v_readlane_b32 s0, v255, 48
	v_readlane_b32 s1, v255, 49
	s_and_b64 s[0:1], s[0:1], exec
	s_cselect_b32 s22, 0, 0x800
	v_mov_b32_e32 v1, v172
	s_lshr_b32 s0, s22, 4
	s_barrier
	s_mov_b32 s44, 0
	v_accvgpr_write_b32 a255, v104
	v_and_b32_e32 v104, 0xff, v172
	v_lshlrev_b32_e32 v104, 4, v104
	v_add_u32_e32 v104, 0x4000, v104
	ds_write_b128 v104, v[84:87] offset:0
	ds_write_b128 v104, v[88:91] offset:4096
	ds_write_b128 v104, v[92:95] offset:8192
	ds_write_b128 v104, v[96:99] offset:12288
	ds_write_b128 v104, v[100:103] offset:16384
	s_waitcnt lgkmcnt(0)
	v_accvgpr_read_b32 v104, a255
	v_mov_b32_e32 v84, 0
	v_lshlrev_b32_e32 v85, 2, v172
	v_add_u32_e32 v85, 0x3000, v85
	ds_write_b32 v85, v84
	s_waitcnt lgkmcnt(0)
	s_barrier
	s_xor_b32 s1, s0, 0x1080
	v_ashrrev_i32_e32 v2, 6, v1
	v_readlane_b32 s0, v254, 20
	v_readlane_b32 s3, v254, 22
	v_readlane_b32 s6, v254, 25
	v_add_u32_e32 v0, s0, v2
	v_readlane_b32 s0, v254, 21
	s_add_i32 s0, s0, s1
	s_ashr_i32 s2, s0, 31
	s_xor_b32 s2, s2, s3
	s_abs_i32 s0, s0
	v_readlane_b32 s3, v254, 26
	s_mul_hi_u32 s3, s0, s3
	s_mul_i32 s4, s3, s6
	s_sub_i32 s0, s0, s4
	s_add_i32 s4, s3, 1
	s_sub_i32 s5, s0, s6
	s_cmp_ge_u32 s0, s6
	s_cselect_b32 s3, s4, s3
	s_cselect_b32 s0, s5, s0
	s_add_i32 s4, s3, 1
	s_cmp_ge_u32 s0, s6
	s_cselect_b32 s0, s4, s3
	s_xor_b32 s0, s0, s2
	s_sub_i32 s0, s0, s2
	v_mul_lo_u32 v17, v0, s0
	v_add_u32_e32 v3, s0, v17
	v_min_i32_e32 v52, s1, v3
	v_cmp_lt_i32_e32 vcc, v17, v52
	s_and_saveexec_b64 s[10:11], vcc
	s_cbranch_execz .LBB0_551
	v_readlane_b32 s2, v254, 39
	v_readlane_b32 s48, v255, 3
	v_readlane_b32 s3, v254, 40
	v_readlane_b32 s56, v255, 11
	v_readlane_b32 s57, v255, 12
	v_readlane_b32 s58, v255, 13
	v_readlane_b32 s59, v255, 14
	v_readlane_b32 s60, v255, 15
	v_readlane_b32 s61, v255, 16
	s_mov_b32 s3, s85
	v_readlane_b32 s62, v255, 17
	v_readlane_b32 s63, v255, 18
	s_mov_b64 s[56:57], s[60:61]
	s_lshl_b64 s[2:3], s[2:3], 2
	s_mov_b64 s[58:59], s[62:63]
	v_readlane_b32 s49, v255, 4
	v_readlane_b32 s50, v255, 5
	v_readlane_b32 s51, v255, 6
	v_readlane_b32 s52, v255, 7
	v_readlane_b32 s53, v255, 8
	v_readlane_b32 s54, v255, 9
	v_readlane_b32 s55, v255, 10
	s_add_u32 s2, s58, s2
	s_addc_u32 s3, s59, s3
	s_movk_i32 s1, 0xc00
	v_bfe_u32 v4, v1, 4, 2
	v_readlane_b32 s4, v255, 26
	v_readlane_b32 s48, v253, 35
	v_and_b32_e32 v53, 63, v1
	v_and_b32_e32 v54, 15, v1
	v_mul_lo_u32 v3, v2, s1
	v_lshlrev_b32_e32 v12, 5, v4
	v_mov_b32_e32 v13, v149
	s_movk_i32 s1, 0xc0
	s_lshl_b32 s23, s4, 5
	v_readlane_b32 s50, v253, 37
	v_readlane_b32 s6, v254, 41
	v_mul_lo_u32 v0, v0, s0
	v_lshlrev_b32_e32 v2, 3, v4
	v_lshl_add_u64 v[14:15], s[2:3], 0, v[12:13]
	v_lshl_or_b32 v5, v54, 2, v3
	v_mad_u32_u24 v13, v53, s1, v3
	v_mul_u32_u24_e32 v3, 0x300, v4
	v_readlane_b32 s51, v253, 38
	v_readlane_b32 s7, v254, 42
	s_add_u32 s8, s50, s6
	s_mul_hi_u32 s1, s4, 0x30000
	s_mul_i32 s4, s4, 0x30000
	v_lshlrev_b32_e32 v4, 11, v54
	v_and_b32_e32 v16, 48, v1
	v_lshlrev_b32_e32 v0, 4, v0
	v_cmp_gt_u32_e64 s[2:3], 16, v53
	s_addc_u32 s9, s51, s7
	v_or3_b32 v18, s4, v4, v16
	v_mov_b32_e32 v19, s1
	v_add3_u32 v20, s22, v0, v54
	s_mov_b64 s[20:21], 0
	v_lshlrev_b32_e32 v148, 2, v2
	v_add_u32_e32 v55, v5, v3
	v_readlane_b32 s5, v255, 27
	v_readlane_b32 s49, v253, 36
	v_readlane_b32 s52, v253, 39
	v_readlane_b32 s53, v253, 40
	v_readlane_b32 s54, v253, 41
	v_readlane_b32 s55, v253, 42
	v_readlane_b32 s56, v253, 43
	v_readlane_b32 s57, v253, 44
	v_readlane_b32 s58, v253, 45
	v_readlane_b32 s59, v253, 46
	v_readlane_b32 s60, v253, 47
	v_readlane_b32 s61, v253, 48
	v_readlane_b32 s62, v253, 49
	v_readlane_b32 s63, v253, 50
	s_branch .LBB0_545

; DI float shx(float v, int o) { int ln = TIDX & 63; return __builtin_bit_cast(float, __builtin_amdgcn_ds_bpermute((ln ^ o) << 2, __builtin_bit_cast(int, v))); }
; DI void row2_phase(const Params& P, int l, int r_begin, char* smem) {
;     ...
;     const int r0 = r_begin + grp * 16, row = r0 + fr, n = row_mod(r0);
;     const float* xm = (row < TC ? P.xcbuf + (size_t)row * D : P.out + (size_t)(row - TC) * D) + fq * 8;
;     float ss = 0.f;
; #pragma unroll 16
;     for (int kk = 0; kk < 32; kk++) {
;       const float4 a = *(const float4*)(xm + kk * 32), b = *(const float4*)(xm + kk * 32 + 4);
;       ss += a.x * a.x + a.y * a.y + a.z * a.z + a.w * a.w + b.x * b.x + b.y * b.y + b.z * b.z + b.w * b.w;
;     }
;     ss += shx(ss, 16); ss += shx(ss, 32);
;     const float rstd = rsqrtf(ss * (1.f / 1024.f) + EPS);
;     const float* sh = P.mod + (size_t)(l * 9 + n) * 6144 + 3 * 1024 + fq * 8; const float* sc = sh + 1024;
;     f4 acc[3];
; #pragma unroll
;     for (int i = 0; i < 3; i++) acc[i] = (f4){0.f, 0.f, 0.f, 0.f};
;     half_t* hxo = P.hx + (size_t)row * D + fq * 8;
; #pragma unroll 4
;     for (int kk = 0; kk < 32; kk++) {
;       const int k0 = kk * 32;
;       float x[8], g[8], s1[8], s0[8];
;       *(float4*)&x[0] = *(const float4*)(xm + k0); *(float4*)&x[4] = *(const float4*)(xm + k0 + 4);
;       *(float4*)&g[0] = *(const float4*)(gam + fq * 8 + k0); *(float4*)&g[4] = *(const float4*)(gam + fq * 8 + k0 + 4);
;       *(float4*)&s1[0] = *(const float4*)(sc + k0); *(float4*)&s1[4] = *(const float4*)(sc + k0 + 4);
;       *(float4*)&s0[0] = *(const float4*)(sh + k0); *(float4*)&s0[4] = *(const float4*)(sh + k0 + 4);
.LBB0_546:
	v_readfirstlane_b32 s100, v22
	v_readfirstlane_b32 s101, v23
	s_sub_u32 s98, s100, s14
	s_subb_u32 s99, s101, s15
	s_cmp_eq_u32 s99, 0
	s_cselect_b32 s98, s98, -1
	s_cmp_lt_u32 s98, 0x800000
	s_cselect_b32 s32, s14, s62
	s_cselect_b32 s84, 0x400000, 0
	s_cselect_b32 s101, 15, 20
	s_add_u32 s98, s90, 0x200bc700
	s_addc_u32 s99, s91, 0
	s_add_u32 s98, s98, s84
	s_addc_u32 s99, s99, 0
	s_sub_u32 s84, s101, 2
	s_lshl_b32 s84, 1, s84
	v_subrev_u32_e32 v2, s32, v22
	v_lshrrev_b32_e32 v2, 12, v2
	v_bfe_u32 v3, v172, 4, 2
	v_lshlrev_b32_e32 v2, 2, v2
	v_lshlrev_b32_e32 v3, s101, v3
	v_add_u32_e32 v2, v2, v3
	v_add_u32_e32 v3, s84, v2
	v_add_u32_e32 v4, s84, v3
	v_add_u32_e32 v5, s84, v4
	global_load_dword v2, v2, s[98:99]
	global_load_dword v3, v3, s[98:99]
	global_load_dword v4, v4, s[98:99]
	global_load_dword v5, v5, s[98:99]
	s_waitcnt vmcnt(0)
	v_add_f32_e32 v0, v2, v3
	v_add_f32_e32 v1, v4, v5
	v_add_f32_e32 v0, v0, v1
	v_mov_b32_e32 v2, v172
	v_bfrev_b32_e32 v3, 0.5
	v_lshlrev_b32_e32 v2, 2, v2
	v_bitop3_b32 v2, v2, 64, v3 bitop3:0x6c
	ds_bpermute_b32 v2, v2, v0
	s_movk_i32 s0, 0x7ff
	v_cmp_lt_i32_e32 vcc, s0, v56
	s_movk_i32 s0, 0x80
	v_add_u32_e32 v1, 0xfffff800, v56
	s_waitcnt lgkmcnt(0)
	v_add_f32_e32 v0, v0, v2
	v_mov_b32_e32 v2, v172
	v_lshrrev_b32_e32 v1, 13, v1
	v_lshlrev_b32_e32 v2, 2, v2
	v_bitop3_b32 v2, v2, s0, v3 bitop3:0x6c
	ds_bpermute_b32 v2, v2, v0
	v_cndmask_b32_e32 v1, 8, v1, vcc
	v_ashrrev_i32_e32 v21, 31, v20
	v_add_u32_e32 v1, s89, v1
	v_lshlrev_b64 v[24:25], 11, v[20:21]
	s_waitcnt lgkmcnt(0)
	v_add_f32_e32 v0, v0, v2
	v_mov_b32_e32 v2, 0x358637bd
	v_fmamk_f32 v0, v0, 0x3a800000, v2
	v_cmp_gt_f32_e32 vcc, s46, v0
	v_mul_f32_e32 v2, 0x4b800000, v0
	v_mul_hi_u32_u24_e32 v27, 0x6000, v1
	v_cndmask_b32_e32 v0, v0, v2, vcc
	v_rsq_f32_e32 v0, v0
	v_mul_u32_u24_e32 v1, 0x6000, v1
	v_or_b32_e32 v24, v16, v24
	v_or_b32_e32 v26, v12, v1
	v_mul_f32_e32 v2, 0x45800000, v0
	v_cndmask_b32_e32 v28, v0, v2, vcc
	v_mov_b32_e32 v29, v28
	v_accvgpr_write_b32 a3, 0
	v_accvgpr_write_b32 a2, 0
	v_accvgpr_write_b32 a1, 0
	v_accvgpr_write_b32 a0, 0
	v_accvgpr_write_b32 a7, 0
	v_accvgpr_write_b32 a6, 0
	v_accvgpr_write_b32 a5, 0
	v_accvgpr_write_b32 a4, 0
	v_accvgpr_write_b32 a11, 0
	v_accvgpr_write_b32 a10, 0
	v_accvgpr_write_b32 a9, 0
	v_accvgpr_write_b32 a8, 0
	s_mov_b64 s[0:1], 0
	v_mov_b64_e32 v[30:31], v[18:19]
.LBB0_548:
	v_lshl_add_u64 v[84:85], s[90:91], 0, v[26:27]
	s_mov_b64 s[100:101], 0xce03000
	v_lshl_add_u64 v[86:87], v[84:85], 0, s[100:101]
	s_mov_b64 s[100:101], 0xce04000
	v_lshl_add_u64 v[84:85], v[84:85], 0, s[100:101]
	v_lshl_add_u64 v[88:89], s[90:91], 0, v[24:25]
	s_mov_b64 s[100:101], 0xf8bc700
	v_lshl_add_u64 v[88:89], v[88:89], 0, s[100:101]
	v_readlane_b32 s100, v255, 26
	v_and_b32_e32 v90, 15, v172
	v_bfe_u32 v91, v172, 4, 2
	v_lshlrev_b32_e32 v90, 11, v90
	v_lshl_or_b32 v90, v91, 4, v90
	v_mov_b32_e32 v91, 0
	s_mul_i32 s100, s100, 0x30000
	s_add_u32 s100, s100, 0xf85c700
	s_mov_b32 s101, 0
	v_lshl_add_u64 v[90:91], s[90:91], 0, v[90:91]
	v_lshl_add_u64 v[90:91], v[90:91], 0, s[100:101]
	s_mov_b64 s[100:101], 0x18000
	v_lshl_add_u64 v[92:93], v[90:91], 0, s[100:101]
	s_mov_b64 s[100:101], 0x8000
	v_lshl_add_u64 v[94:95], v[90:91], 0, s[100:101]
	s_mov_b64 s[100:101], 0x20000
	v_lshl_add_u64 v[96:97], v[90:91], 0, s[100:101]
	s_mov_b64 s[100:101], 0x10000
	v_lshl_add_u64 v[98:99], v[90:91], 0, s[100:101]
	s_mov_b64 s[100:101], 0x28000
	v_lshl_add_u64 v[100:101], v[90:91], 0, s[100:101]
	v_lshrrev_b32_e32 v102, 6, v172
	v_mul_u32_u24_e32 v102, 0x3000, v102
	v_bfe_u32 v103, v172, 4, 2
	v_lshl_add_u32 v102, v103, 5, v102
	v_add_u32_e32 v102, 0x18000, v102
	v_readfirstlane_b32 s100, v84
	s_cmp_eq_u32 s100, s44
	s_cbranch_scc1 .Lr2_tabok
	s_mov_b32 s44, s100
	v_and_b32_e32 v66, 15, v172
	v_lshlrev_b32_e32 v66, 8, v66
	v_mov_b32_e32 v67, 0
	v_lshl_add_u64 v[68:69], v[14:15], 0, v[66:67]
	global_load_dwordx4 a[16:19], v[68:69], off offset:0
	global_load_dwordx4 a[20:23], v[68:69], off offset:16
	global_load_dwordx4 a[24:27], v[68:69], off offset:128
	global_load_dwordx4 a[28:31], v[68:69], off offset:144
	v_lshl_add_u64 v[68:69], v[84:85], 0, v[66:67]
	global_load_dwordx4 a[32:35], v[68:69], off offset:0
	global_load_dwordx4 a[36:39], v[68:69], off offset:16
	global_load_dwordx4 a[40:43], v[68:69], off offset:128
	global_load_dwordx4 a[44:47], v[68:69], off offset:144
	v_lshl_add_u64 v[68:69], v[86:87], 0, v[66:67]
	global_load_dwordx4 a[48:51], v[68:69], off offset:0
	global_load_dwordx4 a[52:55], v[68:69], off offset:16
	global_load_dwordx4 a[56:59], v[68:69], off offset:128
	global_load_dwordx4 a[60:63], v[68:69], off offset:144
	v_add_u32_e32 v70, v102, v66
	s_waitcnt vmcnt(0)
	ds_write_b128 v70, a[16:19] offset:0
	ds_write_b128 v70, a[20:23] offset:16
	ds_write_b128 v70, a[24:27] offset:128
	ds_write_b128 v70, a[28:31] offset:144
	ds_write_b128 v70, a[32:35] offset:4096
	ds_write_b128 v70, a[36:39] offset:4112
	ds_write_b128 v70, a[40:43] offset:4224
	ds_write_b128 v70, a[44:47] offset:4240
	ds_write_b128 v70, a[48:51] offset:8192
	ds_write_b128 v70, a[52:55] offset:8208
	ds_write_b128 v70, a[56:59] offset:8320
	ds_write_b128 v70, a[60:63] offset:8336
	s_waitcnt lgkmcnt(0)
; DI f4 mfma16(h8 a, h8 b, f4 c) { return __builtin_amdgcn_mfma_f32_16x16x32_f16(a, b, c, 0, 0, 0); }
; DI void row2_phase(const Params& P, int l, int r_begin, char* smem) {
;     ...
; #pragma unroll 4
;     for (int kk = 0; kk < 32; kk++) {
;       const int k0 = kk * 32;
;       float x[8], g[8], s1[8], s0[8];
;       *(float4*)&x[0] = *(const float4*)(xm + k0); *(float4*)&x[4] = *(const float4*)(xm + k0 + 4);
;       *(float4*)&g[0] = *(const float4*)(gam + fq * 8 + k0); *(float4*)&g[4] = *(const float4*)(gam + fq * 8 + k0 + 4);
;       *(float4*)&s1[0] = *(const float4*)(sc + k0); *(float4*)&s1[4] = *(const float4*)(sc + k0 + 4);
;       *(float4*)&s0[0] = *(const float4*)(sh + k0); *(float4*)&s0[4] = *(const float4*)(sh + k0 + 4);
;       h8 hi, lo;
; #pragma unroll
;       for (int i = 0; i < 8; i++) {
;         float v = x[i] * rstd * g[i] * (1.f + s1[i]) + s0[i];
;         hi[i] = (half_t)v; lo[i] = (half_t)(v - (float)hi[i]);
;       }
;       *(h8*)(hxo + k0) = hi;
; #pragma unroll
;       for (int n3 = 0; n3 < 3; n3++) {
;         h8 bh = *(const h8*)(Whi + (size_t)(n3 * 16 + fr) * 1024 + k0 + fq * 8);
;         h8 bl = *(const h8*)(Wlo + (size_t)(n3 * 16 + fr) * 1024 + k0 + fq * 8);
;         acc[n3] = mfma16(hi, bh, acc[n3]); acc[n3] = mfma16(lo, bh, acc[n3]); acc[n3] = mfma16(hi, bl, acc[n3]);
;       }
;     }
.Lr2_tabok:
	global_load_dwordx4 a[16:19], v[22:23], off offset:0
	global_load_dwordx4 a[20:23], v[22:23], off offset:16
	global_load_dwordx4 a[24:27], v[22:23], off offset:128
	global_load_dwordx4 a[28:31], v[22:23], off offset:144
	global_load_dwordx4 a[32:35], v[22:23], off offset:256
	global_load_dwordx4 a[36:39], v[22:23], off offset:272
	global_load_dwordx4 a[40:43], v[22:23], off offset:384
	global_load_dwordx4 a[44:47], v[22:23], off offset:400
	global_load_dwordx4 a[48:51], v[22:23], off offset:512
	global_load_dwordx4 a[52:55], v[22:23], off offset:528
	global_load_dwordx4 a[56:59], v[22:23], off offset:640
	global_load_dwordx4 a[60:63], v[22:23], off offset:656
	global_load_dwordx4 a[64:67], v[22:23], off offset:768
	global_load_dwordx4 a[68:71], v[22:23], off offset:784
	global_load_dwordx4 a[72:75], v[22:23], off offset:896
	global_load_dwordx4 a[76:79], v[22:23], off offset:912
	global_load_dwordx4 a[80:83], v[90:91], off offset:0
	global_load_dwordx4 a[84:87], v[92:93], off offset:0
	global_load_dwordx4 a[88:91], v[94:95], off offset:0
	global_load_dwordx4 a[92:95], v[96:97], off offset:0
	global_load_dwordx4 a[96:99], v[98:99], off offset:0
	global_load_dwordx4 a[100:103], v[100:101], off offset:0
	global_load_dwordx4 a[104:107], v[90:91], off offset:64
	global_load_dwordx4 a[108:111], v[92:93], off offset:64
	global_load_dwordx4 a[112:115], v[94:95], off offset:64
	global_load_dwordx4 a[116:119], v[96:97], off offset:64
	global_load_dwordx4 a[120:123], v[98:99], off offset:64
	global_load_dwordx4 a[124:127], v[100:101], off offset:64
	global_load_dwordx4 a[128:131], v[90:91], off offset:128
	global_load_dwordx4 a[132:135], v[92:93], off offset:128
	global_load_dwordx4 a[136:139], v[94:95], off offset:128
	global_load_dwordx4 a[140:143], v[96:97], off offset:128
	global_load_dwordx4 a[144:147], v[98:99], off offset:128
	global_load_dwordx4 a[148:151], v[100:101], off offset:128
	global_load_dwordx4 a[152:155], v[90:91], off offset:192
	global_load_dwordx4 a[156:159], v[92:93], off offset:192
	global_load_dwordx4 a[160:163], v[94:95], off offset:192
	global_load_dwordx4 a[164:167], v[96:97], off offset:192
	global_load_dwordx4 a[168:171], v[98:99], off offset:192
	global_load_dwordx4 a[172:175], v[100:101], off offset:192
	global_load_dwordx4 a[204:207], v[90:91], off offset:256
	global_load_dwordx4 a[208:211], v[92:93], off offset:256
	global_load_dwordx4 a[212:215], v[94:95], off offset:256
	global_load_dwordx4 a[216:219], v[96:97], off offset:256
	global_load_dwordx4 a[220:223], v[98:99], off offset:256
	global_load_dwordx4 a[224:227], v[100:101], off offset:256
	global_load_dwordx4 a[228:231], v[90:91], off offset:320
	global_load_dwordx4 a[232:235], v[92:93], off offset:320
	global_load_dwordx4 a[236:239], v[94:95], off offset:320
	global_load_dwordx4 a[240:243], v[96:97], off offset:320
	global_load_dwordx4 a[244:247], v[98:99], off offset:320
	global_load_dwordx4 a[248:251], v[100:101], off offset:320
	ds_read_b128 v[32:35], v102 offset:0
	ds_read_b128 v[36:39], v102 offset:16
	ds_read_b128 v[40:43], v102 offset:4096
	ds_read_b128 v[44:47], v102 offset:4112
	ds_read_b128 v[58:61], v102 offset:8192
	ds_read_b128 v[62:65], v102 offset:8208
	s_waitcnt vmcnt(50)
	v_accvgpr_read_b32 v0, a16
	v_accvgpr_read_b32 v1, a17
	v_accvgpr_read_b32 v2, a18
	v_accvgpr_read_b32 v3, a19
	v_accvgpr_read_b32 v4, a20
	v_accvgpr_read_b32 v5, a21
	v_accvgpr_read_b32 v6, a22
	v_accvgpr_read_b32 v7, a23
	global_load_dwordx4 a[16:19], v[22:23], off offset:1024
	global_load_dwordx4 a[20:23], v[22:23], off offset:1040
	v_pk_mul_f32 v[0:1], v[28:29], v[0:1]
	v_pk_mul_f32 v[2:3], v[28:29], v[2:3]
	v_pk_mul_f32 v[4:5], v[28:29], v[4:5]
	v_pk_mul_f32 v[6:7], v[28:29], v[6:7]
	s_waitcnt lgkmcnt(0)
	v_pk_mul_f32 v[0:1], v[0:1], v[32:33]
	v_pk_mul_f32 v[2:3], v[2:3], v[34:35]
	v_pk_mul_f32 v[4:5], v[4:5], v[36:37]
	v_pk_mul_f32 v[6:7], v[6:7], v[38:39]
	v_pk_add_f32 v[40:41], v[40:41], 1.0 op_sel_hi:[1,0]
	v_pk_add_f32 v[42:43], v[42:43], 1.0 op_sel_hi:[1,0]
	v_pk_add_f32 v[44:45], v[44:45], 1.0 op_sel_hi:[1,0]
	v_pk_add_f32 v[46:47], v[46:47], 1.0 op_sel_hi:[1,0]
	v_pk_fma_f32 v[0:1], v[0:1], v[40:41], v[58:59]
	v_pk_fma_f32 v[2:3], v[2:3], v[42:43], v[60:61]
	v_pk_fma_f32 v[4:5], v[4:5], v[44:45], v[62:63]
	v_pk_fma_f32 v[6:7], v[6:7], v[46:47], v[64:65]
	ds_read_b128 v[32:35], v102 offset:128
	ds_read_b128 v[36:39], v102 offset:144
	ds_read_b128 v[40:43], v102 offset:4224
	ds_read_b128 v[44:47], v102 offset:4240
	ds_read_b128 v[58:61], v102 offset:8320
	ds_read_b128 v[62:65], v102 offset:8336
	v_cvt_pk_f16_f32 v74, v0, v1
	v_cvt_pk_f16_f32 v75, v2, v3
	v_cvt_pk_f16_f32 v76, v4, v5
	v_cvt_pk_f16_f32 v77, v6, v7
	v_cvt_f32_f16_e32 v66, v74
	v_cvt_f32_f16_sdwa v67, v74 dst_sel:DWORD dst_unused:UNUSED_PAD src0_sel:WORD_1
	v_cvt_f32_f16_e32 v68, v75
	v_cvt_f32_f16_sdwa v69, v75 dst_sel:DWORD dst_unused:UNUSED_PAD src0_sel:WORD_1
	v_cvt_f32_f16_e32 v70, v76
	v_cvt_f32_f16_sdwa v71, v76 dst_sel:DWORD dst_unused:UNUSED_PAD src0_sel:WORD_1
	v_cvt_f32_f16_e32 v72, v77
	v_cvt_f32_f16_sdwa v73, v77 dst_sel:DWORD dst_unused:UNUSED_PAD src0_sel:WORD_1
	v_pk_add_f32 v[0:1], v[0:1], v[66:67] neg_lo:[0,1] neg_hi:[0,1]
	v_pk_add_f32 v[2:3], v[2:3], v[68:69] neg_lo:[0,1] neg_hi:[0,1]
	v_pk_add_f32 v[4:5], v[4:5], v[70:71] neg_lo:[0,1] neg_hi:[0,1]
	v_pk_add_f32 v[6:7], v[6:7], v[72:73] neg_lo:[0,1] neg_hi:[0,1]
	s_nop 0
	v_cvt_pk_f16_f32 v78, v0, v1
	v_cvt_pk_f16_f32 v79, v2, v3
	v_cvt_pk_f16_f32 v80, v4, v5
	v_cvt_pk_f16_f32 v81, v6, v7
	global_store_dwordx4 v[88:89], v[74:77], off offset:0
	s_waitcnt vmcnt(33)
; DI f4 mfma16(h8 a, h8 b, f4 c) { return __builtin_amdgcn_mfma_f32_16x16x32_f16(a, b, c, 0, 0, 0); }
; DI void row2_phase(const Params& P, int l, int r_begin, char* smem) {
;     ...
; #pragma unroll 4
;     for (int kk = 0; kk < 32; kk++) {
;       const int k0 = kk * 32;
;       float x[8], g[8], s1[8], s0[8];
;       *(float4*)&x[0] = *(const float4*)(xm + k0); *(float4*)&x[4] = *(const float4*)(xm + k0 + 4);
;       *(float4*)&g[0] = *(const float4*)(gam + fq * 8 + k0); *(float4*)&g[4] = *(const float4*)(gam + fq * 8 + k0 + 4);
;       *(float4*)&s1[0] = *(const float4*)(sc + k0); *(float4*)&s1[4] = *(const float4*)(sc + k0 + 4);
;       *(float4*)&s0[0] = *(const float4*)(sh + k0); *(float4*)&s0[4] = *(const float4*)(sh + k0 + 4);
;       h8 hi, lo;
; #pragma unroll
;       for (int i = 0; i < 8; i++) {
;         float v = x[i] * rstd * g[i] * (1.f + s1[i]) + s0[i];
;         hi[i] = (half_t)v; lo[i] = (half_t)(v - (float)hi[i]);
;       }
;       *(h8*)(hxo + k0) = hi;
; #pragma unroll
;       for (int n3 = 0; n3 < 3; n3++) {
;         h8 bh = *(const h8*)(Whi + (size_t)(n3 * 16 + fr) * 1024 + k0 + fq * 8);
;         h8 bl = *(const h8*)(Wlo + (size_t)(n3 * 16 + fr) * 1024 + k0 + fq * 8);
;         acc[n3] = mfma16(hi, bh, acc[n3]); acc[n3] = mfma16(lo, bh, acc[n3]); acc[n3] = mfma16(hi, bl, acc[n3]);
;       }
;     }
	v_mfma_f32_16x16x32_f16 a[8:11], v[74:77], a[80:83], a[8:11]
	v_mfma_f32_16x16x32_f16 a[8:11], v[78:81], a[80:83], a[8:11]
	v_mfma_f32_16x16x32_f16 a[8:11], v[74:77], a[84:87], a[8:11]
	v_mfma_f32_16x16x32_f16 a[4:7], v[74:77], a[88:91], a[4:7]
	v_mfma_f32_16x16x32_f16 a[4:7], v[78:81], a[88:91], a[4:7]
	v_mfma_f32_16x16x32_f16 a[4:7], v[74:77], a[92:95], a[4:7]
	v_mfma_f32_16x16x32_f16 a[0:3], v[74:77], a[96:99], a[0:3]
	v_mfma_f32_16x16x32_f16 a[0:3], v[78:81], a[96:99], a[0:3]
	v_mfma_f32_16x16x32_f16 a[0:3], v[74:77], a[100:103], a[0:3]
	global_load_dwordx4 a[80:83], v[90:91], off offset:384
	global_load_dwordx4 a[84:87], v[92:93], off offset:384
	global_load_dwordx4 a[88:91], v[94:95], off offset:384
	global_load_dwordx4 a[92:95], v[96:97], off offset:384
	global_load_dwordx4 a[96:99], v[98:99], off offset:384
	global_load_dwordx4 a[100:103], v[100:101], off offset:384
	s_waitcnt vmcnt(39)
	v_accvgpr_read_b32 v0, a24
	v_accvgpr_read_b32 v1, a25
	v_accvgpr_read_b32 v2, a26
	v_accvgpr_read_b32 v3, a27
	v_accvgpr_read_b32 v4, a28
	v_accvgpr_read_b32 v5, a29
	v_accvgpr_read_b32 v6, a30
	v_accvgpr_read_b32 v7, a31
	global_load_dwordx4 a[24:27], v[22:23], off offset:1152
	global_load_dwordx4 a[28:31], v[22:23], off offset:1168
	v_pk_mul_f32 v[0:1], v[28:29], v[0:1]
	v_pk_mul_f32 v[2:3], v[28:29], v[2:3]
	v_pk_mul_f32 v[4:5], v[28:29], v[4:5]
	v_pk_mul_f32 v[6:7], v[28:29], v[6:7]
	s_waitcnt lgkmcnt(0)
	v_pk_mul_f32 v[0:1], v[0:1], v[32:33]
	v_pk_mul_f32 v[2:3], v[2:3], v[34:35]
	v_pk_mul_f32 v[4:5], v[4:5], v[36:37]
	v_pk_mul_f32 v[6:7], v[6:7], v[38:39]
	v_pk_add_f32 v[40:41], v[40:41], 1.0 op_sel_hi:[1,0]
	v_pk_add_f32 v[42:43], v[42:43], 1.0 op_sel_hi:[1,0]
	v_pk_add_f32 v[44:45], v[44:45], 1.0 op_sel_hi:[1,0]
	v_pk_add_f32 v[46:47], v[46:47], 1.0 op_sel_hi:[1,0]
	v_pk_fma_f32 v[0:1], v[0:1], v[40:41], v[58:59]
	v_pk_fma_f32 v[2:3], v[2:3], v[42:43], v[60:61]
	v_pk_fma_f32 v[4:5], v[4:5], v[44:45], v[62:63]
	v_pk_fma_f32 v[6:7], v[6:7], v[46:47], v[64:65]
	ds_read_b128 v[32:35], v102 offset:256
	ds_read_b128 v[36:39], v102 offset:272
	ds_read_b128 v[40:43], v102 offset:4352
	ds_read_b128 v[44:47], v102 offset:4368
	ds_read_b128 v[58:61], v102 offset:8448
	ds_read_b128 v[62:65], v102 offset:8464
	v_cvt_pk_f16_f32 v74, v0, v1
	v_cvt_pk_f16_f32 v75, v2, v3
	v_cvt_pk_f16_f32 v76, v4, v5
	v_cvt_pk_f16_f32 v77, v6, v7
	v_cvt_f32_f16_e32 v66, v74
	v_cvt_f32_f16_sdwa v67, v74 dst_sel:DWORD dst_unused:UNUSED_PAD src0_sel:WORD_1
	v_cvt_f32_f16_e32 v68, v75
	v_cvt_f32_f16_sdwa v69, v75 dst_sel:DWORD dst_unused:UNUSED_PAD src0_sel:WORD_1
	v_cvt_f32_f16_e32 v70, v76
	v_cvt_f32_f16_sdwa v71, v76 dst_sel:DWORD dst_unused:UNUSED_PAD src0_sel:WORD_1
	v_cvt_f32_f16_e32 v72, v77
	v_cvt_f32_f16_sdwa v73, v77 dst_sel:DWORD dst_unused:UNUSED_PAD src0_sel:WORD_1
	v_pk_add_f32 v[0:1], v[0:1], v[66:67] neg_lo:[0,1] neg_hi:[0,1]
	v_pk_add_f32 v[2:3], v[2:3], v[68:69] neg_lo:[0,1] neg_hi:[0,1]
	v_pk_add_f32 v[4:5], v[4:5], v[70:71] neg_lo:[0,1] neg_hi:[0,1]
	v_pk_add_f32 v[6:7], v[6:7], v[72:73] neg_lo:[0,1] neg_hi:[0,1]
	s_nop 0
	v_cvt_pk_f16_f32 v78, v0, v1
	v_cvt_pk_f16_f32 v79, v2, v3
	v_cvt_pk_f16_f32 v80, v4, v5
	v_cvt_pk_f16_f32 v81, v6, v7
	global_store_dwordx4 v[88:89], v[74:77], off offset:64
	s_waitcnt vmcnt(36)
	v_mfma_f32_16x16x32_f16 a[8:11], v[74:77], a[104:107], a[8:11]
	v_mfma_f32_16x16x32_f16 a[8:11], v[78:81], a[104:107], a[8:11]
	v_mfma_f32_16x16x32_f16 a[8:11], v[74:77], a[108:111], a[8:11]
	v_mfma_f32_16x16x32_f16 a[4:7], v[74:77], a[112:115], a[4:7]
	v_mfma_f32_16x16x32_f16 a[4:7], v[78:81], a[112:115], a[4:7]
	v_mfma_f32_16x16x32_f16 a[4:7], v[74:77], a[116:119], a[4:7]
	v_mfma_f32_16x16x32_f16 a[0:3], v[74:77], a[120:123], a[0:3]
	v_mfma_f32_16x16x32_f16 a[0:3], v[78:81], a[120:123], a[0:3]
	v_mfma_f32_16x16x32_f16 a[0:3], v[74:77], a[124:127], a[0:3]
	global_load_dwordx4 a[104:107], v[90:91], off offset:448
	global_load_dwordx4 a[108:111], v[92:93], off offset:448
	global_load_dwordx4 a[112:115], v[94:95], off offset:448
	global_load_dwordx4 a[116:119], v[96:97], off offset:448
	global_load_dwordx4 a[120:123], v[98:99], off offset:448
	global_load_dwordx4 a[124:127], v[100:101], off offset:448
	s_waitcnt vmcnt(42)
	v_accvgpr_read_b32 v0, a32
	v_accvgpr_read_b32 v1, a33
	v_accvgpr_read_b32 v2, a34
	v_accvgpr_read_b32 v3, a35
	v_accvgpr_read_b32 v4, a36
	v_accvgpr_read_b32 v5, a37
	v_accvgpr_read_b32 v6, a38
	v_accvgpr_read_b32 v7, a39
	global_load_dwordx4 a[32:35], v[22:23], off offset:1280
	global_load_dwordx4 a[36:39], v[22:23], off offset:1296
	v_pk_mul_f32 v[0:1], v[28:29], v[0:1]
	v_pk_mul_f32 v[2:3], v[28:29], v[2:3]
	v_pk_mul_f32 v[4:5], v[28:29], v[4:5]
	v_pk_mul_f32 v[6:7], v[28:29], v[6:7]
	s_waitcnt lgkmcnt(0)
	v_pk_mul_f32 v[0:1], v[0:1], v[32:33]
	v_pk_mul_f32 v[2:3], v[2:3], v[34:35]
	v_pk_mul_f32 v[4:5], v[4:5], v[36:37]
	v_pk_mul_f32 v[6:7], v[6:7], v[38:39]
	v_pk_add_f32 v[40:41], v[40:41], 1.0 op_sel_hi:[1,0]
	v_pk_add_f32 v[42:43], v[42:43], 1.0 op_sel_hi:[1,0]
	v_pk_add_f32 v[44:45], v[44:45], 1.0 op_sel_hi:[1,0]
	v_pk_add_f32 v[46:47], v[46:47], 1.0 op_sel_hi:[1,0]
	v_pk_fma_f32 v[0:1], v[0:1], v[40:41], v[58:59]
	v_pk_fma_f32 v[2:3], v[2:3], v[42:43], v[60:61]
	v_pk_fma_f32 v[4:5], v[4:5], v[44:45], v[62:63]
	v_pk_fma_f32 v[6:7], v[6:7], v[46:47], v[64:65]
	ds_read_b128 v[32:35], v102 offset:384
	ds_read_b128 v[36:39], v102 offset:400
	ds_read_b128 v[40:43], v102 offset:4480
	ds_read_b128 v[44:47], v102 offset:4496
	ds_read_b128 v[58:61], v102 offset:8576
	ds_read_b128 v[62:65], v102 offset:8592
	v_cvt_pk_f16_f32 v74, v0, v1
	v_cvt_pk_f16_f32 v75, v2, v3
	v_cvt_pk_f16_f32 v76, v4, v5
	v_cvt_pk_f16_f32 v77, v6, v7
	v_cvt_f32_f16_e32 v66, v74
	v_cvt_f32_f16_sdwa v67, v74 dst_sel:DWORD dst_unused:UNUSED_PAD src0_sel:WORD_1
	v_cvt_f32_f16_e32 v68, v75
	v_cvt_f32_f16_sdwa v69, v75 dst_sel:DWORD dst_unused:UNUSED_PAD src0_sel:WORD_1
	v_cvt_f32_f16_e32 v70, v76
	v_cvt_f32_f16_sdwa v71, v76 dst_sel:DWORD dst_unused:UNUSED_PAD src0_sel:WORD_1
	v_cvt_f32_f16_e32 v72, v77
	v_cvt_f32_f16_sdwa v73, v77 dst_sel:DWORD dst_unused:UNUSED_PAD src0_sel:WORD_1
	v_pk_add_f32 v[0:1], v[0:1], v[66:67] neg_lo:[0,1] neg_hi:[0,1]
	v_pk_add_f32 v[2:3], v[2:3], v[68:69] neg_lo:[0,1] neg_hi:[0,1]
	v_pk_add_f32 v[4:5], v[4:5], v[70:71] neg_lo:[0,1] neg_hi:[0,1]
	v_pk_add_f32 v[6:7], v[6:7], v[72:73] neg_lo:[0,1] neg_hi:[0,1]
	s_nop 0
	v_cvt_pk_f16_f32 v78, v0, v1
	v_cvt_pk_f16_f32 v79, v2, v3
	v_cvt_pk_f16_f32 v80, v4, v5
	v_cvt_pk_f16_f32 v81, v6, v7
	global_store_dwordx4 v[88:89], v[74:77], off offset:128
	s_waitcnt vmcnt(39)
; DI f4 mfma16(h8 a, h8 b, f4 c) { return __builtin_amdgcn_mfma_f32_16x16x32_f16(a, b, c, 0, 0, 0); }
; DI void row2_phase(const Params& P, int l, int r_begin, char* smem) {
;     ...
; #pragma unroll 4
;     for (int kk = 0; kk < 32; kk++) {
;       const int k0 = kk * 32;
;       float x[8], g[8], s1[8], s0[8];
;       *(float4*)&x[0] = *(const float4*)(xm + k0); *(float4*)&x[4] = *(const float4*)(xm + k0 + 4);
;       *(float4*)&g[0] = *(const float4*)(gam + fq * 8 + k0); *(float4*)&g[4] = *(const float4*)(gam + fq * 8 + k0 + 4);
;       *(float4*)&s1[0] = *(const float4*)(sc + k0); *(float4*)&s1[4] = *(const float4*)(sc + k0 + 4);
;       *(float4*)&s0[0] = *(const float4*)(sh + k0); *(float4*)&s0[4] = *(const float4*)(sh + k0 + 4);
;       h8 hi, lo;
; #pragma unroll
;       for (int i = 0; i < 8; i++) {
;         float v = x[i] * rstd * g[i] * (1.f + s1[i]) + s0[i];
;         hi[i] = (half_t)v; lo[i] = (half_t)(v - (float)hi[i]);
;       }
;       *(h8*)(hxo + k0) = hi;
; #pragma unroll
;       for (int n3 = 0; n3 < 3; n3++) {
;         h8 bh = *(const h8*)(Whi + (size_t)(n3 * 16 + fr) * 1024 + k0 + fq * 8);
;         h8 bl = *(const h8*)(Wlo + (size_t)(n3 * 16 + fr) * 1024 + k0 + fq * 8);
;         acc[n3] = mfma16(hi, bh, acc[n3]); acc[n3] = mfma16(lo, bh, acc[n3]); acc[n3] = mfma16(hi, bl, acc[n3]);
;       }
;     }
	v_mfma_f32_16x16x32_f16 a[8:11], v[74:77], a[128:131], a[8:11]
	v_mfma_f32_16x16x32_f16 a[8:11], v[78:81], a[128:131], a[8:11]
	v_mfma_f32_16x16x32_f16 a[8:11], v[74:77], a[132:135], a[8:11]
	v_mfma_f32_16x16x32_f16 a[4:7], v[74:77], a[136:139], a[4:7]
	v_mfma_f32_16x16x32_f16 a[4:7], v[78:81], a[136:139], a[4:7]
	v_mfma_f32_16x16x32_f16 a[4:7], v[74:77], a[140:143], a[4:7]
	v_mfma_f32_16x16x32_f16 a[0:3], v[74:77], a[144:147], a[0:3]
	v_mfma_f32_16x16x32_f16 a[0:3], v[78:81], a[144:147], a[0:3]
	v_mfma_f32_16x16x32_f16 a[0:3], v[74:77], a[148:151], a[0:3]
	global_load_dwordx4 a[128:131], v[90:91], off offset:512
	global_load_dwordx4 a[132:135], v[92:93], off offset:512
	global_load_dwordx4 a[136:139], v[94:95], off offset:512
	global_load_dwordx4 a[140:143], v[96:97], off offset:512
	global_load_dwordx4 a[144:147], v[98:99], off offset:512
	global_load_dwordx4 a[148:151], v[100:101], off offset:512
	s_waitcnt vmcnt(45)
	v_accvgpr_read_b32 v0, a40
	v_accvgpr_read_b32 v1, a41
	v_accvgpr_read_b32 v2, a42
	v_accvgpr_read_b32 v3, a43
	v_accvgpr_read_b32 v4, a44
	v_accvgpr_read_b32 v5, a45
	v_accvgpr_read_b32 v6, a46
	v_accvgpr_read_b32 v7, a47
	global_load_dwordx4 a[40:43], v[22:23], off offset:1408
	global_load_dwordx4 a[44:47], v[22:23], off offset:1424
	v_pk_mul_f32 v[0:1], v[28:29], v[0:1]
	v_pk_mul_f32 v[2:3], v[28:29], v[2:3]
	v_pk_mul_f32 v[4:5], v[28:29], v[4:5]
	v_pk_mul_f32 v[6:7], v[28:29], v[6:7]
	s_waitcnt lgkmcnt(0)
	v_pk_mul_f32 v[0:1], v[0:1], v[32:33]
	v_pk_mul_f32 v[2:3], v[2:3], v[34:35]
	v_pk_mul_f32 v[4:5], v[4:5], v[36:37]
	v_pk_mul_f32 v[6:7], v[6:7], v[38:39]
	v_pk_add_f32 v[40:41], v[40:41], 1.0 op_sel_hi:[1,0]
	v_pk_add_f32 v[42:43], v[42:43], 1.0 op_sel_hi:[1,0]
	v_pk_add_f32 v[44:45], v[44:45], 1.0 op_sel_hi:[1,0]
	v_pk_add_f32 v[46:47], v[46:47], 1.0 op_sel_hi:[1,0]
	v_pk_fma_f32 v[0:1], v[0:1], v[40:41], v[58:59]
	v_pk_fma_f32 v[2:3], v[2:3], v[42:43], v[60:61]
	v_pk_fma_f32 v[4:5], v[4:5], v[44:45], v[62:63]
	v_pk_fma_f32 v[6:7], v[6:7], v[46:47], v[64:65]
	ds_read_b128 v[32:35], v102 offset:512
	ds_read_b128 v[36:39], v102 offset:528
	ds_read_b128 v[40:43], v102 offset:4608
	ds_read_b128 v[44:47], v102 offset:4624
	ds_read_b128 v[58:61], v102 offset:8704
	ds_read_b128 v[62:65], v102 offset:8720
	v_cvt_pk_f16_f32 v74, v0, v1
	v_cvt_pk_f16_f32 v75, v2, v3
	v_cvt_pk_f16_f32 v76, v4, v5
	v_cvt_pk_f16_f32 v77, v6, v7
	v_cvt_f32_f16_e32 v66, v74
	v_cvt_f32_f16_sdwa v67, v74 dst_sel:DWORD dst_unused:UNUSED_PAD src0_sel:WORD_1
	v_cvt_f32_f16_e32 v68, v75
	v_cvt_f32_f16_sdwa v69, v75 dst_sel:DWORD dst_unused:UNUSED_PAD src0_sel:WORD_1
	v_cvt_f32_f16_e32 v70, v76
	v_cvt_f32_f16_sdwa v71, v76 dst_sel:DWORD dst_unused:UNUSED_PAD src0_sel:WORD_1
	v_cvt_f32_f16_e32 v72, v77
	v_cvt_f32_f16_sdwa v73, v77 dst_sel:DWORD dst_unused:UNUSED_PAD src0_sel:WORD_1
	v_pk_add_f32 v[0:1], v[0:1], v[66:67] neg_lo:[0,1] neg_hi:[0,1]
	v_pk_add_f32 v[2:3], v[2:3], v[68:69] neg_lo:[0,1] neg_hi:[0,1]
	v_pk_add_f32 v[4:5], v[4:5], v[70:71] neg_lo:[0,1] neg_hi:[0,1]
	v_pk_add_f32 v[6:7], v[6:7], v[72:73] neg_lo:[0,1] neg_hi:[0,1]
	s_nop 0
	v_cvt_pk_f16_f32 v78, v0, v1
	v_cvt_pk_f16_f32 v79, v2, v3
	v_cvt_pk_f16_f32 v80, v4, v5
	v_cvt_pk_f16_f32 v81, v6, v7
	global_store_dwordx4 v[88:89], v[74:77], off offset:192
	s_waitcnt vmcnt(42)
	v_mfma_f32_16x16x32_f16 a[8:11], v[74:77], a[152:155], a[8:11]
	v_mfma_f32_16x16x32_f16 a[8:11], v[78:81], a[152:155], a[8:11]
	v_mfma_f32_16x16x32_f16 a[8:11], v[74:77], a[156:159], a[8:11]
	v_mfma_f32_16x16x32_f16 a[4:7], v[74:77], a[160:163], a[4:7]
	v_mfma_f32_16x16x32_f16 a[4:7], v[78:81], a[160:163], a[4:7]
	v_mfma_f32_16x16x32_f16 a[4:7], v[74:77], a[164:167], a[4:7]
	v_mfma_f32_16x16x32_f16 a[0:3], v[74:77], a[168:171], a[0:3]
	v_mfma_f32_16x16x32_f16 a[0:3], v[78:81], a[168:171], a[0:3]
	v_mfma_f32_16x16x32_f16 a[0:3], v[74:77], a[172:175], a[0:3]
	global_load_dwordx4 a[152:155], v[90:91], off offset:576
	global_load_dwordx4 a[156:159], v[92:93], off offset:576
	global_load_dwordx4 a[160:163], v[94:95], off offset:576
	global_load_dwordx4 a[164:167], v[96:97], off offset:576
	global_load_dwordx4 a[168:171], v[98:99], off offset:576
	global_load_dwordx4 a[172:175], v[100:101], off offset:576
	s_waitcnt vmcnt(48)
	v_accvgpr_read_b32 v0, a48
	v_accvgpr_read_b32 v1, a49
	v_accvgpr_read_b32 v2, a50
	v_accvgpr_read_b32 v3, a51
	v_accvgpr_read_b32 v4, a52
	v_accvgpr_read_b32 v5, a53
	v_accvgpr_read_b32 v6, a54
	v_accvgpr_read_b32 v7, a55
	global_load_dwordx4 a[48:51], v[22:23], off offset:1536
	global_load_dwordx4 a[52:55], v[22:23], off offset:1552
	v_pk_mul_f32 v[0:1], v[28:29], v[0:1]
	v_pk_mul_f32 v[2:3], v[28:29], v[2:3]
	v_pk_mul_f32 v[4:5], v[28:29], v[4:5]
	v_pk_mul_f32 v[6:7], v[28:29], v[6:7]
	s_waitcnt lgkmcnt(0)
; DI f4 mfma16(h8 a, h8 b, f4 c) { return __builtin_amdgcn_mfma_f32_16x16x32_f16(a, b, c, 0, 0, 0); }
; DI void row2_phase(const Params& P, int l, int r_begin, char* smem) {
;     ...
; #pragma unroll 4
;     for (int kk = 0; kk < 32; kk++) {
;       const int k0 = kk * 32;
;       float x[8], g[8], s1[8], s0[8];
;       *(float4*)&x[0] = *(const float4*)(xm + k0); *(float4*)&x[4] = *(const float4*)(xm + k0 + 4);
;       *(float4*)&g[0] = *(const float4*)(gam + fq * 8 + k0); *(float4*)&g[4] = *(const float4*)(gam + fq * 8 + k0 + 4);
;       *(float4*)&s1[0] = *(const float4*)(sc + k0); *(float4*)&s1[4] = *(const float4*)(sc + k0 + 4);
;       *(float4*)&s0[0] = *(const float4*)(sh + k0); *(float4*)&s0[4] = *(const float4*)(sh + k0 + 4);
;       h8 hi, lo;
; #pragma unroll
;       for (int i = 0; i < 8; i++) {
;         float v = x[i] * rstd * g[i] * (1.f + s1[i]) + s0[i];
;         hi[i] = (half_t)v; lo[i] = (half_t)(v - (float)hi[i]);
;       }
;       *(h8*)(hxo + k0) = hi;
; #pragma unroll
;       for (int n3 = 0; n3 < 3; n3++) {
;         h8 bh = *(const h8*)(Whi + (size_t)(n3 * 16 + fr) * 1024 + k0 + fq * 8);
;         h8 bl = *(const h8*)(Wlo + (size_t)(n3 * 16 + fr) * 1024 + k0 + fq * 8);
;         acc[n3] = mfma16(hi, bh, acc[n3]); acc[n3] = mfma16(lo, bh, acc[n3]); acc[n3] = mfma16(hi, bl, acc[n3]);
;       }
;     }
	v_pk_mul_f32 v[0:1], v[0:1], v[32:33]
	v_pk_mul_f32 v[2:3], v[2:3], v[34:35]
	v_pk_mul_f32 v[4:5], v[4:5], v[36:37]
	v_pk_mul_f32 v[6:7], v[6:7], v[38:39]
	v_pk_add_f32 v[40:41], v[40:41], 1.0 op_sel_hi:[1,0]
	v_pk_add_f32 v[42:43], v[42:43], 1.0 op_sel_hi:[1,0]
	v_pk_add_f32 v[44:45], v[44:45], 1.0 op_sel_hi:[1,0]
	v_pk_add_f32 v[46:47], v[46:47], 1.0 op_sel_hi:[1,0]
	v_pk_fma_f32 v[0:1], v[0:1], v[40:41], v[58:59]
	v_pk_fma_f32 v[2:3], v[2:3], v[42:43], v[60:61]
	v_pk_fma_f32 v[4:5], v[4:5], v[44:45], v[62:63]
	v_pk_fma_f32 v[6:7], v[6:7], v[46:47], v[64:65]
	ds_read_b128 v[32:35], v102 offset:640
	ds_read_b128 v[36:39], v102 offset:656
	ds_read_b128 v[40:43], v102 offset:4736
	ds_read_b128 v[44:47], v102 offset:4752
	ds_read_b128 v[58:61], v102 offset:8832
	ds_read_b128 v[62:65], v102 offset:8848
	v_cvt_pk_f16_f32 v74, v0, v1
	v_cvt_pk_f16_f32 v75, v2, v3
	v_cvt_pk_f16_f32 v76, v4, v5
	v_cvt_pk_f16_f32 v77, v6, v7
	v_cvt_f32_f16_e32 v66, v74
	v_cvt_f32_f16_sdwa v67, v74 dst_sel:DWORD dst_unused:UNUSED_PAD src0_sel:WORD_1
	v_cvt_f32_f16_e32 v68, v75
	v_cvt_f32_f16_sdwa v69, v75 dst_sel:DWORD dst_unused:UNUSED_PAD src0_sel:WORD_1
	v_cvt_f32_f16_e32 v70, v76
	v_cvt_f32_f16_sdwa v71, v76 dst_sel:DWORD dst_unused:UNUSED_PAD src0_sel:WORD_1
	v_cvt_f32_f16_e32 v72, v77
	v_cvt_f32_f16_sdwa v73, v77 dst_sel:DWORD dst_unused:UNUSED_PAD src0_sel:WORD_1
	v_pk_add_f32 v[0:1], v[0:1], v[66:67] neg_lo:[0,1] neg_hi:[0,1]
	v_pk_add_f32 v[2:3], v[2:3], v[68:69] neg_lo:[0,1] neg_hi:[0,1]
	v_pk_add_f32 v[4:5], v[4:5], v[70:71] neg_lo:[0,1] neg_hi:[0,1]
	v_pk_add_f32 v[6:7], v[6:7], v[72:73] neg_lo:[0,1] neg_hi:[0,1]
	s_nop 0
	v_cvt_pk_f16_f32 v78, v0, v1
	v_cvt_pk_f16_f32 v79, v2, v3
	v_cvt_pk_f16_f32 v80, v4, v5
	v_cvt_pk_f16_f32 v81, v6, v7
	global_store_dwordx4 v[88:89], v[74:77], off offset:256
	s_waitcnt vmcnt(45)
	v_mfma_f32_16x16x32_f16 a[8:11], v[74:77], a[204:207], a[8:11]
	v_mfma_f32_16x16x32_f16 a[8:11], v[78:81], a[204:207], a[8:11]
	v_mfma_f32_16x16x32_f16 a[8:11], v[74:77], a[208:211], a[8:11]
	v_mfma_f32_16x16x32_f16 a[4:7], v[74:77], a[212:215], a[4:7]
	v_mfma_f32_16x16x32_f16 a[4:7], v[78:81], a[212:215], a[4:7]
	v_mfma_f32_16x16x32_f16 a[4:7], v[74:77], a[216:219], a[4:7]
	v_mfma_f32_16x16x32_f16 a[0:3], v[74:77], a[220:223], a[0:3]
	v_mfma_f32_16x16x32_f16 a[0:3], v[78:81], a[220:223], a[0:3]
	v_mfma_f32_16x16x32_f16 a[0:3], v[74:77], a[224:227], a[0:3]
	global_load_dwordx4 a[204:207], v[90:91], off offset:640
	global_load_dwordx4 a[208:211], v[92:93], off offset:640
	global_load_dwordx4 a[212:215], v[94:95], off offset:640
	global_load_dwordx4 a[216:219], v[96:97], off offset:640
	global_load_dwordx4 a[220:223], v[98:99], off offset:640
	global_load_dwordx4 a[224:227], v[100:101], off offset:640
	s_waitcnt vmcnt(51)
	v_accvgpr_read_b32 v0, a56
	v_accvgpr_read_b32 v1, a57
	v_accvgpr_read_b32 v2, a58
	v_accvgpr_read_b32 v3, a59
	v_accvgpr_read_b32 v4, a60
	v_accvgpr_read_b32 v5, a61
	v_accvgpr_read_b32 v6, a62
	v_accvgpr_read_b32 v7, a63
	global_load_dwordx4 a[56:59], v[22:23], off offset:1664
	global_load_dwordx4 a[60:63], v[22:23], off offset:1680
	v_pk_mul_f32 v[0:1], v[28:29], v[0:1]
	v_pk_mul_f32 v[2:3], v[28:29], v[2:3]
	v_pk_mul_f32 v[4:5], v[28:29], v[4:5]
	v_pk_mul_f32 v[6:7], v[28:29], v[6:7]
	s_waitcnt lgkmcnt(0)
	v_pk_mul_f32 v[0:1], v[0:1], v[32:33]
	v_pk_mul_f32 v[2:3], v[2:3], v[34:35]
	v_pk_mul_f32 v[4:5], v[4:5], v[36:37]
	v_pk_mul_f32 v[6:7], v[6:7], v[38:39]
	v_pk_add_f32 v[40:41], v[40:41], 1.0 op_sel_hi:[1,0]
	v_pk_add_f32 v[42:43], v[42:43], 1.0 op_sel_hi:[1,0]
	v_pk_add_f32 v[44:45], v[44:45], 1.0 op_sel_hi:[1,0]
	v_pk_add_f32 v[46:47], v[46:47], 1.0 op_sel_hi:[1,0]
	v_pk_fma_f32 v[0:1], v[0:1], v[40:41], v[58:59]
	v_pk_fma_f32 v[2:3], v[2:3], v[42:43], v[60:61]
	v_pk_fma_f32 v[4:5], v[4:5], v[44:45], v[62:63]
	v_pk_fma_f32 v[6:7], v[6:7], v[46:47], v[64:65]
	ds_read_b128 v[32:35], v102 offset:768
	ds_read_b128 v[36:39], v102 offset:784
	ds_read_b128 v[40:43], v102 offset:4864
	ds_read_b128 v[44:47], v102 offset:4880
	ds_read_b128 v[58:61], v102 offset:8960
	ds_read_b128 v[62:65], v102 offset:8976
	v_cvt_pk_f16_f32 v74, v0, v1
	v_cvt_pk_f16_f32 v75, v2, v3
	v_cvt_pk_f16_f32 v76, v4, v5
	v_cvt_pk_f16_f32 v77, v6, v7
	v_cvt_f32_f16_e32 v66, v74
	v_cvt_f32_f16_sdwa v67, v74 dst_sel:DWORD dst_unused:UNUSED_PAD src0_sel:WORD_1
	v_cvt_f32_f16_e32 v68, v75
	v_cvt_f32_f16_sdwa v69, v75 dst_sel:DWORD dst_unused:UNUSED_PAD src0_sel:WORD_1
	v_cvt_f32_f16_e32 v70, v76
	v_cvt_f32_f16_sdwa v71, v76 dst_sel:DWORD dst_unused:UNUSED_PAD src0_sel:WORD_1
	v_cvt_f32_f16_e32 v72, v77
	v_cvt_f32_f16_sdwa v73, v77 dst_sel:DWORD dst_unused:UNUSED_PAD src0_sel:WORD_1
	v_pk_add_f32 v[0:1], v[0:1], v[66:67] neg_lo:[0,1] neg_hi:[0,1]
	v_pk_add_f32 v[2:3], v[2:3], v[68:69] neg_lo:[0,1] neg_hi:[0,1]
	v_pk_add_f32 v[4:5], v[4:5], v[70:71] neg_lo:[0,1] neg_hi:[0,1]
	v_pk_add_f32 v[6:7], v[6:7], v[72:73] neg_lo:[0,1] neg_hi:[0,1]
	s_nop 0
	v_cvt_pk_f16_f32 v78, v0, v1
	v_cvt_pk_f16_f32 v79, v2, v3
	v_cvt_pk_f16_f32 v80, v4, v5
	v_cvt_pk_f16_f32 v81, v6, v7
	global_store_dwordx4 v[88:89], v[74:77], off offset:320
	s_waitcnt vmcnt(48)
	v_mfma_f32_16x16x32_f16 a[8:11], v[74:77], a[228:231], a[8:11]
	v_mfma_f32_16x16x32_f16 a[8:11], v[78:81], a[228:231], a[8:11]
	v_mfma_f32_16x16x32_f16 a[8:11], v[74:77], a[232:235], a[8:11]
	v_mfma_f32_16x16x32_f16 a[4:7], v[74:77], a[236:239], a[4:7]
	v_mfma_f32_16x16x32_f16 a[4:7], v[78:81], a[236:239], a[4:7]
	v_mfma_f32_16x16x32_f16 a[4:7], v[74:77], a[240:243], a[4:7]
	v_mfma_f32_16x16x32_f16 a[0:3], v[74:77], a[244:247], a[0:3]
	v_mfma_f32_16x16x32_f16 a[0:3], v[78:81], a[244:247], a[0:3]
	v_mfma_f32_16x16x32_f16 a[0:3], v[74:77], a[248:251], a[0:3]
	global_load_dwordx4 a[228:231], v[90:91], off offset:704
	global_load_dwordx4 a[232:235], v[92:93], off offset:704
	global_load_dwordx4 a[236:239], v[94:95], off offset:704
	global_load_dwordx4 a[240:243], v[96:97], off offset:704
	global_load_dwordx4 a[244:247], v[98:99], off offset:704
	global_load_dwordx4 a[248:251], v[100:101], off offset:704
	s_waitcnt vmcnt(54)
; DI f4 mfma16(h8 a, h8 b, f4 c) { return __builtin_amdgcn_mfma_f32_16x16x32_f16(a, b, c, 0, 0, 0); }
; DI void row2_phase(const Params& P, int l, int r_begin, char* smem) {
;     ...
; #pragma unroll 4
;     for (int kk = 0; kk < 32; kk++) {
;       const int k0 = kk * 32;
;       float x[8], g[8], s1[8], s0[8];
;       *(float4*)&x[0] = *(const float4*)(xm + k0); *(float4*)&x[4] = *(const float4*)(xm + k0 + 4);
;       *(float4*)&g[0] = *(const float4*)(gam + fq * 8 + k0); *(float4*)&g[4] = *(const float4*)(gam + fq * 8 + k0 + 4);
;       *(float4*)&s1[0] = *(const float4*)(sc + k0); *(float4*)&s1[4] = *(const float4*)(sc + k0 + 4);
;       *(float4*)&s0[0] = *(const float4*)(sh + k0); *(float4*)&s0[4] = *(const float4*)(sh + k0 + 4);
;       h8 hi, lo;
; #pragma unroll
;       for (int i = 0; i < 8; i++) {
;         float v = x[i] * rstd * g[i] * (1.f + s1[i]) + s0[i];
;         hi[i] = (half_t)v; lo[i] = (half_t)(v - (float)hi[i]);
;       }
;       *(h8*)(hxo + k0) = hi;
; #pragma unroll
;       for (int n3 = 0; n3 < 3; n3++) {
;         h8 bh = *(const h8*)(Whi + (size_t)(n3 * 16 + fr) * 1024 + k0 + fq * 8);
;         h8 bl = *(const h8*)(Wlo + (size_t)(n3 * 16 + fr) * 1024 + k0 + fq * 8);
;         acc[n3] = mfma16(hi, bh, acc[n3]); acc[n3] = mfma16(lo, bh, acc[n3]); acc[n3] = mfma16(hi, bl, acc[n3]);
;       }
;     }
	v_accvgpr_read_b32 v0, a64
	v_accvgpr_read_b32 v1, a65
	v_accvgpr_read_b32 v2, a66
	v_accvgpr_read_b32 v3, a67
	v_accvgpr_read_b32 v4, a68
	v_accvgpr_read_b32 v5, a69
	v_accvgpr_read_b32 v6, a70
	v_accvgpr_read_b32 v7, a71
	global_load_dwordx4 a[64:67], v[22:23], off offset:1792
	global_load_dwordx4 a[68:71], v[22:23], off offset:1808
	v_pk_mul_f32 v[0:1], v[28:29], v[0:1]
	v_pk_mul_f32 v[2:3], v[28:29], v[2:3]
	v_pk_mul_f32 v[4:5], v[28:29], v[4:5]
	v_pk_mul_f32 v[6:7], v[28:29], v[6:7]
	s_waitcnt lgkmcnt(0)
	v_pk_mul_f32 v[0:1], v[0:1], v[32:33]
	v_pk_mul_f32 v[2:3], v[2:3], v[34:35]
	v_pk_mul_f32 v[4:5], v[4:5], v[36:37]
	v_pk_mul_f32 v[6:7], v[6:7], v[38:39]
	v_pk_add_f32 v[40:41], v[40:41], 1.0 op_sel_hi:[1,0]
	v_pk_add_f32 v[42:43], v[42:43], 1.0 op_sel_hi:[1,0]
	v_pk_add_f32 v[44:45], v[44:45], 1.0 op_sel_hi:[1,0]
	v_pk_add_f32 v[46:47], v[46:47], 1.0 op_sel_hi:[1,0]
	v_pk_fma_f32 v[0:1], v[0:1], v[40:41], v[58:59]
	v_pk_fma_f32 v[2:3], v[2:3], v[42:43], v[60:61]
	v_pk_fma_f32 v[4:5], v[4:5], v[44:45], v[62:63]
	v_pk_fma_f32 v[6:7], v[6:7], v[46:47], v[64:65]
	ds_read_b128 v[32:35], v102 offset:896
	ds_read_b128 v[36:39], v102 offset:912
	ds_read_b128 v[40:43], v102 offset:4992
	ds_read_b128 v[44:47], v102 offset:5008
	ds_read_b128 v[58:61], v102 offset:9088
	ds_read_b128 v[62:65], v102 offset:9104
	v_cvt_pk_f16_f32 v74, v0, v1
	v_cvt_pk_f16_f32 v75, v2, v3
	v_cvt_pk_f16_f32 v76, v4, v5
	v_cvt_pk_f16_f32 v77, v6, v7
	v_cvt_f32_f16_e32 v66, v74
	v_cvt_f32_f16_sdwa v67, v74 dst_sel:DWORD dst_unused:UNUSED_PAD src0_sel:WORD_1
	v_cvt_f32_f16_e32 v68, v75
	v_cvt_f32_f16_sdwa v69, v75 dst_sel:DWORD dst_unused:UNUSED_PAD src0_sel:WORD_1
	v_cvt_f32_f16_e32 v70, v76
	v_cvt_f32_f16_sdwa v71, v76 dst_sel:DWORD dst_unused:UNUSED_PAD src0_sel:WORD_1
	v_cvt_f32_f16_e32 v72, v77
	v_cvt_f32_f16_sdwa v73, v77 dst_sel:DWORD dst_unused:UNUSED_PAD src0_sel:WORD_1
	v_pk_add_f32 v[0:1], v[0:1], v[66:67] neg_lo:[0,1] neg_hi:[0,1]
	v_pk_add_f32 v[2:3], v[2:3], v[68:69] neg_lo:[0,1] neg_hi:[0,1]
	v_pk_add_f32 v[4:5], v[4:5], v[70:71] neg_lo:[0,1] neg_hi:[0,1]
	v_pk_add_f32 v[6:7], v[6:7], v[72:73] neg_lo:[0,1] neg_hi:[0,1]
	s_nop 0
	v_cvt_pk_f16_f32 v78, v0, v1
	v_cvt_pk_f16_f32 v79, v2, v3
	v_cvt_pk_f16_f32 v80, v4, v5
	v_cvt_pk_f16_f32 v81, v6, v7
	global_store_dwordx4 v[88:89], v[74:77], off offset:384
	s_waitcnt vmcnt(48)
	v_mfma_f32_16x16x32_f16 a[8:11], v[74:77], a[80:83], a[8:11]
	v_mfma_f32_16x16x32_f16 a[8:11], v[78:81], a[80:83], a[8:11]
	v_mfma_f32_16x16x32_f16 a[8:11], v[74:77], a[84:87], a[8:11]
	v_mfma_f32_16x16x32_f16 a[4:7], v[74:77], a[88:91], a[4:7]
	v_mfma_f32_16x16x32_f16 a[4:7], v[78:81], a[88:91], a[4:7]
	v_mfma_f32_16x16x32_f16 a[4:7], v[74:77], a[92:95], a[4:7]
	v_mfma_f32_16x16x32_f16 a[0:3], v[74:77], a[96:99], a[0:3]
	v_mfma_f32_16x16x32_f16 a[0:3], v[78:81], a[96:99], a[0:3]
	v_mfma_f32_16x16x32_f16 a[0:3], v[74:77], a[100:103], a[0:3]
	global_load_dwordx4 a[80:83], v[90:91], off offset:768
	global_load_dwordx4 a[84:87], v[92:93], off offset:768
	global_load_dwordx4 a[88:91], v[94:95], off offset:768
	global_load_dwordx4 a[92:95], v[96:97], off offset:768
	global_load_dwordx4 a[96:99], v[98:99], off offset:768
	global_load_dwordx4 a[100:103], v[100:101], off offset:768
	s_waitcnt vmcnt(54)
	v_accvgpr_read_b32 v0, a72
	v_accvgpr_read_b32 v1, a73
	v_accvgpr_read_b32 v2, a74
	v_accvgpr_read_b32 v3, a75
	v_accvgpr_read_b32 v4, a76
	v_accvgpr_read_b32 v5, a77
	v_accvgpr_read_b32 v6, a78
	v_accvgpr_read_b32 v7, a79
	global_load_dwordx4 a[72:75], v[22:23], off offset:1920
	global_load_dwordx4 a[76:79], v[22:23], off offset:1936
	v_pk_mul_f32 v[0:1], v[28:29], v[0:1]
	v_pk_mul_f32 v[2:3], v[28:29], v[2:3]
	v_pk_mul_f32 v[4:5], v[28:29], v[4:5]
	v_pk_mul_f32 v[6:7], v[28:29], v[6:7]
	s_waitcnt lgkmcnt(0)
	v_pk_mul_f32 v[0:1], v[0:1], v[32:33]
	v_pk_mul_f32 v[2:3], v[2:3], v[34:35]
	v_pk_mul_f32 v[4:5], v[4:5], v[36:37]
	v_pk_mul_f32 v[6:7], v[6:7], v[38:39]
	v_pk_add_f32 v[40:41], v[40:41], 1.0 op_sel_hi:[1,0]
	v_pk_add_f32 v[42:43], v[42:43], 1.0 op_sel_hi:[1,0]
	v_pk_add_f32 v[44:45], v[44:45], 1.0 op_sel_hi:[1,0]
	v_pk_add_f32 v[46:47], v[46:47], 1.0 op_sel_hi:[1,0]
	v_pk_fma_f32 v[0:1], v[0:1], v[40:41], v[58:59]
	v_pk_fma_f32 v[2:3], v[2:3], v[42:43], v[60:61]
	v_pk_fma_f32 v[4:5], v[4:5], v[44:45], v[62:63]
	v_pk_fma_f32 v[6:7], v[6:7], v[46:47], v[64:65]
	ds_read_b128 v[32:35], v102 offset:1024
	ds_read_b128 v[36:39], v102 offset:1040
	ds_read_b128 v[40:43], v102 offset:5120
	ds_read_b128 v[44:47], v102 offset:5136
	ds_read_b128 v[58:61], v102 offset:9216
	ds_read_b128 v[62:65], v102 offset:9232
	v_cvt_pk_f16_f32 v74, v0, v1
	v_cvt_pk_f16_f32 v75, v2, v3
	v_cvt_pk_f16_f32 v76, v4, v5
	v_cvt_pk_f16_f32 v77, v6, v7
	v_cvt_f32_f16_e32 v66, v74
	v_cvt_f32_f16_sdwa v67, v74 dst_sel:DWORD dst_unused:UNUSED_PAD src0_sel:WORD_1
	v_cvt_f32_f16_e32 v68, v75
	v_cvt_f32_f16_sdwa v69, v75 dst_sel:DWORD dst_unused:UNUSED_PAD src0_sel:WORD_1
	v_cvt_f32_f16_e32 v70, v76
	v_cvt_f32_f16_sdwa v71, v76 dst_sel:DWORD dst_unused:UNUSED_PAD src0_sel:WORD_1
	v_cvt_f32_f16_e32 v72, v77
	v_cvt_f32_f16_sdwa v73, v77 dst_sel:DWORD dst_unused:UNUSED_PAD src0_sel:WORD_1
	v_pk_add_f32 v[0:1], v[0:1], v[66:67] neg_lo:[0,1] neg_hi:[0,1]
	v_pk_add_f32 v[2:3], v[2:3], v[68:69] neg_lo:[0,1] neg_hi:[0,1]
	v_pk_add_f32 v[4:5], v[4:5], v[70:71] neg_lo:[0,1] neg_hi:[0,1]
	v_pk_add_f32 v[6:7], v[6:7], v[72:73] neg_lo:[0,1] neg_hi:[0,1]
	s_nop 0
	v_cvt_pk_f16_f32 v78, v0, v1
	v_cvt_pk_f16_f32 v79, v2, v3
	v_cvt_pk_f16_f32 v80, v4, v5
	v_cvt_pk_f16_f32 v81, v6, v7
	global_store_dwordx4 v[88:89], v[74:77], off offset:448
	s_waitcnt vmcnt(48)
; DI f4 mfma16(h8 a, h8 b, f4 c) { return __builtin_amdgcn_mfma_f32_16x16x32_f16(a, b, c, 0, 0, 0); }
; DI void row2_phase(const Params& P, int l, int r_begin, char* smem) {
;     ...
; #pragma unroll 4
;     for (int kk = 0; kk < 32; kk++) {
;       const int k0 = kk * 32;
;       float x[8], g[8], s1[8], s0[8];
;       *(float4*)&x[0] = *(const float4*)(xm + k0); *(float4*)&x[4] = *(const float4*)(xm + k0 + 4);
;       *(float4*)&g[0] = *(const float4*)(gam + fq * 8 + k0); *(float4*)&g[4] = *(const float4*)(gam + fq * 8 + k0 + 4);
;       *(float4*)&s1[0] = *(const float4*)(sc + k0); *(float4*)&s1[4] = *(const float4*)(sc + k0 + 4);
;       *(float4*)&s0[0] = *(const float4*)(sh + k0); *(float4*)&s0[4] = *(const float4*)(sh + k0 + 4);
;       h8 hi, lo;
; #pragma unroll
;       for (int i = 0; i < 8; i++) {
;         float v = x[i] * rstd * g[i] * (1.f + s1[i]) + s0[i];
;         hi[i] = (half_t)v; lo[i] = (half_t)(v - (float)hi[i]);
;       }
;       *(h8*)(hxo + k0) = hi;
; #pragma unroll
;       for (int n3 = 0; n3 < 3; n3++) {
;         h8 bh = *(const h8*)(Whi + (size_t)(n3 * 16 + fr) * 1024 + k0 + fq * 8);
;         h8 bl = *(const h8*)(Wlo + (size_t)(n3 * 16 + fr) * 1024 + k0 + fq * 8);
;         acc[n3] = mfma16(hi, bh, acc[n3]); acc[n3] = mfma16(lo, bh, acc[n3]); acc[n3] = mfma16(hi, bl, acc[n3]);
;       }
;     }
	v_mfma_f32_16x16x32_f16 a[8:11], v[74:77], a[104:107], a[8:11]
	v_mfma_f32_16x16x32_f16 a[8:11], v[78:81], a[104:107], a[8:11]
	v_mfma_f32_16x16x32_f16 a[8:11], v[74:77], a[108:111], a[8:11]
	v_mfma_f32_16x16x32_f16 a[4:7], v[74:77], a[112:115], a[4:7]
	v_mfma_f32_16x16x32_f16 a[4:7], v[78:81], a[112:115], a[4:7]
	v_mfma_f32_16x16x32_f16 a[4:7], v[74:77], a[116:119], a[4:7]
	v_mfma_f32_16x16x32_f16 a[0:3], v[74:77], a[120:123], a[0:3]
	v_mfma_f32_16x16x32_f16 a[0:3], v[78:81], a[120:123], a[0:3]
	v_mfma_f32_16x16x32_f16 a[0:3], v[74:77], a[124:127], a[0:3]
	global_load_dwordx4 a[104:107], v[90:91], off offset:832
	global_load_dwordx4 a[108:111], v[92:93], off offset:832
	global_load_dwordx4 a[112:115], v[94:95], off offset:832
	global_load_dwordx4 a[116:119], v[96:97], off offset:832
	global_load_dwordx4 a[120:123], v[98:99], off offset:832
	global_load_dwordx4 a[124:127], v[100:101], off offset:832
	s_waitcnt vmcnt(54)
	v_accvgpr_read_b32 v0, a16
	v_accvgpr_read_b32 v1, a17
	v_accvgpr_read_b32 v2, a18
	v_accvgpr_read_b32 v3, a19
	v_accvgpr_read_b32 v4, a20
	v_accvgpr_read_b32 v5, a21
	v_accvgpr_read_b32 v6, a22
	v_accvgpr_read_b32 v7, a23
	global_load_dwordx4 a[16:19], v[22:23], off offset:2048
	global_load_dwordx4 a[20:23], v[22:23], off offset:2064
	v_pk_mul_f32 v[0:1], v[28:29], v[0:1]
	v_pk_mul_f32 v[2:3], v[28:29], v[2:3]
	v_pk_mul_f32 v[4:5], v[28:29], v[4:5]
	v_pk_mul_f32 v[6:7], v[28:29], v[6:7]
	s_waitcnt lgkmcnt(0)
	v_pk_mul_f32 v[0:1], v[0:1], v[32:33]
	v_pk_mul_f32 v[2:3], v[2:3], v[34:35]
	v_pk_mul_f32 v[4:5], v[4:5], v[36:37]
	v_pk_mul_f32 v[6:7], v[6:7], v[38:39]
	v_pk_add_f32 v[40:41], v[40:41], 1.0 op_sel_hi:[1,0]
	v_pk_add_f32 v[42:43], v[42:43], 1.0 op_sel_hi:[1,0]
	v_pk_add_f32 v[44:45], v[44:45], 1.0 op_sel_hi:[1,0]
	v_pk_add_f32 v[46:47], v[46:47], 1.0 op_sel_hi:[1,0]
	v_pk_fma_f32 v[0:1], v[0:1], v[40:41], v[58:59]
	v_pk_fma_f32 v[2:3], v[2:3], v[42:43], v[60:61]
	v_pk_fma_f32 v[4:5], v[4:5], v[44:45], v[62:63]
	v_pk_fma_f32 v[6:7], v[6:7], v[46:47], v[64:65]
	ds_read_b128 v[32:35], v102 offset:1152
	ds_read_b128 v[36:39], v102 offset:1168
	ds_read_b128 v[40:43], v102 offset:5248
	ds_read_b128 v[44:47], v102 offset:5264
	ds_read_b128 v[58:61], v102 offset:9344
	ds_read_b128 v[62:65], v102 offset:9360
	v_cvt_pk_f16_f32 v74, v0, v1
	v_cvt_pk_f16_f32 v75, v2, v3
	v_cvt_pk_f16_f32 v76, v4, v5
	v_cvt_pk_f16_f32 v77, v6, v7
	v_cvt_f32_f16_e32 v66, v74
	v_cvt_f32_f16_sdwa v67, v74 dst_sel:DWORD dst_unused:UNUSED_PAD src0_sel:WORD_1
	v_cvt_f32_f16_e32 v68, v75
	v_cvt_f32_f16_sdwa v69, v75 dst_sel:DWORD dst_unused:UNUSED_PAD src0_sel:WORD_1
	v_cvt_f32_f16_e32 v70, v76
	v_cvt_f32_f16_sdwa v71, v76 dst_sel:DWORD dst_unused:UNUSED_PAD src0_sel:WORD_1
	v_cvt_f32_f16_e32 v72, v77
	v_cvt_f32_f16_sdwa v73, v77 dst_sel:DWORD dst_unused:UNUSED_PAD src0_sel:WORD_1
	v_pk_add_f32 v[0:1], v[0:1], v[66:67] neg_lo:[0,1] neg_hi:[0,1]
	v_pk_add_f32 v[2:3], v[2:3], v[68:69] neg_lo:[0,1] neg_hi:[0,1]
	v_pk_add_f32 v[4:5], v[4:5], v[70:71] neg_lo:[0,1] neg_hi:[0,1]
	v_pk_add_f32 v[6:7], v[6:7], v[72:73] neg_lo:[0,1] neg_hi:[0,1]
	s_nop 0
	v_cvt_pk_f16_f32 v78, v0, v1
	v_cvt_pk_f16_f32 v79, v2, v3
	v_cvt_pk_f16_f32 v80, v4, v5
	v_cvt_pk_f16_f32 v81, v6, v7
	global_store_dwordx4 v[88:89], v[74:77], off offset:512
	s_waitcnt vmcnt(48)
	v_mfma_f32_16x16x32_f16 a[8:11], v[74:77], a[128:131], a[8:11]
	v_mfma_f32_16x16x32_f16 a[8:11], v[78:81], a[128:131], a[8:11]
	v_mfma_f32_16x16x32_f16 a[8:11], v[74:77], a[132:135], a[8:11]
	v_mfma_f32_16x16x32_f16 a[4:7], v[74:77], a[136:139], a[4:7]
	v_mfma_f32_16x16x32_f16 a[4:7], v[78:81], a[136:139], a[4:7]
	v_mfma_f32_16x16x32_f16 a[4:7], v[74:77], a[140:143], a[4:7]
	v_mfma_f32_16x16x32_f16 a[0:3], v[74:77], a[144:147], a[0:3]
	v_mfma_f32_16x16x32_f16 a[0:3], v[78:81], a[144:147], a[0:3]
	v_mfma_f32_16x16x32_f16 a[0:3], v[74:77], a[148:151], a[0:3]
	global_load_dwordx4 a[128:131], v[90:91], off offset:896
	global_load_dwordx4 a[132:135], v[92:93], off offset:896
	global_load_dwordx4 a[136:139], v[94:95], off offset:896
	global_load_dwordx4 a[140:143], v[96:97], off offset:896
	global_load_dwordx4 a[144:147], v[98:99], off offset:896
	global_load_dwordx4 a[148:151], v[100:101], off offset:896
	s_waitcnt vmcnt(54)
	v_accvgpr_read_b32 v0, a24
	v_accvgpr_read_b32 v1, a25
	v_accvgpr_read_b32 v2, a26
	v_accvgpr_read_b32 v3, a27
	v_accvgpr_read_b32 v4, a28
	v_accvgpr_read_b32 v5, a29
	v_accvgpr_read_b32 v6, a30
	v_accvgpr_read_b32 v7, a31
	global_load_dwordx4 a[24:27], v[22:23], off offset:2176
	global_load_dwordx4 a[28:31], v[22:23], off offset:2192
	v_pk_mul_f32 v[0:1], v[28:29], v[0:1]
	v_pk_mul_f32 v[2:3], v[28:29], v[2:3]
	v_pk_mul_f32 v[4:5], v[28:29], v[4:5]
	v_pk_mul_f32 v[6:7], v[28:29], v[6:7]
	s_waitcnt lgkmcnt(0)
; DI f4 mfma16(h8 a, h8 b, f4 c) { return __builtin_amdgcn_mfma_f32_16x16x32_f16(a, b, c, 0, 0, 0); }
; DI void row2_phase(const Params& P, int l, int r_begin, char* smem) {
;     ...
; #pragma unroll 4
;     for (int kk = 0; kk < 32; kk++) {
;       const int k0 = kk * 32;
;       float x[8], g[8], s1[8], s0[8];
;       *(float4*)&x[0] = *(const float4*)(xm + k0); *(float4*)&x[4] = *(const float4*)(xm + k0 + 4);
;       *(float4*)&g[0] = *(const float4*)(gam + fq * 8 + k0); *(float4*)&g[4] = *(const float4*)(gam + fq * 8 + k0 + 4);
;       *(float4*)&s1[0] = *(const float4*)(sc + k0); *(float4*)&s1[4] = *(const float4*)(sc + k0 + 4);
;       *(float4*)&s0[0] = *(const float4*)(sh + k0); *(float4*)&s0[4] = *(const float4*)(sh + k0 + 4);
;       h8 hi, lo;
; #pragma unroll
;       for (int i = 0; i < 8; i++) {
;         float v = x[i] * rstd * g[i] * (1.f + s1[i]) + s0[i];
;         hi[i] = (half_t)v; lo[i] = (half_t)(v - (float)hi[i]);
;       }
;       *(h8*)(hxo + k0) = hi;
; #pragma unroll
;       for (int n3 = 0; n3 < 3; n3++) {
;         h8 bh = *(const h8*)(Whi + (size_t)(n3 * 16 + fr) * 1024 + k0 + fq * 8);
;         h8 bl = *(const h8*)(Wlo + (size_t)(n3 * 16 + fr) * 1024 + k0 + fq * 8);
;         acc[n3] = mfma16(hi, bh, acc[n3]); acc[n3] = mfma16(lo, bh, acc[n3]); acc[n3] = mfma16(hi, bl, acc[n3]);
;       }
;     }
	v_pk_mul_f32 v[0:1], v[0:1], v[32:33]
	v_pk_mul_f32 v[2:3], v[2:3], v[34:35]
	v_pk_mul_f32 v[4:5], v[4:5], v[36:37]
	v_pk_mul_f32 v[6:7], v[6:7], v[38:39]
	v_pk_add_f32 v[40:41], v[40:41], 1.0 op_sel_hi:[1,0]
	v_pk_add_f32 v[42:43], v[42:43], 1.0 op_sel_hi:[1,0]
	v_pk_add_f32 v[44:45], v[44:45], 1.0 op_sel_hi:[1,0]
	v_pk_add_f32 v[46:47], v[46:47], 1.0 op_sel_hi:[1,0]
	v_pk_fma_f32 v[0:1], v[0:1], v[40:41], v[58:59]
	v_pk_fma_f32 v[2:3], v[2:3], v[42:43], v[60:61]
	v_pk_fma_f32 v[4:5], v[4:5], v[44:45], v[62:63]
	v_pk_fma_f32 v[6:7], v[6:7], v[46:47], v[64:65]
	ds_read_b128 v[32:35], v102 offset:1280
	ds_read_b128 v[36:39], v102 offset:1296
	ds_read_b128 v[40:43], v102 offset:5376
	ds_read_b128 v[44:47], v102 offset:5392
	ds_read_b128 v[58:61], v102 offset:9472
	ds_read_b128 v[62:65], v102 offset:9488
	v_cvt_pk_f16_f32 v74, v0, v1
	v_cvt_pk_f16_f32 v75, v2, v3
	v_cvt_pk_f16_f32 v76, v4, v5
	v_cvt_pk_f16_f32 v77, v6, v7
	v_cvt_f32_f16_e32 v66, v74
	v_cvt_f32_f16_sdwa v67, v74 dst_sel:DWORD dst_unused:UNUSED_PAD src0_sel:WORD_1
	v_cvt_f32_f16_e32 v68, v75
	v_cvt_f32_f16_sdwa v69, v75 dst_sel:DWORD dst_unused:UNUSED_PAD src0_sel:WORD_1
	v_cvt_f32_f16_e32 v70, v76
	v_cvt_f32_f16_sdwa v71, v76 dst_sel:DWORD dst_unused:UNUSED_PAD src0_sel:WORD_1
	v_cvt_f32_f16_e32 v72, v77
	v_cvt_f32_f16_sdwa v73, v77 dst_sel:DWORD dst_unused:UNUSED_PAD src0_sel:WORD_1
	v_pk_add_f32 v[0:1], v[0:1], v[66:67] neg_lo:[0,1] neg_hi:[0,1]
	v_pk_add_f32 v[2:3], v[2:3], v[68:69] neg_lo:[0,1] neg_hi:[0,1]
	v_pk_add_f32 v[4:5], v[4:5], v[70:71] neg_lo:[0,1] neg_hi:[0,1]
	v_pk_add_f32 v[6:7], v[6:7], v[72:73] neg_lo:[0,1] neg_hi:[0,1]
	s_nop 0
	v_cvt_pk_f16_f32 v78, v0, v1
	v_cvt_pk_f16_f32 v79, v2, v3
	v_cvt_pk_f16_f32 v80, v4, v5
	v_cvt_pk_f16_f32 v81, v6, v7
	global_store_dwordx4 v[88:89], v[74:77], off offset:576
	s_waitcnt vmcnt(48)
	v_mfma_f32_16x16x32_f16 a[8:11], v[74:77], a[152:155], a[8:11]
	v_mfma_f32_16x16x32_f16 a[8:11], v[78:81], a[152:155], a[8:11]
	v_mfma_f32_16x16x32_f16 a[8:11], v[74:77], a[156:159], a[8:11]
	v_mfma_f32_16x16x32_f16 a[4:7], v[74:77], a[160:163], a[4:7]
	v_mfma_f32_16x16x32_f16 a[4:7], v[78:81], a[160:163], a[4:7]
	v_mfma_f32_16x16x32_f16 a[4:7], v[74:77], a[164:167], a[4:7]
	v_mfma_f32_16x16x32_f16 a[0:3], v[74:77], a[168:171], a[0:3]
	v_mfma_f32_16x16x32_f16 a[0:3], v[78:81], a[168:171], a[0:3]
	v_mfma_f32_16x16x32_f16 a[0:3], v[74:77], a[172:175], a[0:3]
	global_load_dwordx4 a[152:155], v[90:91], off offset:960
	global_load_dwordx4 a[156:159], v[92:93], off offset:960
	global_load_dwordx4 a[160:163], v[94:95], off offset:960
	global_load_dwordx4 a[164:167], v[96:97], off offset:960
	global_load_dwordx4 a[168:171], v[98:99], off offset:960
	global_load_dwordx4 a[172:175], v[100:101], off offset:960
	s_waitcnt vmcnt(54)
	v_accvgpr_read_b32 v0, a32
	v_accvgpr_read_b32 v1, a33
	v_accvgpr_read_b32 v2, a34
	v_accvgpr_read_b32 v3, a35
	v_accvgpr_read_b32 v4, a36
	v_accvgpr_read_b32 v5, a37
	v_accvgpr_read_b32 v6, a38
	v_accvgpr_read_b32 v7, a39
	global_load_dwordx4 a[32:35], v[22:23], off offset:2304
	global_load_dwordx4 a[36:39], v[22:23], off offset:2320
	v_pk_mul_f32 v[0:1], v[28:29], v[0:1]
	v_pk_mul_f32 v[2:3], v[28:29], v[2:3]
	v_pk_mul_f32 v[4:5], v[28:29], v[4:5]
	v_pk_mul_f32 v[6:7], v[28:29], v[6:7]
	s_waitcnt lgkmcnt(0)
	v_pk_mul_f32 v[0:1], v[0:1], v[32:33]
	v_pk_mul_f32 v[2:3], v[2:3], v[34:35]
	v_pk_mul_f32 v[4:5], v[4:5], v[36:37]
	v_pk_mul_f32 v[6:7], v[6:7], v[38:39]
	v_pk_add_f32 v[40:41], v[40:41], 1.0 op_sel_hi:[1,0]
	v_pk_add_f32 v[42:43], v[42:43], 1.0 op_sel_hi:[1,0]
	v_pk_add_f32 v[44:45], v[44:45], 1.0 op_sel_hi:[1,0]
	v_pk_add_f32 v[46:47], v[46:47], 1.0 op_sel_hi:[1,0]
	v_pk_fma_f32 v[0:1], v[0:1], v[40:41], v[58:59]
	v_pk_fma_f32 v[2:3], v[2:3], v[42:43], v[60:61]
	v_pk_fma_f32 v[4:5], v[4:5], v[44:45], v[62:63]
	v_pk_fma_f32 v[6:7], v[6:7], v[46:47], v[64:65]
	ds_read_b128 v[32:35], v102 offset:1408
	ds_read_b128 v[36:39], v102 offset:1424
	ds_read_b128 v[40:43], v102 offset:5504
	ds_read_b128 v[44:47], v102 offset:5520
	ds_read_b128 v[58:61], v102 offset:9600
	ds_read_b128 v[62:65], v102 offset:9616
	v_cvt_pk_f16_f32 v74, v0, v1
	v_cvt_pk_f16_f32 v75, v2, v3
	v_cvt_pk_f16_f32 v76, v4, v5
	v_cvt_pk_f16_f32 v77, v6, v7
	v_cvt_f32_f16_e32 v66, v74
	v_cvt_f32_f16_sdwa v67, v74 dst_sel:DWORD dst_unused:UNUSED_PAD src0_sel:WORD_1
	v_cvt_f32_f16_e32 v68, v75
	v_cvt_f32_f16_sdwa v69, v75 dst_sel:DWORD dst_unused:UNUSED_PAD src0_sel:WORD_1
	v_cvt_f32_f16_e32 v70, v76
	v_cvt_f32_f16_sdwa v71, v76 dst_sel:DWORD dst_unused:UNUSED_PAD src0_sel:WORD_1
	v_cvt_f32_f16_e32 v72, v77
	v_cvt_f32_f16_sdwa v73, v77 dst_sel:DWORD dst_unused:UNUSED_PAD src0_sel:WORD_1
	v_pk_add_f32 v[0:1], v[0:1], v[66:67] neg_lo:[0,1] neg_hi:[0,1]
	v_pk_add_f32 v[2:3], v[2:3], v[68:69] neg_lo:[0,1] neg_hi:[0,1]
	v_pk_add_f32 v[4:5], v[4:5], v[70:71] neg_lo:[0,1] neg_hi:[0,1]
	v_pk_add_f32 v[6:7], v[6:7], v[72:73] neg_lo:[0,1] neg_hi:[0,1]
	s_nop 0
	v_cvt_pk_f16_f32 v78, v0, v1
	v_cvt_pk_f16_f32 v79, v2, v3
	v_cvt_pk_f16_f32 v80, v4, v5
	v_cvt_pk_f16_f32 v81, v6, v7
	global_store_dwordx4 v[88:89], v[74:77], off offset:640
	s_waitcnt vmcnt(48)
	v_mfma_f32_16x16x32_f16 a[8:11], v[74:77], a[204:207], a[8:11]
	v_mfma_f32_16x16x32_f16 a[8:11], v[78:81], a[204:207], a[8:11]
	v_mfma_f32_16x16x32_f16 a[8:11], v[74:77], a[208:211], a[8:11]
	v_mfma_f32_16x16x32_f16 a[4:7], v[74:77], a[212:215], a[4:7]
	v_mfma_f32_16x16x32_f16 a[4:7], v[78:81], a[212:215], a[4:7]
	v_mfma_f32_16x16x32_f16 a[4:7], v[74:77], a[216:219], a[4:7]
	v_mfma_f32_16x16x32_f16 a[0:3], v[74:77], a[220:223], a[0:3]
	v_mfma_f32_16x16x32_f16 a[0:3], v[78:81], a[220:223], a[0:3]
	v_mfma_f32_16x16x32_f16 a[0:3], v[74:77], a[224:227], a[0:3]
	global_load_dwordx4 a[204:207], v[90:91], off offset:1024
	global_load_dwordx4 a[208:211], v[92:93], off offset:1024
	global_load_dwordx4 a[212:215], v[94:95], off offset:1024
	global_load_dwordx4 a[216:219], v[96:97], off offset:1024
	global_load_dwordx4 a[220:223], v[98:99], off offset:1024
	global_load_dwordx4 a[224:227], v[100:101], off offset:1024
	s_waitcnt vmcnt(54)
; DI f4 mfma16(h8 a, h8 b, f4 c) { return __builtin_amdgcn_mfma_f32_16x16x32_f16(a, b, c, 0, 0, 0); }
; DI void row2_phase(const Params& P, int l, int r_begin, char* smem) {
;     ...
;     for (int kk = 0; kk < 32; kk++) {
;       const int k0 = kk * 32;
;       float x[8], g[8], s1[8], s0[8];
;       *(float4*)&x[0] = *(const float4*)(xm + k0); *(float4*)&x[4] = *(const float4*)(xm + k0 + 4);
;       *(float4*)&g[0] = *(const float4*)(gam + fq * 8 + k0); *(float4*)&g[4] = *(const float4*)(gam + fq * 8 + k0 + 4);
;       *(float4*)&s1[0] = *(const float4*)(sc + k0); *(float4*)&s1[4] = *(const float4*)(sc + k0 + 4);
;       *(float4*)&s0[0] = *(const float4*)(sh + k0); *(float4*)&s0[4] = *(const float4*)(sh + k0 + 4);
;       h8 hi, lo;
; #pragma unroll
;       for (int i = 0; i < 8; i++) {
;         float v = x[i] * rstd * g[i] * (1.f + s1[i]) + s0[i];
;         hi[i] = (half_t)v; lo[i] = (half_t)(v - (float)hi[i]);
;       }
;       *(h8*)(hxo + k0) = hi;
; #pragma unroll
;       for (int n3 = 0; n3 < 3; n3++) {
;         h8 bh = *(const h8*)(Whi + (size_t)(n3 * 16 + fr) * 1024 + k0 + fq * 8);
;         h8 bl = *(const h8*)(Wlo + (size_t)(n3 * 16 + fr) * 1024 + k0 + fq * 8);
;         acc[n3] = mfma16(hi, bh, acc[n3]); acc[n3] = mfma16(lo, bh, acc[n3]); acc[n3] = mfma16(hi, bl, acc[n3]);
;       }
	v_accvgpr_read_b32 v0, a40
	v_accvgpr_read_b32 v1, a41
	v_accvgpr_read_b32 v2, a42
	v_accvgpr_read_b32 v3, a43
	v_accvgpr_read_b32 v4, a44
	v_accvgpr_read_b32 v5, a45
	v_accvgpr_read_b32 v6, a46
	v_accvgpr_read_b32 v7, a47
	global_load_dwordx4 a[40:43], v[22:23], off offset:2432
	global_load_dwordx4 a[44:47], v[22:23], off offset:2448
	v_pk_mul_f32 v[0:1], v[28:29], v[0:1]
	v_pk_mul_f32 v[2:3], v[28:29], v[2:3]
	v_pk_mul_f32 v[4:5], v[28:29], v[4:5]
	v_pk_mul_f32 v[6:7], v[28:29], v[6:7]
	s_waitcnt lgkmcnt(0)
	v_pk_mul_f32 v[0:1], v[0:1], v[32:33]
	v_pk_mul_f32 v[2:3], v[2:3], v[34:35]
	v_pk_mul_f32 v[4:5], v[4:5], v[36:37]
	v_pk_mul_f32 v[6:7], v[6:7], v[38:39]
	v_pk_add_f32 v[40:41], v[40:41], 1.0 op_sel_hi:[1,0]
	v_pk_add_f32 v[42:43], v[42:43], 1.0 op_sel_hi:[1,0]
	v_pk_add_f32 v[44:45], v[44:45], 1.0 op_sel_hi:[1,0]
	v_pk_add_f32 v[46:47], v[46:47], 1.0 op_sel_hi:[1,0]
	v_pk_fma_f32 v[0:1], v[0:1], v[40:41], v[58:59]
	v_pk_fma_f32 v[2:3], v[2:3], v[42:43], v[60:61]
	v_pk_fma_f32 v[4:5], v[4:5], v[44:45], v[62:63]
	v_pk_fma_f32 v[6:7], v[6:7], v[46:47], v[64:65]
	ds_read_b128 v[32:35], v102 offset:1536
	ds_read_b128 v[36:39], v102 offset:1552
	ds_read_b128 v[40:43], v102 offset:5632
	ds_read_b128 v[44:47], v102 offset:5648
	ds_read_b128 v[58:61], v102 offset:9728
	ds_read_b128 v[62:65], v102 offset:9744
	v_cvt_pk_f16_f32 v74, v0, v1
	v_cvt_pk_f16_f32 v75, v2, v3
	v_cvt_pk_f16_f32 v76, v4, v5
	v_cvt_pk_f16_f32 v77, v6, v7
	v_cvt_f32_f16_e32 v66, v74
	v_cvt_f32_f16_sdwa v67, v74 dst_sel:DWORD dst_unused:UNUSED_PAD src0_sel:WORD_1
	v_cvt_f32_f16_e32 v68, v75
	v_cvt_f32_f16_sdwa v69, v75 dst_sel:DWORD dst_unused:UNUSED_PAD src0_sel:WORD_1
	v_cvt_f32_f16_e32 v70, v76
	v_cvt_f32_f16_sdwa v71, v76 dst_sel:DWORD dst_unused:UNUSED_PAD src0_sel:WORD_1
	v_cvt_f32_f16_e32 v72, v77
	v_cvt_f32_f16_sdwa v73, v77 dst_sel:DWORD dst_unused:UNUSED_PAD src0_sel:WORD_1
	v_pk_add_f32 v[0:1], v[0:1], v[66:67] neg_lo:[0,1] neg_hi:[0,1]
	v_pk_add_f32 v[2:3], v[2:3], v[68:69] neg_lo:[0,1] neg_hi:[0,1]
	v_pk_add_f32 v[4:5], v[4:5], v[70:71] neg_lo:[0,1] neg_hi:[0,1]
	v_pk_add_f32 v[6:7], v[6:7], v[72:73] neg_lo:[0,1] neg_hi:[0,1]
	s_nop 0
	v_cvt_pk_f16_f32 v78, v0, v1
	v_cvt_pk_f16_f32 v79, v2, v3
	v_cvt_pk_f16_f32 v80, v4, v5
	v_cvt_pk_f16_f32 v81, v6, v7
	global_store_dwordx4 v[88:89], v[74:77], off offset:704
	s_waitcnt vmcnt(48)
	v_mfma_f32_16x16x32_f16 a[8:11], v[74:77], a[228:231], a[8:11]
	v_mfma_f32_16x16x32_f16 a[8:11], v[78:81], a[228:231], a[8:11]
	v_mfma_f32_16x16x32_f16 a[8:11], v[74:77], a[232:235], a[8:11]
	v_mfma_f32_16x16x32_f16 a[4:7], v[74:77], a[236:239], a[4:7]
	v_mfma_f32_16x16x32_f16 a[4:7], v[78:81], a[236:239], a[4:7]
	v_mfma_f32_16x16x32_f16 a[4:7], v[74:77], a[240:243], a[4:7]
	v_mfma_f32_16x16x32_f16 a[0:3], v[74:77], a[244:247], a[0:3]
	v_mfma_f32_16x16x32_f16 a[0:3], v[78:81], a[244:247], a[0:3]
	v_mfma_f32_16x16x32_f16 a[0:3], v[74:77], a[248:251], a[0:3]
	global_load_dwordx4 a[228:231], v[90:91], off offset:1088
	global_load_dwordx4 a[232:235], v[92:93], off offset:1088
	global_load_dwordx4 a[236:239], v[94:95], off offset:1088
	global_load_dwordx4 a[240:243], v[96:97], off offset:1088
	global_load_dwordx4 a[244:247], v[98:99], off offset:1088
	global_load_dwordx4 a[248:251], v[100:101], off offset:1088
	s_waitcnt vmcnt(54)
	v_accvgpr_read_b32 v0, a48
	v_accvgpr_read_b32 v1, a49
	v_accvgpr_read_b32 v2, a50
	v_accvgpr_read_b32 v3, a51
	v_accvgpr_read_b32 v4, a52
	v_accvgpr_read_b32 v5, a53
	v_accvgpr_read_b32 v6, a54
	v_accvgpr_read_b32 v7, a55
	global_load_dwordx4 a[48:51], v[22:23], off offset:2560
	global_load_dwordx4 a[52:55], v[22:23], off offset:2576
	v_pk_mul_f32 v[0:1], v[28:29], v[0:1]
	v_pk_mul_f32 v[2:3], v[28:29], v[2:3]
	v_pk_mul_f32 v[4:5], v[28:29], v[4:5]
	v_pk_mul_f32 v[6:7], v[28:29], v[6:7]
	s_waitcnt lgkmcnt(0)
	v_pk_mul_f32 v[0:1], v[0:1], v[32:33]
	v_pk_mul_f32 v[2:3], v[2:3], v[34:35]
	v_pk_mul_f32 v[4:5], v[4:5], v[36:37]
	v_pk_mul_f32 v[6:7], v[6:7], v[38:39]
	v_pk_add_f32 v[40:41], v[40:41], 1.0 op_sel_hi:[1,0]
	v_pk_add_f32 v[42:43], v[42:43], 1.0 op_sel_hi:[1,0]
	v_pk_add_f32 v[44:45], v[44:45], 1.0 op_sel_hi:[1,0]
	v_pk_add_f32 v[46:47], v[46:47], 1.0 op_sel_hi:[1,0]
	v_pk_fma_f32 v[0:1], v[0:1], v[40:41], v[58:59]
	v_pk_fma_f32 v[2:3], v[2:3], v[42:43], v[60:61]
	v_pk_fma_f32 v[4:5], v[4:5], v[44:45], v[62:63]
	v_pk_fma_f32 v[6:7], v[6:7], v[46:47], v[64:65]
	ds_read_b128 v[32:35], v102 offset:1664
	ds_read_b128 v[36:39], v102 offset:1680
	ds_read_b128 v[40:43], v102 offset:5760
	ds_read_b128 v[44:47], v102 offset:5776
	ds_read_b128 v[58:61], v102 offset:9856
	ds_read_b128 v[62:65], v102 offset:9872
	v_cvt_pk_f16_f32 v74, v0, v1
	v_cvt_pk_f16_f32 v75, v2, v3
	v_cvt_pk_f16_f32 v76, v4, v5
	v_cvt_pk_f16_f32 v77, v6, v7
	v_cvt_f32_f16_e32 v66, v74
	v_cvt_f32_f16_sdwa v67, v74 dst_sel:DWORD dst_unused:UNUSED_PAD src0_sel:WORD_1
	v_cvt_f32_f16_e32 v68, v75
	v_cvt_f32_f16_sdwa v69, v75 dst_sel:DWORD dst_unused:UNUSED_PAD src0_sel:WORD_1
	v_cvt_f32_f16_e32 v70, v76
	v_cvt_f32_f16_sdwa v71, v76 dst_sel:DWORD dst_unused:UNUSED_PAD src0_sel:WORD_1
	v_cvt_f32_f16_e32 v72, v77
	v_cvt_f32_f16_sdwa v73, v77 dst_sel:DWORD dst_unused:UNUSED_PAD src0_sel:WORD_1
	v_pk_add_f32 v[0:1], v[0:1], v[66:67] neg_lo:[0,1] neg_hi:[0,1]
	v_pk_add_f32 v[2:3], v[2:3], v[68:69] neg_lo:[0,1] neg_hi:[0,1]
	v_pk_add_f32 v[4:5], v[4:5], v[70:71] neg_lo:[0,1] neg_hi:[0,1]
	v_pk_add_f32 v[6:7], v[6:7], v[72:73] neg_lo:[0,1] neg_hi:[0,1]
	s_nop 0
	v_cvt_pk_f16_f32 v78, v0, v1
	v_cvt_pk_f16_f32 v79, v2, v3
	v_cvt_pk_f16_f32 v80, v4, v5
	v_cvt_pk_f16_f32 v81, v6, v7
	global_store_dwordx4 v[88:89], v[74:77], off offset:768
	s_waitcnt vmcnt(48)
; DI f4 mfma16(h8 a, h8 b, f4 c) { return __builtin_amdgcn_mfma_f32_16x16x32_f16(a, b, c, 0, 0, 0); }
; DI void row2_phase(const Params& P, int l, int r_begin, char* smem) {
;     ...
;     for (int kk = 0; kk < 32; kk++) {
;       const int k0 = kk * 32;
;       float x[8], g[8], s1[8], s0[8];
;       *(float4*)&x[0] = *(const float4*)(xm + k0); *(float4*)&x[4] = *(const float4*)(xm + k0 + 4);
;       *(float4*)&g[0] = *(const float4*)(gam + fq * 8 + k0); *(float4*)&g[4] = *(const float4*)(gam + fq * 8 + k0 + 4);
;       *(float4*)&s1[0] = *(const float4*)(sc + k0); *(float4*)&s1[4] = *(const float4*)(sc + k0 + 4);
;       *(float4*)&s0[0] = *(const float4*)(sh + k0); *(float4*)&s0[4] = *(const float4*)(sh + k0 + 4);
;       h8 hi, lo;
; #pragma unroll
;       for (int i = 0; i < 8; i++) {
;         float v = x[i] * rstd * g[i] * (1.f + s1[i]) + s0[i];
;         hi[i] = (half_t)v; lo[i] = (half_t)(v - (float)hi[i]);
;       }
;       *(h8*)(hxo + k0) = hi;
; #pragma unroll
;       for (int n3 = 0; n3 < 3; n3++) {
;         h8 bh = *(const h8*)(Whi + (size_t)(n3 * 16 + fr) * 1024 + k0 + fq * 8);
;         h8 bl = *(const h8*)(Wlo + (size_t)(n3 * 16 + fr) * 1024 + k0 + fq * 8);
;         acc[n3] = mfma16(hi, bh, acc[n3]); acc[n3] = mfma16(lo, bh, acc[n3]); acc[n3] = mfma16(hi, bl, acc[n3]);
;       }
	v_mfma_f32_16x16x32_f16 a[8:11], v[74:77], a[80:83], a[8:11]
	v_mfma_f32_16x16x32_f16 a[8:11], v[78:81], a[80:83], a[8:11]
	v_mfma_f32_16x16x32_f16 a[8:11], v[74:77], a[84:87], a[8:11]
	v_mfma_f32_16x16x32_f16 a[4:7], v[74:77], a[88:91], a[4:7]
	v_mfma_f32_16x16x32_f16 a[4:7], v[78:81], a[88:91], a[4:7]
	v_mfma_f32_16x16x32_f16 a[4:7], v[74:77], a[92:95], a[4:7]
	v_mfma_f32_16x16x32_f16 a[0:3], v[74:77], a[96:99], a[0:3]
	v_mfma_f32_16x16x32_f16 a[0:3], v[78:81], a[96:99], a[0:3]
	v_mfma_f32_16x16x32_f16 a[0:3], v[74:77], a[100:103], a[0:3]
	global_load_dwordx4 a[80:83], v[90:91], off offset:1152
	global_load_dwordx4 a[84:87], v[92:93], off offset:1152
	global_load_dwordx4 a[88:91], v[94:95], off offset:1152
	global_load_dwordx4 a[92:95], v[96:97], off offset:1152
	global_load_dwordx4 a[96:99], v[98:99], off offset:1152
	global_load_dwordx4 a[100:103], v[100:101], off offset:1152
	s_waitcnt vmcnt(54)
	v_accvgpr_read_b32 v0, a56
	v_accvgpr_read_b32 v1, a57
	v_accvgpr_read_b32 v2, a58
	v_accvgpr_read_b32 v3, a59
	v_accvgpr_read_b32 v4, a60
	v_accvgpr_read_b32 v5, a61
	v_accvgpr_read_b32 v6, a62
	v_accvgpr_read_b32 v7, a63
	global_load_dwordx4 a[56:59], v[22:23], off offset:2688
	global_load_dwordx4 a[60:63], v[22:23], off offset:2704
	v_pk_mul_f32 v[0:1], v[28:29], v[0:1]
	v_pk_mul_f32 v[2:3], v[28:29], v[2:3]
	v_pk_mul_f32 v[4:5], v[28:29], v[4:5]
	v_pk_mul_f32 v[6:7], v[28:29], v[6:7]
	s_waitcnt lgkmcnt(0)
	v_pk_mul_f32 v[0:1], v[0:1], v[32:33]
	v_pk_mul_f32 v[2:3], v[2:3], v[34:35]
	v_pk_mul_f32 v[4:5], v[4:5], v[36:37]
	v_pk_mul_f32 v[6:7], v[6:7], v[38:39]
	v_pk_add_f32 v[40:41], v[40:41], 1.0 op_sel_hi:[1,0]
	v_pk_add_f32 v[42:43], v[42:43], 1.0 op_sel_hi:[1,0]
	v_pk_add_f32 v[44:45], v[44:45], 1.0 op_sel_hi:[1,0]
	v_pk_add_f32 v[46:47], v[46:47], 1.0 op_sel_hi:[1,0]
	v_pk_fma_f32 v[0:1], v[0:1], v[40:41], v[58:59]
	v_pk_fma_f32 v[2:3], v[2:3], v[42:43], v[60:61]
	v_pk_fma_f32 v[4:5], v[4:5], v[44:45], v[62:63]
	v_pk_fma_f32 v[6:7], v[6:7], v[46:47], v[64:65]
	ds_read_b128 v[32:35], v102 offset:1792
	ds_read_b128 v[36:39], v102 offset:1808
	ds_read_b128 v[40:43], v102 offset:5888
	ds_read_b128 v[44:47], v102 offset:5904
	ds_read_b128 v[58:61], v102 offset:9984
	ds_read_b128 v[62:65], v102 offset:10000
	v_cvt_pk_f16_f32 v74, v0, v1
	v_cvt_pk_f16_f32 v75, v2, v3
	v_cvt_pk_f16_f32 v76, v4, v5
	v_cvt_pk_f16_f32 v77, v6, v7
	v_cvt_f32_f16_e32 v66, v74
	v_cvt_f32_f16_sdwa v67, v74 dst_sel:DWORD dst_unused:UNUSED_PAD src0_sel:WORD_1
	v_cvt_f32_f16_e32 v68, v75
	v_cvt_f32_f16_sdwa v69, v75 dst_sel:DWORD dst_unused:UNUSED_PAD src0_sel:WORD_1
	v_cvt_f32_f16_e32 v70, v76
	v_cvt_f32_f16_sdwa v71, v76 dst_sel:DWORD dst_unused:UNUSED_PAD src0_sel:WORD_1
	v_cvt_f32_f16_e32 v72, v77
	v_cvt_f32_f16_sdwa v73, v77 dst_sel:DWORD dst_unused:UNUSED_PAD src0_sel:WORD_1
	v_pk_add_f32 v[0:1], v[0:1], v[66:67] neg_lo:[0,1] neg_hi:[0,1]
	v_pk_add_f32 v[2:3], v[2:3], v[68:69] neg_lo:[0,1] neg_hi:[0,1]
	v_pk_add_f32 v[4:5], v[4:5], v[70:71] neg_lo:[0,1] neg_hi:[0,1]
	v_pk_add_f32 v[6:7], v[6:7], v[72:73] neg_lo:[0,1] neg_hi:[0,1]
	s_nop 0
	v_cvt_pk_f16_f32 v78, v0, v1
	v_cvt_pk_f16_f32 v79, v2, v3
	v_cvt_pk_f16_f32 v80, v4, v5
	v_cvt_pk_f16_f32 v81, v6, v7
	global_store_dwordx4 v[88:89], v[74:77], off offset:832
	s_waitcnt vmcnt(48)
	v_mfma_f32_16x16x32_f16 a[8:11], v[74:77], a[104:107], a[8:11]
	v_mfma_f32_16x16x32_f16 a[8:11], v[78:81], a[104:107], a[8:11]
	v_mfma_f32_16x16x32_f16 a[8:11], v[74:77], a[108:111], a[8:11]
	v_mfma_f32_16x16x32_f16 a[4:7], v[74:77], a[112:115], a[4:7]
	v_mfma_f32_16x16x32_f16 a[4:7], v[78:81], a[112:115], a[4:7]
	v_mfma_f32_16x16x32_f16 a[4:7], v[74:77], a[116:119], a[4:7]
	v_mfma_f32_16x16x32_f16 a[0:3], v[74:77], a[120:123], a[0:3]
	v_mfma_f32_16x16x32_f16 a[0:3], v[78:81], a[120:123], a[0:3]
	v_mfma_f32_16x16x32_f16 a[0:3], v[74:77], a[124:127], a[0:3]
	global_load_dwordx4 a[104:107], v[90:91], off offset:1216
	global_load_dwordx4 a[108:111], v[92:93], off offset:1216
	global_load_dwordx4 a[112:115], v[94:95], off offset:1216
	global_load_dwordx4 a[116:119], v[96:97], off offset:1216
	global_load_dwordx4 a[120:123], v[98:99], off offset:1216
	global_load_dwordx4 a[124:127], v[100:101], off offset:1216
	s_waitcnt vmcnt(54)
	v_accvgpr_read_b32 v0, a64
	v_accvgpr_read_b32 v1, a65
	v_accvgpr_read_b32 v2, a66
	v_accvgpr_read_b32 v3, a67
	v_accvgpr_read_b32 v4, a68
	v_accvgpr_read_b32 v5, a69
	v_accvgpr_read_b32 v6, a70
	v_accvgpr_read_b32 v7, a71
	global_load_dwordx4 a[64:67], v[22:23], off offset:2816
	global_load_dwordx4 a[68:71], v[22:23], off offset:2832
	v_pk_mul_f32 v[0:1], v[28:29], v[0:1]
	v_pk_mul_f32 v[2:3], v[28:29], v[2:3]
	v_pk_mul_f32 v[4:5], v[28:29], v[4:5]
	v_pk_mul_f32 v[6:7], v[28:29], v[6:7]
	s_waitcnt lgkmcnt(0)
; DI f4 mfma16(h8 a, h8 b, f4 c) { return __builtin_amdgcn_mfma_f32_16x16x32_f16(a, b, c, 0, 0, 0); }
; DI void row2_phase(const Params& P, int l, int r_begin, char* smem) {
;     ...
;     for (int kk = 0; kk < 32; kk++) {
;       const int k0 = kk * 32;
;       float x[8], g[8], s1[8], s0[8];
;       *(float4*)&x[0] = *(const float4*)(xm + k0); *(float4*)&x[4] = *(const float4*)(xm + k0 + 4);
;       *(float4*)&g[0] = *(const float4*)(gam + fq * 8 + k0); *(float4*)&g[4] = *(const float4*)(gam + fq * 8 + k0 + 4);
;       *(float4*)&s1[0] = *(const float4*)(sc + k0); *(float4*)&s1[4] = *(const float4*)(sc + k0 + 4);
;       *(float4*)&s0[0] = *(const float4*)(sh + k0); *(float4*)&s0[4] = *(const float4*)(sh + k0 + 4);
;       h8 hi, lo;
; #pragma unroll
;       for (int i = 0; i < 8; i++) {
;         float v = x[i] * rstd * g[i] * (1.f + s1[i]) + s0[i];
;         hi[i] = (half_t)v; lo[i] = (half_t)(v - (float)hi[i]);
;       }
;       *(h8*)(hxo + k0) = hi;
; #pragma unroll
;       for (int n3 = 0; n3 < 3; n3++) {
;         h8 bh = *(const h8*)(Whi + (size_t)(n3 * 16 + fr) * 1024 + k0 + fq * 8);
;         h8 bl = *(const h8*)(Wlo + (size_t)(n3 * 16 + fr) * 1024 + k0 + fq * 8);
;         acc[n3] = mfma16(hi, bh, acc[n3]); acc[n3] = mfma16(lo, bh, acc[n3]); acc[n3] = mfma16(hi, bl, acc[n3]);
;       }
	v_pk_mul_f32 v[0:1], v[0:1], v[32:33]
	v_pk_mul_f32 v[2:3], v[2:3], v[34:35]
	v_pk_mul_f32 v[4:5], v[4:5], v[36:37]
	v_pk_mul_f32 v[6:7], v[6:7], v[38:39]
	v_pk_add_f32 v[40:41], v[40:41], 1.0 op_sel_hi:[1,0]
	v_pk_add_f32 v[42:43], v[42:43], 1.0 op_sel_hi:[1,0]
	v_pk_add_f32 v[44:45], v[44:45], 1.0 op_sel_hi:[1,0]
	v_pk_add_f32 v[46:47], v[46:47], 1.0 op_sel_hi:[1,0]
	v_pk_fma_f32 v[0:1], v[0:1], v[40:41], v[58:59]
	v_pk_fma_f32 v[2:3], v[2:3], v[42:43], v[60:61]
	v_pk_fma_f32 v[4:5], v[4:5], v[44:45], v[62:63]
	v_pk_fma_f32 v[6:7], v[6:7], v[46:47], v[64:65]
	ds_read_b128 v[32:35], v102 offset:1920
	ds_read_b128 v[36:39], v102 offset:1936
	ds_read_b128 v[40:43], v102 offset:6016
	ds_read_b128 v[44:47], v102 offset:6032
	ds_read_b128 v[58:61], v102 offset:10112
	ds_read_b128 v[62:65], v102 offset:10128
	v_cvt_pk_f16_f32 v74, v0, v1
	v_cvt_pk_f16_f32 v75, v2, v3
	v_cvt_pk_f16_f32 v76, v4, v5
	v_cvt_pk_f16_f32 v77, v6, v7
	v_cvt_f32_f16_e32 v66, v74
	v_cvt_f32_f16_sdwa v67, v74 dst_sel:DWORD dst_unused:UNUSED_PAD src0_sel:WORD_1
	v_cvt_f32_f16_e32 v68, v75
	v_cvt_f32_f16_sdwa v69, v75 dst_sel:DWORD dst_unused:UNUSED_PAD src0_sel:WORD_1
	v_cvt_f32_f16_e32 v70, v76
	v_cvt_f32_f16_sdwa v71, v76 dst_sel:DWORD dst_unused:UNUSED_PAD src0_sel:WORD_1
	v_cvt_f32_f16_e32 v72, v77
	v_cvt_f32_f16_sdwa v73, v77 dst_sel:DWORD dst_unused:UNUSED_PAD src0_sel:WORD_1
	v_pk_add_f32 v[0:1], v[0:1], v[66:67] neg_lo:[0,1] neg_hi:[0,1]
	v_pk_add_f32 v[2:3], v[2:3], v[68:69] neg_lo:[0,1] neg_hi:[0,1]
	v_pk_add_f32 v[4:5], v[4:5], v[70:71] neg_lo:[0,1] neg_hi:[0,1]
	v_pk_add_f32 v[6:7], v[6:7], v[72:73] neg_lo:[0,1] neg_hi:[0,1]
	s_nop 0
	v_cvt_pk_f16_f32 v78, v0, v1
	v_cvt_pk_f16_f32 v79, v2, v3
	v_cvt_pk_f16_f32 v80, v4, v5
	v_cvt_pk_f16_f32 v81, v6, v7
	global_store_dwordx4 v[88:89], v[74:77], off offset:896
	s_waitcnt vmcnt(48)
	v_mfma_f32_16x16x32_f16 a[8:11], v[74:77], a[128:131], a[8:11]
	v_mfma_f32_16x16x32_f16 a[8:11], v[78:81], a[128:131], a[8:11]
	v_mfma_f32_16x16x32_f16 a[8:11], v[74:77], a[132:135], a[8:11]
	v_mfma_f32_16x16x32_f16 a[4:7], v[74:77], a[136:139], a[4:7]
	v_mfma_f32_16x16x32_f16 a[4:7], v[78:81], a[136:139], a[4:7]
	v_mfma_f32_16x16x32_f16 a[4:7], v[74:77], a[140:143], a[4:7]
	v_mfma_f32_16x16x32_f16 a[0:3], v[74:77], a[144:147], a[0:3]
	v_mfma_f32_16x16x32_f16 a[0:3], v[78:81], a[144:147], a[0:3]
	v_mfma_f32_16x16x32_f16 a[0:3], v[74:77], a[148:151], a[0:3]
	global_load_dwordx4 a[128:131], v[90:91], off offset:1280
	global_load_dwordx4 a[132:135], v[92:93], off offset:1280
	global_load_dwordx4 a[136:139], v[94:95], off offset:1280
	global_load_dwordx4 a[140:143], v[96:97], off offset:1280
	global_load_dwordx4 a[144:147], v[98:99], off offset:1280
	global_load_dwordx4 a[148:151], v[100:101], off offset:1280
	s_waitcnt vmcnt(54)
	v_accvgpr_read_b32 v0, a72
	v_accvgpr_read_b32 v1, a73
	v_accvgpr_read_b32 v2, a74
	v_accvgpr_read_b32 v3, a75
	v_accvgpr_read_b32 v4, a76
	v_accvgpr_read_b32 v5, a77
	v_accvgpr_read_b32 v6, a78
	v_accvgpr_read_b32 v7, a79
	global_load_dwordx4 a[72:75], v[22:23], off offset:2944
	global_load_dwordx4 a[76:79], v[22:23], off offset:2960
	v_pk_mul_f32 v[0:1], v[28:29], v[0:1]
	v_pk_mul_f32 v[2:3], v[28:29], v[2:3]
	v_pk_mul_f32 v[4:5], v[28:29], v[4:5]
	v_pk_mul_f32 v[6:7], v[28:29], v[6:7]
	s_waitcnt lgkmcnt(0)
	v_pk_mul_f32 v[0:1], v[0:1], v[32:33]
	v_pk_mul_f32 v[2:3], v[2:3], v[34:35]
	v_pk_mul_f32 v[4:5], v[4:5], v[36:37]
	v_pk_mul_f32 v[6:7], v[6:7], v[38:39]
	v_pk_add_f32 v[40:41], v[40:41], 1.0 op_sel_hi:[1,0]
	v_pk_add_f32 v[42:43], v[42:43], 1.0 op_sel_hi:[1,0]
	v_pk_add_f32 v[44:45], v[44:45], 1.0 op_sel_hi:[1,0]
	v_pk_add_f32 v[46:47], v[46:47], 1.0 op_sel_hi:[1,0]
	v_pk_fma_f32 v[0:1], v[0:1], v[40:41], v[58:59]
	v_pk_fma_f32 v[2:3], v[2:3], v[42:43], v[60:61]
	v_pk_fma_f32 v[4:5], v[4:5], v[44:45], v[62:63]
	v_pk_fma_f32 v[6:7], v[6:7], v[46:47], v[64:65]
	ds_read_b128 v[32:35], v102 offset:2048
	ds_read_b128 v[36:39], v102 offset:2064
	ds_read_b128 v[40:43], v102 offset:6144
	ds_read_b128 v[44:47], v102 offset:6160
	ds_read_b128 v[58:61], v102 offset:10240
	ds_read_b128 v[62:65], v102 offset:10256
	v_cvt_pk_f16_f32 v74, v0, v1
	v_cvt_pk_f16_f32 v75, v2, v3
	v_cvt_pk_f16_f32 v76, v4, v5
	v_cvt_pk_f16_f32 v77, v6, v7
	v_cvt_f32_f16_e32 v66, v74
	v_cvt_f32_f16_sdwa v67, v74 dst_sel:DWORD dst_unused:UNUSED_PAD src0_sel:WORD_1
	v_cvt_f32_f16_e32 v68, v75
	v_cvt_f32_f16_sdwa v69, v75 dst_sel:DWORD dst_unused:UNUSED_PAD src0_sel:WORD_1
	v_cvt_f32_f16_e32 v70, v76
	v_cvt_f32_f16_sdwa v71, v76 dst_sel:DWORD dst_unused:UNUSED_PAD src0_sel:WORD_1
	v_cvt_f32_f16_e32 v72, v77
	v_cvt_f32_f16_sdwa v73, v77 dst_sel:DWORD dst_unused:UNUSED_PAD src0_sel:WORD_1
	v_pk_add_f32 v[0:1], v[0:1], v[66:67] neg_lo:[0,1] neg_hi:[0,1]
	v_pk_add_f32 v[2:3], v[2:3], v[68:69] neg_lo:[0,1] neg_hi:[0,1]
	v_pk_add_f32 v[4:5], v[4:5], v[70:71] neg_lo:[0,1] neg_hi:[0,1]
	v_pk_add_f32 v[6:7], v[6:7], v[72:73] neg_lo:[0,1] neg_hi:[0,1]
	s_nop 0
	v_cvt_pk_f16_f32 v78, v0, v1
	v_cvt_pk_f16_f32 v79, v2, v3
	v_cvt_pk_f16_f32 v80, v4, v5
	v_cvt_pk_f16_f32 v81, v6, v7
	global_store_dwordx4 v[88:89], v[74:77], off offset:960
	s_waitcnt vmcnt(48)
	v_mfma_f32_16x16x32_f16 a[8:11], v[74:77], a[152:155], a[8:11]
	v_mfma_f32_16x16x32_f16 a[8:11], v[78:81], a[152:155], a[8:11]
	v_mfma_f32_16x16x32_f16 a[8:11], v[74:77], a[156:159], a[8:11]
	v_mfma_f32_16x16x32_f16 a[4:7], v[74:77], a[160:163], a[4:7]
	v_mfma_f32_16x16x32_f16 a[4:7], v[78:81], a[160:163], a[4:7]
	v_mfma_f32_16x16x32_f16 a[4:7], v[74:77], a[164:167], a[4:7]
	v_mfma_f32_16x16x32_f16 a[0:3], v[74:77], a[168:171], a[0:3]
	v_mfma_f32_16x16x32_f16 a[0:3], v[78:81], a[168:171], a[0:3]
	v_mfma_f32_16x16x32_f16 a[0:3], v[74:77], a[172:175], a[0:3]
	global_load_dwordx4 a[152:155], v[90:91], off offset:1344
	global_load_dwordx4 a[156:159], v[92:93], off offset:1344
	global_load_dwordx4 a[160:163], v[94:95], off offset:1344
	global_load_dwordx4 a[164:167], v[96:97], off offset:1344
	global_load_dwordx4 a[168:171], v[98:99], off offset:1344
	global_load_dwordx4 a[172:175], v[100:101], off offset:1344
	s_waitcnt vmcnt(54)
; DI f4 mfma16(h8 a, h8 b, f4 c) { return __builtin_amdgcn_mfma_f32_16x16x32_f16(a, b, c, 0, 0, 0); }
; DI void row2_phase(const Params& P, int l, int r_begin, char* smem) {
;     ...
;     for (int kk = 0; kk < 32; kk++) {
;       const int k0 = kk * 32;
;       float x[8], g[8], s1[8], s0[8];
;       *(float4*)&x[0] = *(const float4*)(xm + k0); *(float4*)&x[4] = *(const float4*)(xm + k0 + 4);
;       *(float4*)&g[0] = *(const float4*)(gam + fq * 8 + k0); *(float4*)&g[4] = *(const float4*)(gam + fq * 8 + k0 + 4);
;       *(float4*)&s1[0] = *(const float4*)(sc + k0); *(float4*)&s1[4] = *(const float4*)(sc + k0 + 4);
;       *(float4*)&s0[0] = *(const float4*)(sh + k0); *(float4*)&s0[4] = *(const float4*)(sh + k0 + 4);
;       h8 hi, lo;
; #pragma unroll
;       for (int i = 0; i < 8; i++) {
;         float v = x[i] * rstd * g[i] * (1.f + s1[i]) + s0[i];
;         hi[i] = (half_t)v; lo[i] = (half_t)(v - (float)hi[i]);
;       }
;       *(h8*)(hxo + k0) = hi;
; #pragma unroll
;       for (int n3 = 0; n3 < 3; n3++) {
;         h8 bh = *(const h8*)(Whi + (size_t)(n3 * 16 + fr) * 1024 + k0 + fq * 8);
;         h8 bl = *(const h8*)(Wlo + (size_t)(n3 * 16 + fr) * 1024 + k0 + fq * 8);
;         acc[n3] = mfma16(hi, bh, acc[n3]); acc[n3] = mfma16(lo, bh, acc[n3]); acc[n3] = mfma16(hi, bl, acc[n3]);
;       }
	v_accvgpr_read_b32 v0, a16
	v_accvgpr_read_b32 v1, a17
	v_accvgpr_read_b32 v2, a18
	v_accvgpr_read_b32 v3, a19
	v_accvgpr_read_b32 v4, a20
	v_accvgpr_read_b32 v5, a21
	v_accvgpr_read_b32 v6, a22
	v_accvgpr_read_b32 v7, a23
	global_load_dwordx4 a[16:19], v[22:23], off offset:3072
	global_load_dwordx4 a[20:23], v[22:23], off offset:3088
	v_pk_mul_f32 v[0:1], v[28:29], v[0:1]
	v_pk_mul_f32 v[2:3], v[28:29], v[2:3]
	v_pk_mul_f32 v[4:5], v[28:29], v[4:5]
	v_pk_mul_f32 v[6:7], v[28:29], v[6:7]
	s_waitcnt lgkmcnt(0)
	v_pk_mul_f32 v[0:1], v[0:1], v[32:33]
	v_pk_mul_f32 v[2:3], v[2:3], v[34:35]
	v_pk_mul_f32 v[4:5], v[4:5], v[36:37]
	v_pk_mul_f32 v[6:7], v[6:7], v[38:39]
	v_pk_add_f32 v[40:41], v[40:41], 1.0 op_sel_hi:[1,0]
	v_pk_add_f32 v[42:43], v[42:43], 1.0 op_sel_hi:[1,0]
	v_pk_add_f32 v[44:45], v[44:45], 1.0 op_sel_hi:[1,0]
	v_pk_add_f32 v[46:47], v[46:47], 1.0 op_sel_hi:[1,0]
	v_pk_fma_f32 v[0:1], v[0:1], v[40:41], v[58:59]
	v_pk_fma_f32 v[2:3], v[2:3], v[42:43], v[60:61]
	v_pk_fma_f32 v[4:5], v[4:5], v[44:45], v[62:63]
	v_pk_fma_f32 v[6:7], v[6:7], v[46:47], v[64:65]
	ds_read_b128 v[32:35], v102 offset:2176
	ds_read_b128 v[36:39], v102 offset:2192
	ds_read_b128 v[40:43], v102 offset:6272
	ds_read_b128 v[44:47], v102 offset:6288
	ds_read_b128 v[58:61], v102 offset:10368
	ds_read_b128 v[62:65], v102 offset:10384
	v_cvt_pk_f16_f32 v74, v0, v1
	v_cvt_pk_f16_f32 v75, v2, v3
	v_cvt_pk_f16_f32 v76, v4, v5
	v_cvt_pk_f16_f32 v77, v6, v7
	v_cvt_f32_f16_e32 v66, v74
	v_cvt_f32_f16_sdwa v67, v74 dst_sel:DWORD dst_unused:UNUSED_PAD src0_sel:WORD_1
	v_cvt_f32_f16_e32 v68, v75
	v_cvt_f32_f16_sdwa v69, v75 dst_sel:DWORD dst_unused:UNUSED_PAD src0_sel:WORD_1
	v_cvt_f32_f16_e32 v70, v76
	v_cvt_f32_f16_sdwa v71, v76 dst_sel:DWORD dst_unused:UNUSED_PAD src0_sel:WORD_1
	v_cvt_f32_f16_e32 v72, v77
	v_cvt_f32_f16_sdwa v73, v77 dst_sel:DWORD dst_unused:UNUSED_PAD src0_sel:WORD_1
	v_pk_add_f32 v[0:1], v[0:1], v[66:67] neg_lo:[0,1] neg_hi:[0,1]
	v_pk_add_f32 v[2:3], v[2:3], v[68:69] neg_lo:[0,1] neg_hi:[0,1]
	v_pk_add_f32 v[4:5], v[4:5], v[70:71] neg_lo:[0,1] neg_hi:[0,1]
	v_pk_add_f32 v[6:7], v[6:7], v[72:73] neg_lo:[0,1] neg_hi:[0,1]
	s_nop 0
	v_cvt_pk_f16_f32 v78, v0, v1
	v_cvt_pk_f16_f32 v79, v2, v3
	v_cvt_pk_f16_f32 v80, v4, v5
	v_cvt_pk_f16_f32 v81, v6, v7
	global_store_dwordx4 v[88:89], v[74:77], off offset:1024
	s_waitcnt vmcnt(48)
	v_mfma_f32_16x16x32_f16 a[8:11], v[74:77], a[204:207], a[8:11]
	v_mfma_f32_16x16x32_f16 a[8:11], v[78:81], a[204:207], a[8:11]
	v_mfma_f32_16x16x32_f16 a[8:11], v[74:77], a[208:211], a[8:11]
	v_mfma_f32_16x16x32_f16 a[4:7], v[74:77], a[212:215], a[4:7]
	v_mfma_f32_16x16x32_f16 a[4:7], v[78:81], a[212:215], a[4:7]
	v_mfma_f32_16x16x32_f16 a[4:7], v[74:77], a[216:219], a[4:7]
	v_mfma_f32_16x16x32_f16 a[0:3], v[74:77], a[220:223], a[0:3]
	v_mfma_f32_16x16x32_f16 a[0:3], v[78:81], a[220:223], a[0:3]
	v_mfma_f32_16x16x32_f16 a[0:3], v[74:77], a[224:227], a[0:3]
	global_load_dwordx4 a[204:207], v[90:91], off offset:1408
	global_load_dwordx4 a[208:211], v[92:93], off offset:1408
	global_load_dwordx4 a[212:215], v[94:95], off offset:1408
	global_load_dwordx4 a[216:219], v[96:97], off offset:1408
	global_load_dwordx4 a[220:223], v[98:99], off offset:1408
	global_load_dwordx4 a[224:227], v[100:101], off offset:1408
	s_waitcnt vmcnt(54)
	v_accvgpr_read_b32 v0, a24
	v_accvgpr_read_b32 v1, a25
	v_accvgpr_read_b32 v2, a26
	v_accvgpr_read_b32 v3, a27
	v_accvgpr_read_b32 v4, a28
	v_accvgpr_read_b32 v5, a29
	v_accvgpr_read_b32 v6, a30
	v_accvgpr_read_b32 v7, a31
	global_load_dwordx4 a[24:27], v[22:23], off offset:3200
	global_load_dwordx4 a[28:31], v[22:23], off offset:3216
	v_pk_mul_f32 v[0:1], v[28:29], v[0:1]
	v_pk_mul_f32 v[2:3], v[28:29], v[2:3]
	v_pk_mul_f32 v[4:5], v[28:29], v[4:5]
	v_pk_mul_f32 v[6:7], v[28:29], v[6:7]
	s_waitcnt lgkmcnt(0)
	v_pk_mul_f32 v[0:1], v[0:1], v[32:33]
	v_pk_mul_f32 v[2:3], v[2:3], v[34:35]
	v_pk_mul_f32 v[4:5], v[4:5], v[36:37]
	v_pk_mul_f32 v[6:7], v[6:7], v[38:39]
	v_pk_add_f32 v[40:41], v[40:41], 1.0 op_sel_hi:[1,0]
	v_pk_add_f32 v[42:43], v[42:43], 1.0 op_sel_hi:[1,0]
	v_pk_add_f32 v[44:45], v[44:45], 1.0 op_sel_hi:[1,0]
	v_pk_add_f32 v[46:47], v[46:47], 1.0 op_sel_hi:[1,0]
	v_pk_fma_f32 v[0:1], v[0:1], v[40:41], v[58:59]
	v_pk_fma_f32 v[2:3], v[2:3], v[42:43], v[60:61]
	v_pk_fma_f32 v[4:5], v[4:5], v[44:45], v[62:63]
	v_pk_fma_f32 v[6:7], v[6:7], v[46:47], v[64:65]
	ds_read_b128 v[32:35], v102 offset:2304
	ds_read_b128 v[36:39], v102 offset:2320
	ds_read_b128 v[40:43], v102 offset:6400
	ds_read_b128 v[44:47], v102 offset:6416
	ds_read_b128 v[58:61], v102 offset:10496
	ds_read_b128 v[62:65], v102 offset:10512
	v_cvt_pk_f16_f32 v74, v0, v1
	v_cvt_pk_f16_f32 v75, v2, v3
	v_cvt_pk_f16_f32 v76, v4, v5
	v_cvt_pk_f16_f32 v77, v6, v7
	v_cvt_f32_f16_e32 v66, v74
	v_cvt_f32_f16_sdwa v67, v74 dst_sel:DWORD dst_unused:UNUSED_PAD src0_sel:WORD_1
	v_cvt_f32_f16_e32 v68, v75
	v_cvt_f32_f16_sdwa v69, v75 dst_sel:DWORD dst_unused:UNUSED_PAD src0_sel:WORD_1
	v_cvt_f32_f16_e32 v70, v76
	v_cvt_f32_f16_sdwa v71, v76 dst_sel:DWORD dst_unused:UNUSED_PAD src0_sel:WORD_1
	v_cvt_f32_f16_e32 v72, v77
	v_cvt_f32_f16_sdwa v73, v77 dst_sel:DWORD dst_unused:UNUSED_PAD src0_sel:WORD_1
	v_pk_add_f32 v[0:1], v[0:1], v[66:67] neg_lo:[0,1] neg_hi:[0,1]
	v_pk_add_f32 v[2:3], v[2:3], v[68:69] neg_lo:[0,1] neg_hi:[0,1]
	v_pk_add_f32 v[4:5], v[4:5], v[70:71] neg_lo:[0,1] neg_hi:[0,1]
	v_pk_add_f32 v[6:7], v[6:7], v[72:73] neg_lo:[0,1] neg_hi:[0,1]
	s_nop 0
	v_cvt_pk_f16_f32 v78, v0, v1
	v_cvt_pk_f16_f32 v79, v2, v3
	v_cvt_pk_f16_f32 v80, v4, v5
	v_cvt_pk_f16_f32 v81, v6, v7
	global_store_dwordx4 v[88:89], v[74:77], off offset:1088
	s_waitcnt vmcnt(48)
; DI f4 mfma16(h8 a, h8 b, f4 c) { return __builtin_amdgcn_mfma_f32_16x16x32_f16(a, b, c, 0, 0, 0); }
; DI void row2_phase(const Params& P, int l, int r_begin, char* smem) {
;     ...
;     for (int kk = 0; kk < 32; kk++) {
;       const int k0 = kk * 32;
;       float x[8], g[8], s1[8], s0[8];
;       *(float4*)&x[0] = *(const float4*)(xm + k0); *(float4*)&x[4] = *(const float4*)(xm + k0 + 4);
;       *(float4*)&g[0] = *(const float4*)(gam + fq * 8 + k0); *(float4*)&g[4] = *(const float4*)(gam + fq * 8 + k0 + 4);
;       *(float4*)&s1[0] = *(const float4*)(sc + k0); *(float4*)&s1[4] = *(const float4*)(sc + k0 + 4);
;       *(float4*)&s0[0] = *(const float4*)(sh + k0); *(float4*)&s0[4] = *(const float4*)(sh + k0 + 4);
;       h8 hi, lo;
; #pragma unroll
;       for (int i = 0; i < 8; i++) {
;         float v = x[i] * rstd * g[i] * (1.f + s1[i]) + s0[i];
;         hi[i] = (half_t)v; lo[i] = (half_t)(v - (float)hi[i]);
;       }
;       *(h8*)(hxo + k0) = hi;
; #pragma unroll
;       for (int n3 = 0; n3 < 3; n3++) {
;         h8 bh = *(const h8*)(Whi + (size_t)(n3 * 16 + fr) * 1024 + k0 + fq * 8);
;         h8 bl = *(const h8*)(Wlo + (size_t)(n3 * 16 + fr) * 1024 + k0 + fq * 8);
;         acc[n3] = mfma16(hi, bh, acc[n3]); acc[n3] = mfma16(lo, bh, acc[n3]); acc[n3] = mfma16(hi, bl, acc[n3]);
;       }
	v_mfma_f32_16x16x32_f16 a[8:11], v[74:77], a[228:231], a[8:11]
	v_mfma_f32_16x16x32_f16 a[8:11], v[78:81], a[228:231], a[8:11]
	v_mfma_f32_16x16x32_f16 a[8:11], v[74:77], a[232:235], a[8:11]
	v_mfma_f32_16x16x32_f16 a[4:7], v[74:77], a[236:239], a[4:7]
	v_mfma_f32_16x16x32_f16 a[4:7], v[78:81], a[236:239], a[4:7]
	v_mfma_f32_16x16x32_f16 a[4:7], v[74:77], a[240:243], a[4:7]
	v_mfma_f32_16x16x32_f16 a[0:3], v[74:77], a[244:247], a[0:3]
	v_mfma_f32_16x16x32_f16 a[0:3], v[78:81], a[244:247], a[0:3]
	v_mfma_f32_16x16x32_f16 a[0:3], v[74:77], a[248:251], a[0:3]
	global_load_dwordx4 a[228:231], v[90:91], off offset:1472
	global_load_dwordx4 a[232:235], v[92:93], off offset:1472
	global_load_dwordx4 a[236:239], v[94:95], off offset:1472
	global_load_dwordx4 a[240:243], v[96:97], off offset:1472
	global_load_dwordx4 a[244:247], v[98:99], off offset:1472
	global_load_dwordx4 a[248:251], v[100:101], off offset:1472
	s_waitcnt vmcnt(54)
	v_accvgpr_read_b32 v0, a32
	v_accvgpr_read_b32 v1, a33
	v_accvgpr_read_b32 v2, a34
	v_accvgpr_read_b32 v3, a35
	v_accvgpr_read_b32 v4, a36
	v_accvgpr_read_b32 v5, a37
	v_accvgpr_read_b32 v6, a38
	v_accvgpr_read_b32 v7, a39
	global_load_dwordx4 a[32:35], v[22:23], off offset:3328
	global_load_dwordx4 a[36:39], v[22:23], off offset:3344
	v_pk_mul_f32 v[0:1], v[28:29], v[0:1]
	v_pk_mul_f32 v[2:3], v[28:29], v[2:3]
	v_pk_mul_f32 v[4:5], v[28:29], v[4:5]
	v_pk_mul_f32 v[6:7], v[28:29], v[6:7]
	s_waitcnt lgkmcnt(0)
	v_pk_mul_f32 v[0:1], v[0:1], v[32:33]
	v_pk_mul_f32 v[2:3], v[2:3], v[34:35]
	v_pk_mul_f32 v[4:5], v[4:5], v[36:37]
	v_pk_mul_f32 v[6:7], v[6:7], v[38:39]
	v_pk_add_f32 v[40:41], v[40:41], 1.0 op_sel_hi:[1,0]
	v_pk_add_f32 v[42:43], v[42:43], 1.0 op_sel_hi:[1,0]
	v_pk_add_f32 v[44:45], v[44:45], 1.0 op_sel_hi:[1,0]
	v_pk_add_f32 v[46:47], v[46:47], 1.0 op_sel_hi:[1,0]
	v_pk_fma_f32 v[0:1], v[0:1], v[40:41], v[58:59]
	v_pk_fma_f32 v[2:3], v[2:3], v[42:43], v[60:61]
	v_pk_fma_f32 v[4:5], v[4:5], v[44:45], v[62:63]
	v_pk_fma_f32 v[6:7], v[6:7], v[46:47], v[64:65]
	ds_read_b128 v[32:35], v102 offset:2432
	ds_read_b128 v[36:39], v102 offset:2448
	ds_read_b128 v[40:43], v102 offset:6528
	ds_read_b128 v[44:47], v102 offset:6544
	ds_read_b128 v[58:61], v102 offset:10624
	ds_read_b128 v[62:65], v102 offset:10640
	v_cvt_pk_f16_f32 v74, v0, v1
	v_cvt_pk_f16_f32 v75, v2, v3
	v_cvt_pk_f16_f32 v76, v4, v5
	v_cvt_pk_f16_f32 v77, v6, v7
	v_cvt_f32_f16_e32 v66, v74
	v_cvt_f32_f16_sdwa v67, v74 dst_sel:DWORD dst_unused:UNUSED_PAD src0_sel:WORD_1
	v_cvt_f32_f16_e32 v68, v75
	v_cvt_f32_f16_sdwa v69, v75 dst_sel:DWORD dst_unused:UNUSED_PAD src0_sel:WORD_1
	v_cvt_f32_f16_e32 v70, v76
	v_cvt_f32_f16_sdwa v71, v76 dst_sel:DWORD dst_unused:UNUSED_PAD src0_sel:WORD_1
	v_cvt_f32_f16_e32 v72, v77
	v_cvt_f32_f16_sdwa v73, v77 dst_sel:DWORD dst_unused:UNUSED_PAD src0_sel:WORD_1
	v_pk_add_f32 v[0:1], v[0:1], v[66:67] neg_lo:[0,1] neg_hi:[0,1]
	v_pk_add_f32 v[2:3], v[2:3], v[68:69] neg_lo:[0,1] neg_hi:[0,1]
	v_pk_add_f32 v[4:5], v[4:5], v[70:71] neg_lo:[0,1] neg_hi:[0,1]
	v_pk_add_f32 v[6:7], v[6:7], v[72:73] neg_lo:[0,1] neg_hi:[0,1]
	s_nop 0
	v_cvt_pk_f16_f32 v78, v0, v1
	v_cvt_pk_f16_f32 v79, v2, v3
	v_cvt_pk_f16_f32 v80, v4, v5
	v_cvt_pk_f16_f32 v81, v6, v7
	global_store_dwordx4 v[88:89], v[74:77], off offset:1152
	s_waitcnt vmcnt(48)
	v_mfma_f32_16x16x32_f16 a[8:11], v[74:77], a[80:83], a[8:11]
	v_mfma_f32_16x16x32_f16 a[8:11], v[78:81], a[80:83], a[8:11]
	v_mfma_f32_16x16x32_f16 a[8:11], v[74:77], a[84:87], a[8:11]
	v_mfma_f32_16x16x32_f16 a[4:7], v[74:77], a[88:91], a[4:7]
	v_mfma_f32_16x16x32_f16 a[4:7], v[78:81], a[88:91], a[4:7]
	v_mfma_f32_16x16x32_f16 a[4:7], v[74:77], a[92:95], a[4:7]
	v_mfma_f32_16x16x32_f16 a[0:3], v[74:77], a[96:99], a[0:3]
	v_mfma_f32_16x16x32_f16 a[0:3], v[78:81], a[96:99], a[0:3]
	v_mfma_f32_16x16x32_f16 a[0:3], v[74:77], a[100:103], a[0:3]
	global_load_dwordx4 a[80:83], v[90:91], off offset:1536
	global_load_dwordx4 a[84:87], v[92:93], off offset:1536
	global_load_dwordx4 a[88:91], v[94:95], off offset:1536
	global_load_dwordx4 a[92:95], v[96:97], off offset:1536
	global_load_dwordx4 a[96:99], v[98:99], off offset:1536
	global_load_dwordx4 a[100:103], v[100:101], off offset:1536
	s_waitcnt vmcnt(54)
	v_accvgpr_read_b32 v0, a40
	v_accvgpr_read_b32 v1, a41
	v_accvgpr_read_b32 v2, a42
	v_accvgpr_read_b32 v3, a43
	v_accvgpr_read_b32 v4, a44
	v_accvgpr_read_b32 v5, a45
	v_accvgpr_read_b32 v6, a46
	v_accvgpr_read_b32 v7, a47
	global_load_dwordx4 a[40:43], v[22:23], off offset:3456
	global_load_dwordx4 a[44:47], v[22:23], off offset:3472
	v_pk_mul_f32 v[0:1], v[28:29], v[0:1]
	v_pk_mul_f32 v[2:3], v[28:29], v[2:3]
	v_pk_mul_f32 v[4:5], v[28:29], v[4:5]
	v_pk_mul_f32 v[6:7], v[28:29], v[6:7]
	s_waitcnt lgkmcnt(0)
; DI f4 mfma16(h8 a, h8 b, f4 c) { return __builtin_amdgcn_mfma_f32_16x16x32_f16(a, b, c, 0, 0, 0); }
; DI void row2_phase(const Params& P, int l, int r_begin, char* smem) {
;     ...
;     for (int kk = 0; kk < 32; kk++) {
;       const int k0 = kk * 32;
;       float x[8], g[8], s1[8], s0[8];
;       *(float4*)&x[0] = *(const float4*)(xm + k0); *(float4*)&x[4] = *(const float4*)(xm + k0 + 4);
;       *(float4*)&g[0] = *(const float4*)(gam + fq * 8 + k0); *(float4*)&g[4] = *(const float4*)(gam + fq * 8 + k0 + 4);
;       *(float4*)&s1[0] = *(const float4*)(sc + k0); *(float4*)&s1[4] = *(const float4*)(sc + k0 + 4);
;       *(float4*)&s0[0] = *(const float4*)(sh + k0); *(float4*)&s0[4] = *(const float4*)(sh + k0 + 4);
;       h8 hi, lo;
; #pragma unroll
;       for (int i = 0; i < 8; i++) {
;         float v = x[i] * rstd * g[i] * (1.f + s1[i]) + s0[i];
;         hi[i] = (half_t)v; lo[i] = (half_t)(v - (float)hi[i]);
;       }
;       *(h8*)(hxo + k0) = hi;
; #pragma unroll
;       for (int n3 = 0; n3 < 3; n3++) {
;         h8 bh = *(const h8*)(Whi + (size_t)(n3 * 16 + fr) * 1024 + k0 + fq * 8);
;         h8 bl = *(const h8*)(Wlo + (size_t)(n3 * 16 + fr) * 1024 + k0 + fq * 8);
;         acc[n3] = mfma16(hi, bh, acc[n3]); acc[n3] = mfma16(lo, bh, acc[n3]); acc[n3] = mfma16(hi, bl, acc[n3]);
;       }
	v_pk_mul_f32 v[0:1], v[0:1], v[32:33]
	v_pk_mul_f32 v[2:3], v[2:3], v[34:35]
	v_pk_mul_f32 v[4:5], v[4:5], v[36:37]
	v_pk_mul_f32 v[6:7], v[6:7], v[38:39]
	v_pk_add_f32 v[40:41], v[40:41], 1.0 op_sel_hi:[1,0]
	v_pk_add_f32 v[42:43], v[42:43], 1.0 op_sel_hi:[1,0]
	v_pk_add_f32 v[44:45], v[44:45], 1.0 op_sel_hi:[1,0]
	v_pk_add_f32 v[46:47], v[46:47], 1.0 op_sel_hi:[1,0]
	v_pk_fma_f32 v[0:1], v[0:1], v[40:41], v[58:59]
	v_pk_fma_f32 v[2:3], v[2:3], v[42:43], v[60:61]
	v_pk_fma_f32 v[4:5], v[4:5], v[44:45], v[62:63]
	v_pk_fma_f32 v[6:7], v[6:7], v[46:47], v[64:65]
	ds_read_b128 v[32:35], v102 offset:2560
	ds_read_b128 v[36:39], v102 offset:2576
	ds_read_b128 v[40:43], v102 offset:6656
	ds_read_b128 v[44:47], v102 offset:6672
	ds_read_b128 v[58:61], v102 offset:10752
	ds_read_b128 v[62:65], v102 offset:10768
	v_cvt_pk_f16_f32 v74, v0, v1
	v_cvt_pk_f16_f32 v75, v2, v3
	v_cvt_pk_f16_f32 v76, v4, v5
	v_cvt_pk_f16_f32 v77, v6, v7
	v_cvt_f32_f16_e32 v66, v74
	v_cvt_f32_f16_sdwa v67, v74 dst_sel:DWORD dst_unused:UNUSED_PAD src0_sel:WORD_1
	v_cvt_f32_f16_e32 v68, v75
	v_cvt_f32_f16_sdwa v69, v75 dst_sel:DWORD dst_unused:UNUSED_PAD src0_sel:WORD_1
	v_cvt_f32_f16_e32 v70, v76
	v_cvt_f32_f16_sdwa v71, v76 dst_sel:DWORD dst_unused:UNUSED_PAD src0_sel:WORD_1
	v_cvt_f32_f16_e32 v72, v77
	v_cvt_f32_f16_sdwa v73, v77 dst_sel:DWORD dst_unused:UNUSED_PAD src0_sel:WORD_1
	v_pk_add_f32 v[0:1], v[0:1], v[66:67] neg_lo:[0,1] neg_hi:[0,1]
	v_pk_add_f32 v[2:3], v[2:3], v[68:69] neg_lo:[0,1] neg_hi:[0,1]
	v_pk_add_f32 v[4:5], v[4:5], v[70:71] neg_lo:[0,1] neg_hi:[0,1]
	v_pk_add_f32 v[6:7], v[6:7], v[72:73] neg_lo:[0,1] neg_hi:[0,1]
	s_nop 0
	v_cvt_pk_f16_f32 v78, v0, v1
	v_cvt_pk_f16_f32 v79, v2, v3
	v_cvt_pk_f16_f32 v80, v4, v5
	v_cvt_pk_f16_f32 v81, v6, v7
	global_store_dwordx4 v[88:89], v[74:77], off offset:1216
	s_waitcnt vmcnt(48)
	v_mfma_f32_16x16x32_f16 a[8:11], v[74:77], a[104:107], a[8:11]
	v_mfma_f32_16x16x32_f16 a[8:11], v[78:81], a[104:107], a[8:11]
	v_mfma_f32_16x16x32_f16 a[8:11], v[74:77], a[108:111], a[8:11]
	v_mfma_f32_16x16x32_f16 a[4:7], v[74:77], a[112:115], a[4:7]
	v_mfma_f32_16x16x32_f16 a[4:7], v[78:81], a[112:115], a[4:7]
	v_mfma_f32_16x16x32_f16 a[4:7], v[74:77], a[116:119], a[4:7]
	v_mfma_f32_16x16x32_f16 a[0:3], v[74:77], a[120:123], a[0:3]
	v_mfma_f32_16x16x32_f16 a[0:3], v[78:81], a[120:123], a[0:3]
	v_mfma_f32_16x16x32_f16 a[0:3], v[74:77], a[124:127], a[0:3]
	global_load_dwordx4 a[104:107], v[90:91], off offset:1600
	global_load_dwordx4 a[108:111], v[92:93], off offset:1600
	global_load_dwordx4 a[112:115], v[94:95], off offset:1600
	global_load_dwordx4 a[116:119], v[96:97], off offset:1600
	global_load_dwordx4 a[120:123], v[98:99], off offset:1600
	global_load_dwordx4 a[124:127], v[100:101], off offset:1600
	s_waitcnt vmcnt(54)
	v_accvgpr_read_b32 v0, a48
	v_accvgpr_read_b32 v1, a49
	v_accvgpr_read_b32 v2, a50
	v_accvgpr_read_b32 v3, a51
	v_accvgpr_read_b32 v4, a52
	v_accvgpr_read_b32 v5, a53
	v_accvgpr_read_b32 v6, a54
	v_accvgpr_read_b32 v7, a55
	global_load_dwordx4 a[48:51], v[22:23], off offset:3584
	global_load_dwordx4 a[52:55], v[22:23], off offset:3600
	v_pk_mul_f32 v[0:1], v[28:29], v[0:1]
	v_pk_mul_f32 v[2:3], v[28:29], v[2:3]
	v_pk_mul_f32 v[4:5], v[28:29], v[4:5]
	v_pk_mul_f32 v[6:7], v[28:29], v[6:7]
	s_waitcnt lgkmcnt(0)
	v_pk_mul_f32 v[0:1], v[0:1], v[32:33]
	v_pk_mul_f32 v[2:3], v[2:3], v[34:35]
	v_pk_mul_f32 v[4:5], v[4:5], v[36:37]
	v_pk_mul_f32 v[6:7], v[6:7], v[38:39]
	v_pk_add_f32 v[40:41], v[40:41], 1.0 op_sel_hi:[1,0]
	v_pk_add_f32 v[42:43], v[42:43], 1.0 op_sel_hi:[1,0]
	v_pk_add_f32 v[44:45], v[44:45], 1.0 op_sel_hi:[1,0]
	v_pk_add_f32 v[46:47], v[46:47], 1.0 op_sel_hi:[1,0]
	v_pk_fma_f32 v[0:1], v[0:1], v[40:41], v[58:59]
	v_pk_fma_f32 v[2:3], v[2:3], v[42:43], v[60:61]
	v_pk_fma_f32 v[4:5], v[4:5], v[44:45], v[62:63]
	v_pk_fma_f32 v[6:7], v[6:7], v[46:47], v[64:65]
	ds_read_b128 v[32:35], v102 offset:2688
	ds_read_b128 v[36:39], v102 offset:2704
	ds_read_b128 v[40:43], v102 offset:6784
	ds_read_b128 v[44:47], v102 offset:6800
	ds_read_b128 v[58:61], v102 offset:10880
	ds_read_b128 v[62:65], v102 offset:10896
	v_cvt_pk_f16_f32 v74, v0, v1
	v_cvt_pk_f16_f32 v75, v2, v3
	v_cvt_pk_f16_f32 v76, v4, v5
	v_cvt_pk_f16_f32 v77, v6, v7
	v_cvt_f32_f16_e32 v66, v74
	v_cvt_f32_f16_sdwa v67, v74 dst_sel:DWORD dst_unused:UNUSED_PAD src0_sel:WORD_1
	v_cvt_f32_f16_e32 v68, v75
	v_cvt_f32_f16_sdwa v69, v75 dst_sel:DWORD dst_unused:UNUSED_PAD src0_sel:WORD_1
	v_cvt_f32_f16_e32 v70, v76
	v_cvt_f32_f16_sdwa v71, v76 dst_sel:DWORD dst_unused:UNUSED_PAD src0_sel:WORD_1
	v_cvt_f32_f16_e32 v72, v77
	v_cvt_f32_f16_sdwa v73, v77 dst_sel:DWORD dst_unused:UNUSED_PAD src0_sel:WORD_1
	v_pk_add_f32 v[0:1], v[0:1], v[66:67] neg_lo:[0,1] neg_hi:[0,1]
	v_pk_add_f32 v[2:3], v[2:3], v[68:69] neg_lo:[0,1] neg_hi:[0,1]
	v_pk_add_f32 v[4:5], v[4:5], v[70:71] neg_lo:[0,1] neg_hi:[0,1]
	v_pk_add_f32 v[6:7], v[6:7], v[72:73] neg_lo:[0,1] neg_hi:[0,1]
	s_nop 0
	v_cvt_pk_f16_f32 v78, v0, v1
	v_cvt_pk_f16_f32 v79, v2, v3
	v_cvt_pk_f16_f32 v80, v4, v5
	v_cvt_pk_f16_f32 v81, v6, v7
	global_store_dwordx4 v[88:89], v[74:77], off offset:1280
	s_waitcnt vmcnt(48)
	v_mfma_f32_16x16x32_f16 a[8:11], v[74:77], a[128:131], a[8:11]
	v_mfma_f32_16x16x32_f16 a[8:11], v[78:81], a[128:131], a[8:11]
	v_mfma_f32_16x16x32_f16 a[8:11], v[74:77], a[132:135], a[8:11]
	v_mfma_f32_16x16x32_f16 a[4:7], v[74:77], a[136:139], a[4:7]
	v_mfma_f32_16x16x32_f16 a[4:7], v[78:81], a[136:139], a[4:7]
	v_mfma_f32_16x16x32_f16 a[4:7], v[74:77], a[140:143], a[4:7]
	v_mfma_f32_16x16x32_f16 a[0:3], v[74:77], a[144:147], a[0:3]
	v_mfma_f32_16x16x32_f16 a[0:3], v[78:81], a[144:147], a[0:3]
	v_mfma_f32_16x16x32_f16 a[0:3], v[74:77], a[148:151], a[0:3]
	global_load_dwordx4 a[128:131], v[90:91], off offset:1664
	global_load_dwordx4 a[132:135], v[92:93], off offset:1664
	global_load_dwordx4 a[136:139], v[94:95], off offset:1664
	global_load_dwordx4 a[140:143], v[96:97], off offset:1664
	global_load_dwordx4 a[144:147], v[98:99], off offset:1664
	global_load_dwordx4 a[148:151], v[100:101], off offset:1664
	s_waitcnt vmcnt(54)
; DI f4 mfma16(h8 a, h8 b, f4 c) { return __builtin_amdgcn_mfma_f32_16x16x32_f16(a, b, c, 0, 0, 0); }
; DI void row2_phase(const Params& P, int l, int r_begin, char* smem) {
;     ...
;     for (int kk = 0; kk < 32; kk++) {
;       const int k0 = kk * 32;
;       float x[8], g[8], s1[8], s0[8];
;       *(float4*)&x[0] = *(const float4*)(xm + k0); *(float4*)&x[4] = *(const float4*)(xm + k0 + 4);
;       *(float4*)&g[0] = *(const float4*)(gam + fq * 8 + k0); *(float4*)&g[4] = *(const float4*)(gam + fq * 8 + k0 + 4);
;       *(float4*)&s1[0] = *(const float4*)(sc + k0); *(float4*)&s1[4] = *(const float4*)(sc + k0 + 4);
;       *(float4*)&s0[0] = *(const float4*)(sh + k0); *(float4*)&s0[4] = *(const float4*)(sh + k0 + 4);
;       h8 hi, lo;
; #pragma unroll
;       for (int i = 0; i < 8; i++) {
;         float v = x[i] * rstd * g[i] * (1.f + s1[i]) + s0[i];
;         hi[i] = (half_t)v; lo[i] = (half_t)(v - (float)hi[i]);
;       }
;       *(h8*)(hxo + k0) = hi;
; #pragma unroll
;       for (int n3 = 0; n3 < 3; n3++) {
;         h8 bh = *(const h8*)(Whi + (size_t)(n3 * 16 + fr) * 1024 + k0 + fq * 8);
;         h8 bl = *(const h8*)(Wlo + (size_t)(n3 * 16 + fr) * 1024 + k0 + fq * 8);
;         acc[n3] = mfma16(hi, bh, acc[n3]); acc[n3] = mfma16(lo, bh, acc[n3]); acc[n3] = mfma16(hi, bl, acc[n3]);
;       }
	v_accvgpr_read_b32 v0, a56
	v_accvgpr_read_b32 v1, a57
	v_accvgpr_read_b32 v2, a58
	v_accvgpr_read_b32 v3, a59
	v_accvgpr_read_b32 v4, a60
	v_accvgpr_read_b32 v5, a61
	v_accvgpr_read_b32 v6, a62
	v_accvgpr_read_b32 v7, a63
	global_load_dwordx4 a[56:59], v[22:23], off offset:3712
	global_load_dwordx4 a[60:63], v[22:23], off offset:3728
	v_pk_mul_f32 v[0:1], v[28:29], v[0:1]
	v_pk_mul_f32 v[2:3], v[28:29], v[2:3]
	v_pk_mul_f32 v[4:5], v[28:29], v[4:5]
	v_pk_mul_f32 v[6:7], v[28:29], v[6:7]
	s_waitcnt lgkmcnt(0)
	v_pk_mul_f32 v[0:1], v[0:1], v[32:33]
	v_pk_mul_f32 v[2:3], v[2:3], v[34:35]
	v_pk_mul_f32 v[4:5], v[4:5], v[36:37]
	v_pk_mul_f32 v[6:7], v[6:7], v[38:39]
	v_pk_add_f32 v[40:41], v[40:41], 1.0 op_sel_hi:[1,0]
	v_pk_add_f32 v[42:43], v[42:43], 1.0 op_sel_hi:[1,0]
	v_pk_add_f32 v[44:45], v[44:45], 1.0 op_sel_hi:[1,0]
	v_pk_add_f32 v[46:47], v[46:47], 1.0 op_sel_hi:[1,0]
	v_pk_fma_f32 v[0:1], v[0:1], v[40:41], v[58:59]
	v_pk_fma_f32 v[2:3], v[2:3], v[42:43], v[60:61]
	v_pk_fma_f32 v[4:5], v[4:5], v[44:45], v[62:63]
	v_pk_fma_f32 v[6:7], v[6:7], v[46:47], v[64:65]
	ds_read_b128 v[32:35], v102 offset:2816
	ds_read_b128 v[36:39], v102 offset:2832
	ds_read_b128 v[40:43], v102 offset:6912
	ds_read_b128 v[44:47], v102 offset:6928
	ds_read_b128 v[58:61], v102 offset:11008
	ds_read_b128 v[62:65], v102 offset:11024
	v_cvt_pk_f16_f32 v74, v0, v1
	v_cvt_pk_f16_f32 v75, v2, v3
	v_cvt_pk_f16_f32 v76, v4, v5
	v_cvt_pk_f16_f32 v77, v6, v7
	v_cvt_f32_f16_e32 v66, v74
	v_cvt_f32_f16_sdwa v67, v74 dst_sel:DWORD dst_unused:UNUSED_PAD src0_sel:WORD_1
	v_cvt_f32_f16_e32 v68, v75
	v_cvt_f32_f16_sdwa v69, v75 dst_sel:DWORD dst_unused:UNUSED_PAD src0_sel:WORD_1
	v_cvt_f32_f16_e32 v70, v76
	v_cvt_f32_f16_sdwa v71, v76 dst_sel:DWORD dst_unused:UNUSED_PAD src0_sel:WORD_1
	v_cvt_f32_f16_e32 v72, v77
	v_cvt_f32_f16_sdwa v73, v77 dst_sel:DWORD dst_unused:UNUSED_PAD src0_sel:WORD_1
	v_pk_add_f32 v[0:1], v[0:1], v[66:67] neg_lo:[0,1] neg_hi:[0,1]
	v_pk_add_f32 v[2:3], v[2:3], v[68:69] neg_lo:[0,1] neg_hi:[0,1]
	v_pk_add_f32 v[4:5], v[4:5], v[70:71] neg_lo:[0,1] neg_hi:[0,1]
	v_pk_add_f32 v[6:7], v[6:7], v[72:73] neg_lo:[0,1] neg_hi:[0,1]
	s_nop 0
	v_cvt_pk_f16_f32 v78, v0, v1
	v_cvt_pk_f16_f32 v79, v2, v3
	v_cvt_pk_f16_f32 v80, v4, v5
	v_cvt_pk_f16_f32 v81, v6, v7
	global_store_dwordx4 v[88:89], v[74:77], off offset:1344
	s_waitcnt vmcnt(48)
	v_mfma_f32_16x16x32_f16 a[8:11], v[74:77], a[152:155], a[8:11]
	v_mfma_f32_16x16x32_f16 a[8:11], v[78:81], a[152:155], a[8:11]
	v_mfma_f32_16x16x32_f16 a[8:11], v[74:77], a[156:159], a[8:11]
	v_mfma_f32_16x16x32_f16 a[4:7], v[74:77], a[160:163], a[4:7]
	v_mfma_f32_16x16x32_f16 a[4:7], v[78:81], a[160:163], a[4:7]
	v_mfma_f32_16x16x32_f16 a[4:7], v[74:77], a[164:167], a[4:7]
	v_mfma_f32_16x16x32_f16 a[0:3], v[74:77], a[168:171], a[0:3]
	v_mfma_f32_16x16x32_f16 a[0:3], v[78:81], a[168:171], a[0:3]
	v_mfma_f32_16x16x32_f16 a[0:3], v[74:77], a[172:175], a[0:3]
	global_load_dwordx4 a[152:155], v[90:91], off offset:1728
	global_load_dwordx4 a[156:159], v[92:93], off offset:1728
	global_load_dwordx4 a[160:163], v[94:95], off offset:1728
	global_load_dwordx4 a[164:167], v[96:97], off offset:1728
	global_load_dwordx4 a[168:171], v[98:99], off offset:1728
	global_load_dwordx4 a[172:175], v[100:101], off offset:1728
	s_waitcnt vmcnt(54)
	v_accvgpr_read_b32 v0, a64
	v_accvgpr_read_b32 v1, a65
	v_accvgpr_read_b32 v2, a66
	v_accvgpr_read_b32 v3, a67
	v_accvgpr_read_b32 v4, a68
	v_accvgpr_read_b32 v5, a69
	v_accvgpr_read_b32 v6, a70
	v_accvgpr_read_b32 v7, a71
	global_load_dwordx4 a[64:67], v[22:23], off offset:3840
	global_load_dwordx4 a[68:71], v[22:23], off offset:3856
	v_pk_mul_f32 v[0:1], v[28:29], v[0:1]
	v_pk_mul_f32 v[2:3], v[28:29], v[2:3]
	v_pk_mul_f32 v[4:5], v[28:29], v[4:5]
	v_pk_mul_f32 v[6:7], v[28:29], v[6:7]
	s_waitcnt lgkmcnt(0)
	v_pk_mul_f32 v[0:1], v[0:1], v[32:33]
	v_pk_mul_f32 v[2:3], v[2:3], v[34:35]
	v_pk_mul_f32 v[4:5], v[4:5], v[36:37]
	v_pk_mul_f32 v[6:7], v[6:7], v[38:39]
	v_pk_add_f32 v[40:41], v[40:41], 1.0 op_sel_hi:[1,0]
	v_pk_add_f32 v[42:43], v[42:43], 1.0 op_sel_hi:[1,0]
	v_pk_add_f32 v[44:45], v[44:45], 1.0 op_sel_hi:[1,0]
	v_pk_add_f32 v[46:47], v[46:47], 1.0 op_sel_hi:[1,0]
	v_pk_fma_f32 v[0:1], v[0:1], v[40:41], v[58:59]
	v_pk_fma_f32 v[2:3], v[2:3], v[42:43], v[60:61]
	v_pk_fma_f32 v[4:5], v[4:5], v[44:45], v[62:63]
	v_pk_fma_f32 v[6:7], v[6:7], v[46:47], v[64:65]
	ds_read_b128 v[32:35], v102 offset:2944
	ds_read_b128 v[36:39], v102 offset:2960
	ds_read_b128 v[40:43], v102 offset:7040
	ds_read_b128 v[44:47], v102 offset:7056
	ds_read_b128 v[58:61], v102 offset:11136
	ds_read_b128 v[62:65], v102 offset:11152
	v_cvt_pk_f16_f32 v74, v0, v1
	v_cvt_pk_f16_f32 v75, v2, v3
	v_cvt_pk_f16_f32 v76, v4, v5
	v_cvt_pk_f16_f32 v77, v6, v7
	v_cvt_f32_f16_e32 v66, v74
	v_cvt_f32_f16_sdwa v67, v74 dst_sel:DWORD dst_unused:UNUSED_PAD src0_sel:WORD_1
	v_cvt_f32_f16_e32 v68, v75
	v_cvt_f32_f16_sdwa v69, v75 dst_sel:DWORD dst_unused:UNUSED_PAD src0_sel:WORD_1
	v_cvt_f32_f16_e32 v70, v76
	v_cvt_f32_f16_sdwa v71, v76 dst_sel:DWORD dst_unused:UNUSED_PAD src0_sel:WORD_1
	v_cvt_f32_f16_e32 v72, v77
	v_cvt_f32_f16_sdwa v73, v77 dst_sel:DWORD dst_unused:UNUSED_PAD src0_sel:WORD_1
	v_pk_add_f32 v[0:1], v[0:1], v[66:67] neg_lo:[0,1] neg_hi:[0,1]
	v_pk_add_f32 v[2:3], v[2:3], v[68:69] neg_lo:[0,1] neg_hi:[0,1]
	v_pk_add_f32 v[4:5], v[4:5], v[70:71] neg_lo:[0,1] neg_hi:[0,1]
	v_pk_add_f32 v[6:7], v[6:7], v[72:73] neg_lo:[0,1] neg_hi:[0,1]
	s_nop 0
	v_cvt_pk_f16_f32 v78, v0, v1
	v_cvt_pk_f16_f32 v79, v2, v3
	v_cvt_pk_f16_f32 v80, v4, v5
	v_cvt_pk_f16_f32 v81, v6, v7
	global_store_dwordx4 v[88:89], v[74:77], off offset:1408
	s_waitcnt vmcnt(48)
; DI f4 mfma16(h8 a, h8 b, f4 c) { return __builtin_amdgcn_mfma_f32_16x16x32_f16(a, b, c, 0, 0, 0); }
; DI void row2_phase(const Params& P, int l, int r_begin, char* smem) {
;     ...
;     for (int kk = 0; kk < 32; kk++) {
;       const int k0 = kk * 32;
;       float x[8], g[8], s1[8], s0[8];
;       *(float4*)&x[0] = *(const float4*)(xm + k0); *(float4*)&x[4] = *(const float4*)(xm + k0 + 4);
;       *(float4*)&g[0] = *(const float4*)(gam + fq * 8 + k0); *(float4*)&g[4] = *(const float4*)(gam + fq * 8 + k0 + 4);
;       *(float4*)&s1[0] = *(const float4*)(sc + k0); *(float4*)&s1[4] = *(const float4*)(sc + k0 + 4);
;       *(float4*)&s0[0] = *(const float4*)(sh + k0); *(float4*)&s0[4] = *(const float4*)(sh + k0 + 4);
;       h8 hi, lo;
; #pragma unroll
;       for (int i = 0; i < 8; i++) {
;         float v = x[i] * rstd * g[i] * (1.f + s1[i]) + s0[i];
;         hi[i] = (half_t)v; lo[i] = (half_t)(v - (float)hi[i]);
;       }
;       *(h8*)(hxo + k0) = hi;
; #pragma unroll
;       for (int n3 = 0; n3 < 3; n3++) {
;         h8 bh = *(const h8*)(Whi + (size_t)(n3 * 16 + fr) * 1024 + k0 + fq * 8);
;         h8 bl = *(const h8*)(Wlo + (size_t)(n3 * 16 + fr) * 1024 + k0 + fq * 8);
;         acc[n3] = mfma16(hi, bh, acc[n3]); acc[n3] = mfma16(lo, bh, acc[n3]); acc[n3] = mfma16(hi, bl, acc[n3]);
;       }
	v_mfma_f32_16x16x32_f16 a[8:11], v[74:77], a[204:207], a[8:11]
	v_mfma_f32_16x16x32_f16 a[8:11], v[78:81], a[204:207], a[8:11]
	v_mfma_f32_16x16x32_f16 a[8:11], v[74:77], a[208:211], a[8:11]
	v_mfma_f32_16x16x32_f16 a[4:7], v[74:77], a[212:215], a[4:7]
	v_mfma_f32_16x16x32_f16 a[4:7], v[78:81], a[212:215], a[4:7]
	v_mfma_f32_16x16x32_f16 a[4:7], v[74:77], a[216:219], a[4:7]
	v_mfma_f32_16x16x32_f16 a[0:3], v[74:77], a[220:223], a[0:3]
	v_mfma_f32_16x16x32_f16 a[0:3], v[78:81], a[220:223], a[0:3]
	v_mfma_f32_16x16x32_f16 a[0:3], v[74:77], a[224:227], a[0:3]
	global_load_dwordx4 a[204:207], v[90:91], off offset:1792
	global_load_dwordx4 a[208:211], v[92:93], off offset:1792
	global_load_dwordx4 a[212:215], v[94:95], off offset:1792
	global_load_dwordx4 a[216:219], v[96:97], off offset:1792
	global_load_dwordx4 a[220:223], v[98:99], off offset:1792
	global_load_dwordx4 a[224:227], v[100:101], off offset:1792
	s_waitcnt vmcnt(54)
	v_accvgpr_read_b32 v0, a72
	v_accvgpr_read_b32 v1, a73
	v_accvgpr_read_b32 v2, a74
	v_accvgpr_read_b32 v3, a75
	v_accvgpr_read_b32 v4, a76
	v_accvgpr_read_b32 v5, a77
	v_accvgpr_read_b32 v6, a78
	v_accvgpr_read_b32 v7, a79
	global_load_dwordx4 a[72:75], v[22:23], off offset:3968
	global_load_dwordx4 a[76:79], v[22:23], off offset:3984
	v_pk_mul_f32 v[0:1], v[28:29], v[0:1]
	v_pk_mul_f32 v[2:3], v[28:29], v[2:3]
	v_pk_mul_f32 v[4:5], v[28:29], v[4:5]
	v_pk_mul_f32 v[6:7], v[28:29], v[6:7]
	s_waitcnt lgkmcnt(0)
	v_pk_mul_f32 v[0:1], v[0:1], v[32:33]
	v_pk_mul_f32 v[2:3], v[2:3], v[34:35]
	v_pk_mul_f32 v[4:5], v[4:5], v[36:37]
	v_pk_mul_f32 v[6:7], v[6:7], v[38:39]
	v_pk_add_f32 v[40:41], v[40:41], 1.0 op_sel_hi:[1,0]
	v_pk_add_f32 v[42:43], v[42:43], 1.0 op_sel_hi:[1,0]
	v_pk_add_f32 v[44:45], v[44:45], 1.0 op_sel_hi:[1,0]
	v_pk_add_f32 v[46:47], v[46:47], 1.0 op_sel_hi:[1,0]
	v_pk_fma_f32 v[0:1], v[0:1], v[40:41], v[58:59]
	v_pk_fma_f32 v[2:3], v[2:3], v[42:43], v[60:61]
	v_pk_fma_f32 v[4:5], v[4:5], v[44:45], v[62:63]
	v_pk_fma_f32 v[6:7], v[6:7], v[46:47], v[64:65]
	ds_read_b128 v[32:35], v102 offset:3072
	ds_read_b128 v[36:39], v102 offset:3088
	ds_read_b128 v[40:43], v102 offset:7168
	ds_read_b128 v[44:47], v102 offset:7184
	ds_read_b128 v[58:61], v102 offset:11264
	ds_read_b128 v[62:65], v102 offset:11280
	v_cvt_pk_f16_f32 v74, v0, v1
	v_cvt_pk_f16_f32 v75, v2, v3
	v_cvt_pk_f16_f32 v76, v4, v5
	v_cvt_pk_f16_f32 v77, v6, v7
	v_cvt_f32_f16_e32 v66, v74
	v_cvt_f32_f16_sdwa v67, v74 dst_sel:DWORD dst_unused:UNUSED_PAD src0_sel:WORD_1
	v_cvt_f32_f16_e32 v68, v75
	v_cvt_f32_f16_sdwa v69, v75 dst_sel:DWORD dst_unused:UNUSED_PAD src0_sel:WORD_1
	v_cvt_f32_f16_e32 v70, v76
	v_cvt_f32_f16_sdwa v71, v76 dst_sel:DWORD dst_unused:UNUSED_PAD src0_sel:WORD_1
	v_cvt_f32_f16_e32 v72, v77
	v_cvt_f32_f16_sdwa v73, v77 dst_sel:DWORD dst_unused:UNUSED_PAD src0_sel:WORD_1
	v_pk_add_f32 v[0:1], v[0:1], v[66:67] neg_lo:[0,1] neg_hi:[0,1]
	v_pk_add_f32 v[2:3], v[2:3], v[68:69] neg_lo:[0,1] neg_hi:[0,1]
	v_pk_add_f32 v[4:5], v[4:5], v[70:71] neg_lo:[0,1] neg_hi:[0,1]
	v_pk_add_f32 v[6:7], v[6:7], v[72:73] neg_lo:[0,1] neg_hi:[0,1]
	s_nop 0
	v_cvt_pk_f16_f32 v78, v0, v1
	v_cvt_pk_f16_f32 v79, v2, v3
	v_cvt_pk_f16_f32 v80, v4, v5
	v_cvt_pk_f16_f32 v81, v6, v7
	global_store_dwordx4 v[88:89], v[74:77], off offset:1472
	s_waitcnt vmcnt(48)
	v_mfma_f32_16x16x32_f16 a[8:11], v[74:77], a[228:231], a[8:11]
	v_mfma_f32_16x16x32_f16 a[8:11], v[78:81], a[228:231], a[8:11]
	v_mfma_f32_16x16x32_f16 a[8:11], v[74:77], a[232:235], a[8:11]
	v_mfma_f32_16x16x32_f16 a[4:7], v[74:77], a[236:239], a[4:7]
	v_mfma_f32_16x16x32_f16 a[4:7], v[78:81], a[236:239], a[4:7]
	v_mfma_f32_16x16x32_f16 a[4:7], v[74:77], a[240:243], a[4:7]
	v_mfma_f32_16x16x32_f16 a[0:3], v[74:77], a[244:247], a[0:3]
	v_mfma_f32_16x16x32_f16 a[0:3], v[78:81], a[244:247], a[0:3]
	v_mfma_f32_16x16x32_f16 a[0:3], v[74:77], a[248:251], a[0:3]
	global_load_dwordx4 a[228:231], v[90:91], off offset:1856
	global_load_dwordx4 a[232:235], v[92:93], off offset:1856
	global_load_dwordx4 a[236:239], v[94:95], off offset:1856
	global_load_dwordx4 a[240:243], v[96:97], off offset:1856
	global_load_dwordx4 a[244:247], v[98:99], off offset:1856
	global_load_dwordx4 a[248:251], v[100:101], off offset:1856
	s_waitcnt vmcnt(54)
	v_accvgpr_read_b32 v0, a16
	v_accvgpr_read_b32 v1, a17
	v_accvgpr_read_b32 v2, a18
	v_accvgpr_read_b32 v3, a19
	v_accvgpr_read_b32 v4, a20
	v_accvgpr_read_b32 v5, a21
	v_accvgpr_read_b32 v6, a22
	v_accvgpr_read_b32 v7, a23
	v_pk_mul_f32 v[0:1], v[28:29], v[0:1]
	v_pk_mul_f32 v[2:3], v[28:29], v[2:3]
	v_pk_mul_f32 v[4:5], v[28:29], v[4:5]
	v_pk_mul_f32 v[6:7], v[28:29], v[6:7]
	s_waitcnt lgkmcnt(0)
	v_pk_mul_f32 v[0:1], v[0:1], v[32:33]
	v_pk_mul_f32 v[2:3], v[2:3], v[34:35]
	v_pk_mul_f32 v[4:5], v[4:5], v[36:37]
	v_pk_mul_f32 v[6:7], v[6:7], v[38:39]
	v_pk_add_f32 v[40:41], v[40:41], 1.0 op_sel_hi:[1,0]
	v_pk_add_f32 v[42:43], v[42:43], 1.0 op_sel_hi:[1,0]
	v_pk_add_f32 v[44:45], v[44:45], 1.0 op_sel_hi:[1,0]
	v_pk_add_f32 v[46:47], v[46:47], 1.0 op_sel_hi:[1,0]
	v_pk_fma_f32 v[0:1], v[0:1], v[40:41], v[58:59]
	v_pk_fma_f32 v[2:3], v[2:3], v[42:43], v[60:61]
	v_pk_fma_f32 v[4:5], v[4:5], v[44:45], v[62:63]
	v_pk_fma_f32 v[6:7], v[6:7], v[46:47], v[64:65]
	ds_read_b128 v[32:35], v102 offset:3200
	ds_read_b128 v[36:39], v102 offset:3216
	ds_read_b128 v[40:43], v102 offset:7296
	ds_read_b128 v[44:47], v102 offset:7312
	ds_read_b128 v[58:61], v102 offset:11392
	ds_read_b128 v[62:65], v102 offset:11408
	v_cvt_pk_f16_f32 v74, v0, v1
	v_cvt_pk_f16_f32 v75, v2, v3
	v_cvt_pk_f16_f32 v76, v4, v5
	v_cvt_pk_f16_f32 v77, v6, v7
	v_cvt_f32_f16_e32 v66, v74
	v_cvt_f32_f16_sdwa v67, v74 dst_sel:DWORD dst_unused:UNUSED_PAD src0_sel:WORD_1
	v_cvt_f32_f16_e32 v68, v75
	v_cvt_f32_f16_sdwa v69, v75 dst_sel:DWORD dst_unused:UNUSED_PAD src0_sel:WORD_1
	v_cvt_f32_f16_e32 v70, v76
	v_cvt_f32_f16_sdwa v71, v76 dst_sel:DWORD dst_unused:UNUSED_PAD src0_sel:WORD_1
	v_cvt_f32_f16_e32 v72, v77
	v_cvt_f32_f16_sdwa v73, v77 dst_sel:DWORD dst_unused:UNUSED_PAD src0_sel:WORD_1
	v_pk_add_f32 v[0:1], v[0:1], v[66:67] neg_lo:[0,1] neg_hi:[0,1]
	v_pk_add_f32 v[2:3], v[2:3], v[68:69] neg_lo:[0,1] neg_hi:[0,1]
	v_pk_add_f32 v[4:5], v[4:5], v[70:71] neg_lo:[0,1] neg_hi:[0,1]
	v_pk_add_f32 v[6:7], v[6:7], v[72:73] neg_lo:[0,1] neg_hi:[0,1]
	s_nop 0
	v_cvt_pk_f16_f32 v78, v0, v1
	v_cvt_pk_f16_f32 v79, v2, v3
	v_cvt_pk_f16_f32 v80, v4, v5
	v_cvt_pk_f16_f32 v81, v6, v7
	global_store_dwordx4 v[88:89], v[74:77], off offset:1536
	s_waitcnt vmcnt(46)
; DI f4 mfma16(h8 a, h8 b, f4 c) { return __builtin_amdgcn_mfma_f32_16x16x32_f16(a, b, c, 0, 0, 0); }
; DI void row2_phase(const Params& P, int l, int r_begin, char* smem) {
;     ...
;     for (int kk = 0; kk < 32; kk++) {
;       const int k0 = kk * 32;
;       float x[8], g[8], s1[8], s0[8];
;       *(float4*)&x[0] = *(const float4*)(xm + k0); *(float4*)&x[4] = *(const float4*)(xm + k0 + 4);
;       *(float4*)&g[0] = *(const float4*)(gam + fq * 8 + k0); *(float4*)&g[4] = *(const float4*)(gam + fq * 8 + k0 + 4);
;       *(float4*)&s1[0] = *(const float4*)(sc + k0); *(float4*)&s1[4] = *(const float4*)(sc + k0 + 4);
;       *(float4*)&s0[0] = *(const float4*)(sh + k0); *(float4*)&s0[4] = *(const float4*)(sh + k0 + 4);
;       h8 hi, lo;
; #pragma unroll
;       for (int i = 0; i < 8; i++) {
;         float v = x[i] * rstd * g[i] * (1.f + s1[i]) + s0[i];
;         hi[i] = (half_t)v; lo[i] = (half_t)(v - (float)hi[i]);
;       }
;       *(h8*)(hxo + k0) = hi;
; #pragma unroll
;       for (int n3 = 0; n3 < 3; n3++) {
;         h8 bh = *(const h8*)(Whi + (size_t)(n3 * 16 + fr) * 1024 + k0 + fq * 8);
;         h8 bl = *(const h8*)(Wlo + (size_t)(n3 * 16 + fr) * 1024 + k0 + fq * 8);
;         acc[n3] = mfma16(hi, bh, acc[n3]); acc[n3] = mfma16(lo, bh, acc[n3]); acc[n3] = mfma16(hi, bl, acc[n3]);
;       }
	v_mfma_f32_16x16x32_f16 a[8:11], v[74:77], a[80:83], a[8:11]
	v_mfma_f32_16x16x32_f16 a[8:11], v[78:81], a[80:83], a[8:11]
	v_mfma_f32_16x16x32_f16 a[8:11], v[74:77], a[84:87], a[8:11]
	v_mfma_f32_16x16x32_f16 a[4:7], v[74:77], a[88:91], a[4:7]
	v_mfma_f32_16x16x32_f16 a[4:7], v[78:81], a[88:91], a[4:7]
	v_mfma_f32_16x16x32_f16 a[4:7], v[74:77], a[92:95], a[4:7]
	v_mfma_f32_16x16x32_f16 a[0:3], v[74:77], a[96:99], a[0:3]
	v_mfma_f32_16x16x32_f16 a[0:3], v[78:81], a[96:99], a[0:3]
	v_mfma_f32_16x16x32_f16 a[0:3], v[74:77], a[100:103], a[0:3]
	global_load_dwordx4 a[80:83], v[90:91], off offset:1920
	global_load_dwordx4 a[84:87], v[92:93], off offset:1920
	global_load_dwordx4 a[88:91], v[94:95], off offset:1920
	global_load_dwordx4 a[92:95], v[96:97], off offset:1920
	global_load_dwordx4 a[96:99], v[98:99], off offset:1920
	global_load_dwordx4 a[100:103], v[100:101], off offset:1920
	s_waitcnt vmcnt(52)
	v_accvgpr_read_b32 v0, a24
	v_accvgpr_read_b32 v1, a25
	v_accvgpr_read_b32 v2, a26
	v_accvgpr_read_b32 v3, a27
	v_accvgpr_read_b32 v4, a28
	v_accvgpr_read_b32 v5, a29
	v_accvgpr_read_b32 v6, a30
	v_accvgpr_read_b32 v7, a31
	v_pk_mul_f32 v[0:1], v[28:29], v[0:1]
	v_pk_mul_f32 v[2:3], v[28:29], v[2:3]
	v_pk_mul_f32 v[4:5], v[28:29], v[4:5]
	v_pk_mul_f32 v[6:7], v[28:29], v[6:7]
	s_waitcnt lgkmcnt(0)
	v_pk_mul_f32 v[0:1], v[0:1], v[32:33]
	v_pk_mul_f32 v[2:3], v[2:3], v[34:35]
	v_pk_mul_f32 v[4:5], v[4:5], v[36:37]
	v_pk_mul_f32 v[6:7], v[6:7], v[38:39]
	v_pk_add_f32 v[40:41], v[40:41], 1.0 op_sel_hi:[1,0]
	v_pk_add_f32 v[42:43], v[42:43], 1.0 op_sel_hi:[1,0]
	v_pk_add_f32 v[44:45], v[44:45], 1.0 op_sel_hi:[1,0]
	v_pk_add_f32 v[46:47], v[46:47], 1.0 op_sel_hi:[1,0]
	v_pk_fma_f32 v[0:1], v[0:1], v[40:41], v[58:59]
	v_pk_fma_f32 v[2:3], v[2:3], v[42:43], v[60:61]
	v_pk_fma_f32 v[4:5], v[4:5], v[44:45], v[62:63]
	v_pk_fma_f32 v[6:7], v[6:7], v[46:47], v[64:65]
	ds_read_b128 v[32:35], v102 offset:3328
	ds_read_b128 v[36:39], v102 offset:3344
	ds_read_b128 v[40:43], v102 offset:7424
	ds_read_b128 v[44:47], v102 offset:7440
	ds_read_b128 v[58:61], v102 offset:11520
	ds_read_b128 v[62:65], v102 offset:11536
	v_cvt_pk_f16_f32 v74, v0, v1
	v_cvt_pk_f16_f32 v75, v2, v3
	v_cvt_pk_f16_f32 v76, v4, v5
	v_cvt_pk_f16_f32 v77, v6, v7
	v_cvt_f32_f16_e32 v66, v74
	v_cvt_f32_f16_sdwa v67, v74 dst_sel:DWORD dst_unused:UNUSED_PAD src0_sel:WORD_1
	v_cvt_f32_f16_e32 v68, v75
	v_cvt_f32_f16_sdwa v69, v75 dst_sel:DWORD dst_unused:UNUSED_PAD src0_sel:WORD_1
	v_cvt_f32_f16_e32 v70, v76
	v_cvt_f32_f16_sdwa v71, v76 dst_sel:DWORD dst_unused:UNUSED_PAD src0_sel:WORD_1
	v_cvt_f32_f16_e32 v72, v77
	v_cvt_f32_f16_sdwa v73, v77 dst_sel:DWORD dst_unused:UNUSED_PAD src0_sel:WORD_1
	v_pk_add_f32 v[0:1], v[0:1], v[66:67] neg_lo:[0,1] neg_hi:[0,1]
	v_pk_add_f32 v[2:3], v[2:3], v[68:69] neg_lo:[0,1] neg_hi:[0,1]
	v_pk_add_f32 v[4:5], v[4:5], v[70:71] neg_lo:[0,1] neg_hi:[0,1]
	v_pk_add_f32 v[6:7], v[6:7], v[72:73] neg_lo:[0,1] neg_hi:[0,1]
	s_nop 0
	v_cvt_pk_f16_f32 v78, v0, v1
	v_cvt_pk_f16_f32 v79, v2, v3
	v_cvt_pk_f16_f32 v80, v4, v5
	v_cvt_pk_f16_f32 v81, v6, v7
	global_store_dwordx4 v[88:89], v[74:77], off offset:1600
	s_waitcnt vmcnt(44)
	v_mfma_f32_16x16x32_f16 a[8:11], v[74:77], a[104:107], a[8:11]
	v_mfma_f32_16x16x32_f16 a[8:11], v[78:81], a[104:107], a[8:11]
	v_mfma_f32_16x16x32_f16 a[8:11], v[74:77], a[108:111], a[8:11]
	v_mfma_f32_16x16x32_f16 a[4:7], v[74:77], a[112:115], a[4:7]
	v_mfma_f32_16x16x32_f16 a[4:7], v[78:81], a[112:115], a[4:7]
	v_mfma_f32_16x16x32_f16 a[4:7], v[74:77], a[116:119], a[4:7]
	v_mfma_f32_16x16x32_f16 a[0:3], v[74:77], a[120:123], a[0:3]
	v_mfma_f32_16x16x32_f16 a[0:3], v[78:81], a[120:123], a[0:3]
	v_mfma_f32_16x16x32_f16 a[0:3], v[74:77], a[124:127], a[0:3]
	global_load_dwordx4 a[104:107], v[90:91], off offset:1984
	global_load_dwordx4 a[108:111], v[92:93], off offset:1984
	global_load_dwordx4 a[112:115], v[94:95], off offset:1984
	global_load_dwordx4 a[116:119], v[96:97], off offset:1984
	global_load_dwordx4 a[120:123], v[98:99], off offset:1984
	global_load_dwordx4 a[124:127], v[100:101], off offset:1984
	s_waitcnt vmcnt(50)
	v_accvgpr_read_b32 v0, a32
	v_accvgpr_read_b32 v1, a33
	v_accvgpr_read_b32 v2, a34
	v_accvgpr_read_b32 v3, a35
	v_accvgpr_read_b32 v4, a36
	v_accvgpr_read_b32 v5, a37
	v_accvgpr_read_b32 v6, a38
	v_accvgpr_read_b32 v7, a39
	v_pk_mul_f32 v[0:1], v[28:29], v[0:1]
	v_pk_mul_f32 v[2:3], v[28:29], v[2:3]
	v_pk_mul_f32 v[4:5], v[28:29], v[4:5]
	v_pk_mul_f32 v[6:7], v[28:29], v[6:7]
	s_waitcnt lgkmcnt(0)
	v_pk_mul_f32 v[0:1], v[0:1], v[32:33]
	v_pk_mul_f32 v[2:3], v[2:3], v[34:35]
	v_pk_mul_f32 v[4:5], v[4:5], v[36:37]
	v_pk_mul_f32 v[6:7], v[6:7], v[38:39]
	v_pk_add_f32 v[40:41], v[40:41], 1.0 op_sel_hi:[1,0]
	v_pk_add_f32 v[42:43], v[42:43], 1.0 op_sel_hi:[1,0]
	v_pk_add_f32 v[44:45], v[44:45], 1.0 op_sel_hi:[1,0]
	v_pk_add_f32 v[46:47], v[46:47], 1.0 op_sel_hi:[1,0]
	v_pk_fma_f32 v[0:1], v[0:1], v[40:41], v[58:59]
	v_pk_fma_f32 v[2:3], v[2:3], v[42:43], v[60:61]
	v_pk_fma_f32 v[4:5], v[4:5], v[44:45], v[62:63]
	v_pk_fma_f32 v[6:7], v[6:7], v[46:47], v[64:65]
	ds_read_b128 v[32:35], v102 offset:3456
	ds_read_b128 v[36:39], v102 offset:3472
	ds_read_b128 v[40:43], v102 offset:7552
	ds_read_b128 v[44:47], v102 offset:7568
	ds_read_b128 v[58:61], v102 offset:11648
	ds_read_b128 v[62:65], v102 offset:11664
	v_cvt_pk_f16_f32 v74, v0, v1
	v_cvt_pk_f16_f32 v75, v2, v3
	v_cvt_pk_f16_f32 v76, v4, v5
	v_cvt_pk_f16_f32 v77, v6, v7
	v_cvt_f32_f16_e32 v66, v74
	v_cvt_f32_f16_sdwa v67, v74 dst_sel:DWORD dst_unused:UNUSED_PAD src0_sel:WORD_1
	v_cvt_f32_f16_e32 v68, v75
	v_cvt_f32_f16_sdwa v69, v75 dst_sel:DWORD dst_unused:UNUSED_PAD src0_sel:WORD_1
	v_cvt_f32_f16_e32 v70, v76
	v_cvt_f32_f16_sdwa v71, v76 dst_sel:DWORD dst_unused:UNUSED_PAD src0_sel:WORD_1
	v_cvt_f32_f16_e32 v72, v77
	v_cvt_f32_f16_sdwa v73, v77 dst_sel:DWORD dst_unused:UNUSED_PAD src0_sel:WORD_1
	v_pk_add_f32 v[0:1], v[0:1], v[66:67] neg_lo:[0,1] neg_hi:[0,1]
	v_pk_add_f32 v[2:3], v[2:3], v[68:69] neg_lo:[0,1] neg_hi:[0,1]
	v_pk_add_f32 v[4:5], v[4:5], v[70:71] neg_lo:[0,1] neg_hi:[0,1]
	v_pk_add_f32 v[6:7], v[6:7], v[72:73] neg_lo:[0,1] neg_hi:[0,1]
	s_nop 0
	v_cvt_pk_f16_f32 v78, v0, v1
	v_cvt_pk_f16_f32 v79, v2, v3
	v_cvt_pk_f16_f32 v80, v4, v5
	v_cvt_pk_f16_f32 v81, v6, v7
	global_store_dwordx4 v[88:89], v[74:77], off offset:1664
	s_waitcnt vmcnt(42)
; DI f4 mfma16(h8 a, h8 b, f4 c) { return __builtin_amdgcn_mfma_f32_16x16x32_f16(a, b, c, 0, 0, 0); }
; DI void row2_phase(const Params& P, int l, int r_begin, char* smem) {
;     ...
;     for (int kk = 0; kk < 32; kk++) {
;       const int k0 = kk * 32;
;       float x[8], g[8], s1[8], s0[8];
;       *(float4*)&x[0] = *(const float4*)(xm + k0); *(float4*)&x[4] = *(const float4*)(xm + k0 + 4);
;       *(float4*)&g[0] = *(const float4*)(gam + fq * 8 + k0); *(float4*)&g[4] = *(const float4*)(gam + fq * 8 + k0 + 4);
;       *(float4*)&s1[0] = *(const float4*)(sc + k0); *(float4*)&s1[4] = *(const float4*)(sc + k0 + 4);
;       *(float4*)&s0[0] = *(const float4*)(sh + k0); *(float4*)&s0[4] = *(const float4*)(sh + k0 + 4);
;       h8 hi, lo;
; #pragma unroll
;       for (int i = 0; i < 8; i++) {
;         float v = x[i] * rstd * g[i] * (1.f + s1[i]) + s0[i];
;         hi[i] = (half_t)v; lo[i] = (half_t)(v - (float)hi[i]);
;       }
;       *(h8*)(hxo + k0) = hi;
; #pragma unroll
;       for (int n3 = 0; n3 < 3; n3++) {
;         h8 bh = *(const h8*)(Whi + (size_t)(n3 * 16 + fr) * 1024 + k0 + fq * 8);
;         h8 bl = *(const h8*)(Wlo + (size_t)(n3 * 16 + fr) * 1024 + k0 + fq * 8);
;         acc[n3] = mfma16(hi, bh, acc[n3]); acc[n3] = mfma16(lo, bh, acc[n3]); acc[n3] = mfma16(hi, bl, acc[n3]);
;       }
	v_mfma_f32_16x16x32_f16 a[8:11], v[74:77], a[128:131], a[8:11]
	v_mfma_f32_16x16x32_f16 a[8:11], v[78:81], a[128:131], a[8:11]
	v_mfma_f32_16x16x32_f16 a[8:11], v[74:77], a[132:135], a[8:11]
	v_mfma_f32_16x16x32_f16 a[4:7], v[74:77], a[136:139], a[4:7]
	v_mfma_f32_16x16x32_f16 a[4:7], v[78:81], a[136:139], a[4:7]
	v_mfma_f32_16x16x32_f16 a[4:7], v[74:77], a[140:143], a[4:7]
	v_mfma_f32_16x16x32_f16 a[0:3], v[74:77], a[144:147], a[0:3]
	v_mfma_f32_16x16x32_f16 a[0:3], v[78:81], a[144:147], a[0:3]
	v_mfma_f32_16x16x32_f16 a[0:3], v[74:77], a[148:151], a[0:3]
	s_waitcnt vmcnt(42)
	v_accvgpr_read_b32 v0, a40
	v_accvgpr_read_b32 v1, a41
	v_accvgpr_read_b32 v2, a42
	v_accvgpr_read_b32 v3, a43
	v_accvgpr_read_b32 v4, a44
	v_accvgpr_read_b32 v5, a45
	v_accvgpr_read_b32 v6, a46
	v_accvgpr_read_b32 v7, a47
	v_pk_mul_f32 v[0:1], v[28:29], v[0:1]
	v_pk_mul_f32 v[2:3], v[28:29], v[2:3]
	v_pk_mul_f32 v[4:5], v[28:29], v[4:5]
	v_pk_mul_f32 v[6:7], v[28:29], v[6:7]
	s_waitcnt lgkmcnt(0)
	v_pk_mul_f32 v[0:1], v[0:1], v[32:33]
	v_pk_mul_f32 v[2:3], v[2:3], v[34:35]
	v_pk_mul_f32 v[4:5], v[4:5], v[36:37]
	v_pk_mul_f32 v[6:7], v[6:7], v[38:39]
	v_pk_add_f32 v[40:41], v[40:41], 1.0 op_sel_hi:[1,0]
	v_pk_add_f32 v[42:43], v[42:43], 1.0 op_sel_hi:[1,0]
	v_pk_add_f32 v[44:45], v[44:45], 1.0 op_sel_hi:[1,0]
	v_pk_add_f32 v[46:47], v[46:47], 1.0 op_sel_hi:[1,0]
	v_pk_fma_f32 v[0:1], v[0:1], v[40:41], v[58:59]
	v_pk_fma_f32 v[2:3], v[2:3], v[42:43], v[60:61]
	v_pk_fma_f32 v[4:5], v[4:5], v[44:45], v[62:63]
	v_pk_fma_f32 v[6:7], v[6:7], v[46:47], v[64:65]
	ds_read_b128 v[32:35], v102 offset:3584
	ds_read_b128 v[36:39], v102 offset:3600
	ds_read_b128 v[40:43], v102 offset:7680
	ds_read_b128 v[44:47], v102 offset:7696
	ds_read_b128 v[58:61], v102 offset:11776
	ds_read_b128 v[62:65], v102 offset:11792
	v_cvt_pk_f16_f32 v74, v0, v1
	v_cvt_pk_f16_f32 v75, v2, v3
	v_cvt_pk_f16_f32 v76, v4, v5
	v_cvt_pk_f16_f32 v77, v6, v7
	v_cvt_f32_f16_e32 v66, v74
	v_cvt_f32_f16_sdwa v67, v74 dst_sel:DWORD dst_unused:UNUSED_PAD src0_sel:WORD_1
	v_cvt_f32_f16_e32 v68, v75
	v_cvt_f32_f16_sdwa v69, v75 dst_sel:DWORD dst_unused:UNUSED_PAD src0_sel:WORD_1
	v_cvt_f32_f16_e32 v70, v76
	v_cvt_f32_f16_sdwa v71, v76 dst_sel:DWORD dst_unused:UNUSED_PAD src0_sel:WORD_1
	v_cvt_f32_f16_e32 v72, v77
	v_cvt_f32_f16_sdwa v73, v77 dst_sel:DWORD dst_unused:UNUSED_PAD src0_sel:WORD_1
	v_pk_add_f32 v[0:1], v[0:1], v[66:67] neg_lo:[0,1] neg_hi:[0,1]
	v_pk_add_f32 v[2:3], v[2:3], v[68:69] neg_lo:[0,1] neg_hi:[0,1]
	v_pk_add_f32 v[4:5], v[4:5], v[70:71] neg_lo:[0,1] neg_hi:[0,1]
	v_pk_add_f32 v[6:7], v[6:7], v[72:73] neg_lo:[0,1] neg_hi:[0,1]
	s_nop 0
	v_cvt_pk_f16_f32 v78, v0, v1
	v_cvt_pk_f16_f32 v79, v2, v3
	v_cvt_pk_f16_f32 v80, v4, v5
	v_cvt_pk_f16_f32 v81, v6, v7
	global_store_dwordx4 v[88:89], v[74:77], off offset:1728
	s_waitcnt vmcnt(34)
	v_mfma_f32_16x16x32_f16 a[8:11], v[74:77], a[152:155], a[8:11]
	v_mfma_f32_16x16x32_f16 a[8:11], v[78:81], a[152:155], a[8:11]
	v_mfma_f32_16x16x32_f16 a[8:11], v[74:77], a[156:159], a[8:11]
	v_mfma_f32_16x16x32_f16 a[4:7], v[74:77], a[160:163], a[4:7]
	v_mfma_f32_16x16x32_f16 a[4:7], v[78:81], a[160:163], a[4:7]
	v_mfma_f32_16x16x32_f16 a[4:7], v[74:77], a[164:167], a[4:7]
	v_mfma_f32_16x16x32_f16 a[0:3], v[74:77], a[168:171], a[0:3]
	v_mfma_f32_16x16x32_f16 a[0:3], v[78:81], a[168:171], a[0:3]
	v_mfma_f32_16x16x32_f16 a[0:3], v[74:77], a[172:175], a[0:3]
	s_waitcnt vmcnt(34)
	v_accvgpr_read_b32 v0, a48
	v_accvgpr_read_b32 v1, a49
	v_accvgpr_read_b32 v2, a50
	v_accvgpr_read_b32 v3, a51
	v_accvgpr_read_b32 v4, a52
	v_accvgpr_read_b32 v5, a53
	v_accvgpr_read_b32 v6, a54
	v_accvgpr_read_b32 v7, a55
	v_pk_mul_f32 v[0:1], v[28:29], v[0:1]
	v_pk_mul_f32 v[2:3], v[28:29], v[2:3]
	v_pk_mul_f32 v[4:5], v[28:29], v[4:5]
	v_pk_mul_f32 v[6:7], v[28:29], v[6:7]
	s_waitcnt lgkmcnt(0)
	v_pk_mul_f32 v[0:1], v[0:1], v[32:33]
	v_pk_mul_f32 v[2:3], v[2:3], v[34:35]
	v_pk_mul_f32 v[4:5], v[4:5], v[36:37]
	v_pk_mul_f32 v[6:7], v[6:7], v[38:39]
	v_pk_add_f32 v[40:41], v[40:41], 1.0 op_sel_hi:[1,0]
	v_pk_add_f32 v[42:43], v[42:43], 1.0 op_sel_hi:[1,0]
	v_pk_add_f32 v[44:45], v[44:45], 1.0 op_sel_hi:[1,0]
	v_pk_add_f32 v[46:47], v[46:47], 1.0 op_sel_hi:[1,0]
	v_pk_fma_f32 v[0:1], v[0:1], v[40:41], v[58:59]
	v_pk_fma_f32 v[2:3], v[2:3], v[42:43], v[60:61]
	v_pk_fma_f32 v[4:5], v[4:5], v[44:45], v[62:63]
	v_pk_fma_f32 v[6:7], v[6:7], v[46:47], v[64:65]
	ds_read_b128 v[32:35], v102 offset:3712
	ds_read_b128 v[36:39], v102 offset:3728
	ds_read_b128 v[40:43], v102 offset:7808
	ds_read_b128 v[44:47], v102 offset:7824
	ds_read_b128 v[58:61], v102 offset:11904
	ds_read_b128 v[62:65], v102 offset:11920
	v_cvt_pk_f16_f32 v74, v0, v1
	v_cvt_pk_f16_f32 v75, v2, v3
	v_cvt_pk_f16_f32 v76, v4, v5
	v_cvt_pk_f16_f32 v77, v6, v7
	v_cvt_f32_f16_e32 v66, v74
	v_cvt_f32_f16_sdwa v67, v74 dst_sel:DWORD dst_unused:UNUSED_PAD src0_sel:WORD_1
	v_cvt_f32_f16_e32 v68, v75
	v_cvt_f32_f16_sdwa v69, v75 dst_sel:DWORD dst_unused:UNUSED_PAD src0_sel:WORD_1
	v_cvt_f32_f16_e32 v70, v76
	v_cvt_f32_f16_sdwa v71, v76 dst_sel:DWORD dst_unused:UNUSED_PAD src0_sel:WORD_1
	v_cvt_f32_f16_e32 v72, v77
	v_cvt_f32_f16_sdwa v73, v77 dst_sel:DWORD dst_unused:UNUSED_PAD src0_sel:WORD_1
	v_pk_add_f32 v[0:1], v[0:1], v[66:67] neg_lo:[0,1] neg_hi:[0,1]
	v_pk_add_f32 v[2:3], v[2:3], v[68:69] neg_lo:[0,1] neg_hi:[0,1]
	v_pk_add_f32 v[4:5], v[4:5], v[70:71] neg_lo:[0,1] neg_hi:[0,1]
	v_pk_add_f32 v[6:7], v[6:7], v[72:73] neg_lo:[0,1] neg_hi:[0,1]
	s_nop 0
	v_cvt_pk_f16_f32 v78, v0, v1
	v_cvt_pk_f16_f32 v79, v2, v3
	v_cvt_pk_f16_f32 v80, v4, v5
	v_cvt_pk_f16_f32 v81, v6, v7
	global_store_dwordx4 v[88:89], v[74:77], off offset:1792
	s_waitcnt vmcnt(26)
; DI f4 mfma16(h8 a, h8 b, f4 c) { return __builtin_amdgcn_mfma_f32_16x16x32_f16(a, b, c, 0, 0, 0); }
; DI void row2_phase(const Params& P, int l, int r_begin, char* smem) {
;     ...
;     for (int kk = 0; kk < 32; kk++) {
;       const int k0 = kk * 32;
;       float x[8], g[8], s1[8], s0[8];
;       *(float4*)&x[0] = *(const float4*)(xm + k0); *(float4*)&x[4] = *(const float4*)(xm + k0 + 4);
;       *(float4*)&g[0] = *(const float4*)(gam + fq * 8 + k0); *(float4*)&g[4] = *(const float4*)(gam + fq * 8 + k0 + 4);
;       *(float4*)&s1[0] = *(const float4*)(sc + k0); *(float4*)&s1[4] = *(const float4*)(sc + k0 + 4);
;       *(float4*)&s0[0] = *(const float4*)(sh + k0); *(float4*)&s0[4] = *(const float4*)(sh + k0 + 4);
;       h8 hi, lo;
; #pragma unroll
;       for (int i = 0; i < 8; i++) {
;         float v = x[i] * rstd * g[i] * (1.f + s1[i]) + s0[i];
;         hi[i] = (half_t)v; lo[i] = (half_t)(v - (float)hi[i]);
;       }
;       *(h8*)(hxo + k0) = hi;
; #pragma unroll
;       for (int n3 = 0; n3 < 3; n3++) {
;         h8 bh = *(const h8*)(Whi + (size_t)(n3 * 16 + fr) * 1024 + k0 + fq * 8);
;         h8 bl = *(const h8*)(Wlo + (size_t)(n3 * 16 + fr) * 1024 + k0 + fq * 8);
;         acc[n3] = mfma16(hi, bh, acc[n3]); acc[n3] = mfma16(lo, bh, acc[n3]); acc[n3] = mfma16(hi, bl, acc[n3]);
;       }
	v_mfma_f32_16x16x32_f16 a[8:11], v[74:77], a[204:207], a[8:11]
	v_mfma_f32_16x16x32_f16 a[8:11], v[78:81], a[204:207], a[8:11]
	v_mfma_f32_16x16x32_f16 a[8:11], v[74:77], a[208:211], a[8:11]
	v_mfma_f32_16x16x32_f16 a[4:7], v[74:77], a[212:215], a[4:7]
	v_mfma_f32_16x16x32_f16 a[4:7], v[78:81], a[212:215], a[4:7]
	v_mfma_f32_16x16x32_f16 a[4:7], v[74:77], a[216:219], a[4:7]
	v_mfma_f32_16x16x32_f16 a[0:3], v[74:77], a[220:223], a[0:3]
	v_mfma_f32_16x16x32_f16 a[0:3], v[78:81], a[220:223], a[0:3]
	v_mfma_f32_16x16x32_f16 a[0:3], v[74:77], a[224:227], a[0:3]
	s_waitcnt vmcnt(26)
	v_accvgpr_read_b32 v0, a56
	v_accvgpr_read_b32 v1, a57
	v_accvgpr_read_b32 v2, a58
	v_accvgpr_read_b32 v3, a59
	v_accvgpr_read_b32 v4, a60
	v_accvgpr_read_b32 v5, a61
	v_accvgpr_read_b32 v6, a62
	v_accvgpr_read_b32 v7, a63
	v_pk_mul_f32 v[0:1], v[28:29], v[0:1]
	v_pk_mul_f32 v[2:3], v[28:29], v[2:3]
	v_pk_mul_f32 v[4:5], v[28:29], v[4:5]
	v_pk_mul_f32 v[6:7], v[28:29], v[6:7]
	s_waitcnt lgkmcnt(0)
	v_pk_mul_f32 v[0:1], v[0:1], v[32:33]
	v_pk_mul_f32 v[2:3], v[2:3], v[34:35]
	v_pk_mul_f32 v[4:5], v[4:5], v[36:37]
	v_pk_mul_f32 v[6:7], v[6:7], v[38:39]
	v_pk_add_f32 v[40:41], v[40:41], 1.0 op_sel_hi:[1,0]
	v_pk_add_f32 v[42:43], v[42:43], 1.0 op_sel_hi:[1,0]
	v_pk_add_f32 v[44:45], v[44:45], 1.0 op_sel_hi:[1,0]
	v_pk_add_f32 v[46:47], v[46:47], 1.0 op_sel_hi:[1,0]
	v_pk_fma_f32 v[0:1], v[0:1], v[40:41], v[58:59]
	v_pk_fma_f32 v[2:3], v[2:3], v[42:43], v[60:61]
	v_pk_fma_f32 v[4:5], v[4:5], v[44:45], v[62:63]
	v_pk_fma_f32 v[6:7], v[6:7], v[46:47], v[64:65]
	ds_read_b128 v[32:35], v102 offset:3840
	ds_read_b128 v[36:39], v102 offset:3856
	ds_read_b128 v[40:43], v102 offset:7936
	ds_read_b128 v[44:47], v102 offset:7952
	ds_read_b128 v[58:61], v102 offset:12032
	ds_read_b128 v[62:65], v102 offset:12048
	v_cvt_pk_f16_f32 v74, v0, v1
	v_cvt_pk_f16_f32 v75, v2, v3
	v_cvt_pk_f16_f32 v76, v4, v5
	v_cvt_pk_f16_f32 v77, v6, v7
	v_cvt_f32_f16_e32 v66, v74
	v_cvt_f32_f16_sdwa v67, v74 dst_sel:DWORD dst_unused:UNUSED_PAD src0_sel:WORD_1
	v_cvt_f32_f16_e32 v68, v75
	v_cvt_f32_f16_sdwa v69, v75 dst_sel:DWORD dst_unused:UNUSED_PAD src0_sel:WORD_1
	v_cvt_f32_f16_e32 v70, v76
	v_cvt_f32_f16_sdwa v71, v76 dst_sel:DWORD dst_unused:UNUSED_PAD src0_sel:WORD_1
	v_cvt_f32_f16_e32 v72, v77
	v_cvt_f32_f16_sdwa v73, v77 dst_sel:DWORD dst_unused:UNUSED_PAD src0_sel:WORD_1
	v_pk_add_f32 v[0:1], v[0:1], v[66:67] neg_lo:[0,1] neg_hi:[0,1]
	v_pk_add_f32 v[2:3], v[2:3], v[68:69] neg_lo:[0,1] neg_hi:[0,1]
	v_pk_add_f32 v[4:5], v[4:5], v[70:71] neg_lo:[0,1] neg_hi:[0,1]
	v_pk_add_f32 v[6:7], v[6:7], v[72:73] neg_lo:[0,1] neg_hi:[0,1]
	s_nop 0
	v_cvt_pk_f16_f32 v78, v0, v1
	v_cvt_pk_f16_f32 v79, v2, v3
	v_cvt_pk_f16_f32 v80, v4, v5
	v_cvt_pk_f16_f32 v81, v6, v7
	global_store_dwordx4 v[88:89], v[74:77], off offset:1856
	s_waitcnt vmcnt(18)
	v_mfma_f32_16x16x32_f16 a[8:11], v[74:77], a[228:231], a[8:11]
	v_mfma_f32_16x16x32_f16 a[8:11], v[78:81], a[228:231], a[8:11]
	v_mfma_f32_16x16x32_f16 a[8:11], v[74:77], a[232:235], a[8:11]
	v_mfma_f32_16x16x32_f16 a[4:7], v[74:77], a[236:239], a[4:7]
	v_mfma_f32_16x16x32_f16 a[4:7], v[78:81], a[236:239], a[4:7]
	v_mfma_f32_16x16x32_f16 a[4:7], v[74:77], a[240:243], a[4:7]
	v_mfma_f32_16x16x32_f16 a[0:3], v[74:77], a[244:247], a[0:3]
	v_mfma_f32_16x16x32_f16 a[0:3], v[78:81], a[244:247], a[0:3]
	v_mfma_f32_16x16x32_f16 a[0:3], v[74:77], a[248:251], a[0:3]
	s_waitcnt vmcnt(18)
	v_accvgpr_read_b32 v0, a64
	v_accvgpr_read_b32 v1, a65
	v_accvgpr_read_b32 v2, a66
	v_accvgpr_read_b32 v3, a67
	v_accvgpr_read_b32 v4, a68
	v_accvgpr_read_b32 v5, a69
	v_accvgpr_read_b32 v6, a70
	v_accvgpr_read_b32 v7, a71
	v_pk_mul_f32 v[0:1], v[28:29], v[0:1]
	v_pk_mul_f32 v[2:3], v[28:29], v[2:3]
	v_pk_mul_f32 v[4:5], v[28:29], v[4:5]
	v_pk_mul_f32 v[6:7], v[28:29], v[6:7]
	s_waitcnt lgkmcnt(0)
	v_pk_mul_f32 v[0:1], v[0:1], v[32:33]
	v_pk_mul_f32 v[2:3], v[2:3], v[34:35]
	v_pk_mul_f32 v[4:5], v[4:5], v[36:37]
	v_pk_mul_f32 v[6:7], v[6:7], v[38:39]
	v_pk_add_f32 v[40:41], v[40:41], 1.0 op_sel_hi:[1,0]
	v_pk_add_f32 v[42:43], v[42:43], 1.0 op_sel_hi:[1,0]
	v_pk_add_f32 v[44:45], v[44:45], 1.0 op_sel_hi:[1,0]
	v_pk_add_f32 v[46:47], v[46:47], 1.0 op_sel_hi:[1,0]
	v_pk_fma_f32 v[0:1], v[0:1], v[40:41], v[58:59]
	v_pk_fma_f32 v[2:3], v[2:3], v[42:43], v[60:61]
	v_pk_fma_f32 v[4:5], v[4:5], v[44:45], v[62:63]
	v_pk_fma_f32 v[6:7], v[6:7], v[46:47], v[64:65]
	ds_read_b128 v[32:35], v102 offset:3968
	ds_read_b128 v[36:39], v102 offset:3984
	ds_read_b128 v[40:43], v102 offset:8064
	ds_read_b128 v[44:47], v102 offset:8080
	ds_read_b128 v[58:61], v102 offset:12160
	ds_read_b128 v[62:65], v102 offset:12176
	v_cvt_pk_f16_f32 v74, v0, v1
	v_cvt_pk_f16_f32 v75, v2, v3
	v_cvt_pk_f16_f32 v76, v4, v5
	v_cvt_pk_f16_f32 v77, v6, v7
	v_cvt_f32_f16_e32 v66, v74
	v_cvt_f32_f16_sdwa v67, v74 dst_sel:DWORD dst_unused:UNUSED_PAD src0_sel:WORD_1
	v_cvt_f32_f16_e32 v68, v75
	v_cvt_f32_f16_sdwa v69, v75 dst_sel:DWORD dst_unused:UNUSED_PAD src0_sel:WORD_1
	v_cvt_f32_f16_e32 v70, v76
	v_cvt_f32_f16_sdwa v71, v76 dst_sel:DWORD dst_unused:UNUSED_PAD src0_sel:WORD_1
	v_cvt_f32_f16_e32 v72, v77
	v_cvt_f32_f16_sdwa v73, v77 dst_sel:DWORD dst_unused:UNUSED_PAD src0_sel:WORD_1
	v_pk_add_f32 v[0:1], v[0:1], v[66:67] neg_lo:[0,1] neg_hi:[0,1]
	v_pk_add_f32 v[2:3], v[2:3], v[68:69] neg_lo:[0,1] neg_hi:[0,1]
	v_pk_add_f32 v[4:5], v[4:5], v[70:71] neg_lo:[0,1] neg_hi:[0,1]
	v_pk_add_f32 v[6:7], v[6:7], v[72:73] neg_lo:[0,1] neg_hi:[0,1]
	s_nop 0
	v_cvt_pk_f16_f32 v78, v0, v1
	v_cvt_pk_f16_f32 v79, v2, v3
	v_cvt_pk_f16_f32 v80, v4, v5
	v_cvt_pk_f16_f32 v81, v6, v7
	global_store_dwordx4 v[88:89], v[74:77], off offset:1920
	s_waitcnt vmcnt(12)
; DI f4 mfma16(h8 a, h8 b, f4 c) { return __builtin_amdgcn_mfma_f32_16x16x32_f16(a, b, c, 0, 0, 0); }
; DI void row2_phase(const Params& P, int l, int r_begin, char* smem) {
;     ...
;       for (int n3 = 0; n3 < 3; n3++) {
;         h8 bh = *(const h8*)(Whi + (size_t)(n3 * 16 + fr) * 1024 + k0 + fq * 8);
;         h8 bl = *(const h8*)(Wlo + (size_t)(n3 * 16 + fr) * 1024 + k0 + fq * 8);
;         acc[n3] = mfma16(hi, bh, acc[n3]); acc[n3] = mfma16(lo, bh, acc[n3]); acc[n3] = mfma16(hi, bl, acc[n3]);
;       }
;     }
;     __builtin_amdgcn_wave_barrier();
; #pragma unroll
;     for (int n3 = 0; n3 < 3; n3++)
; #pragma unroll
;       for (int j = 0; j < 4; j++) lg[(fq * 4 + j) * 48 + n3 * 16 + fr] = acc[n3][j];
;     __builtin_amdgcn_wave_barrier();
;     if (lane < 16) {
;       const int r = r0 + lane;
;       const float* L = lg + lane * 48;
;       float gl[4]; int gi = 0;
; #pragma unroll
;       for (int j = 0; j < 4; j++) gl[j] = L[j] + P.b_group[l * 4 + j];
	v_mfma_f32_16x16x32_f16 a[8:11], v[74:77], a[80:83], a[8:11]
	v_mfma_f32_16x16x32_f16 a[8:11], v[78:81], a[80:83], a[8:11]
	v_mfma_f32_16x16x32_f16 a[8:11], v[74:77], a[84:87], a[8:11]
	v_mfma_f32_16x16x32_f16 a[4:7], v[74:77], a[88:91], a[4:7]
	v_mfma_f32_16x16x32_f16 a[4:7], v[78:81], a[88:91], a[4:7]
	v_mfma_f32_16x16x32_f16 a[4:7], v[74:77], a[92:95], a[4:7]
	v_mfma_f32_16x16x32_f16 a[0:3], v[74:77], a[96:99], a[0:3]
	v_mfma_f32_16x16x32_f16 a[0:3], v[78:81], a[96:99], a[0:3]
	v_mfma_f32_16x16x32_f16 a[0:3], v[74:77], a[100:103], a[0:3]
	s_waitcnt vmcnt(12)
	v_accvgpr_read_b32 v0, a72
	v_accvgpr_read_b32 v1, a73
	v_accvgpr_read_b32 v2, a74
	v_accvgpr_read_b32 v3, a75
	v_accvgpr_read_b32 v4, a76
	v_accvgpr_read_b32 v5, a77
	v_accvgpr_read_b32 v6, a78
	v_accvgpr_read_b32 v7, a79
	v_pk_mul_f32 v[0:1], v[28:29], v[0:1]
	v_pk_mul_f32 v[2:3], v[28:29], v[2:3]
	v_pk_mul_f32 v[4:5], v[28:29], v[4:5]
	v_pk_mul_f32 v[6:7], v[28:29], v[6:7]
	s_waitcnt lgkmcnt(0)
	v_pk_mul_f32 v[0:1], v[0:1], v[32:33]
	v_pk_mul_f32 v[2:3], v[2:3], v[34:35]
	v_pk_mul_f32 v[4:5], v[4:5], v[36:37]
	v_pk_mul_f32 v[6:7], v[6:7], v[38:39]
	v_pk_add_f32 v[40:41], v[40:41], 1.0 op_sel_hi:[1,0]
	v_pk_add_f32 v[42:43], v[42:43], 1.0 op_sel_hi:[1,0]
	v_pk_add_f32 v[44:45], v[44:45], 1.0 op_sel_hi:[1,0]
	v_pk_add_f32 v[46:47], v[46:47], 1.0 op_sel_hi:[1,0]
	v_pk_fma_f32 v[0:1], v[0:1], v[40:41], v[58:59]
	v_pk_fma_f32 v[2:3], v[2:3], v[42:43], v[60:61]
	v_pk_fma_f32 v[4:5], v[4:5], v[44:45], v[62:63]
	v_pk_fma_f32 v[6:7], v[6:7], v[46:47], v[64:65]
	v_cvt_pk_f16_f32 v74, v0, v1
	v_cvt_pk_f16_f32 v75, v2, v3
	v_cvt_pk_f16_f32 v76, v4, v5
	v_cvt_pk_f16_f32 v77, v6, v7
	v_cvt_f32_f16_e32 v66, v74
	v_cvt_f32_f16_sdwa v67, v74 dst_sel:DWORD dst_unused:UNUSED_PAD src0_sel:WORD_1
	v_cvt_f32_f16_e32 v68, v75
	v_cvt_f32_f16_sdwa v69, v75 dst_sel:DWORD dst_unused:UNUSED_PAD src0_sel:WORD_1
	v_cvt_f32_f16_e32 v70, v76
	v_cvt_f32_f16_sdwa v71, v76 dst_sel:DWORD dst_unused:UNUSED_PAD src0_sel:WORD_1
	v_cvt_f32_f16_e32 v72, v77
	v_cvt_f32_f16_sdwa v73, v77 dst_sel:DWORD dst_unused:UNUSED_PAD src0_sel:WORD_1
	v_pk_add_f32 v[0:1], v[0:1], v[66:67] neg_lo:[0,1] neg_hi:[0,1]
	v_pk_add_f32 v[2:3], v[2:3], v[68:69] neg_lo:[0,1] neg_hi:[0,1]
	v_pk_add_f32 v[4:5], v[4:5], v[70:71] neg_lo:[0,1] neg_hi:[0,1]
	v_pk_add_f32 v[6:7], v[6:7], v[72:73] neg_lo:[0,1] neg_hi:[0,1]
	s_nop 0
	v_cvt_pk_f16_f32 v78, v0, v1
	v_cvt_pk_f16_f32 v79, v2, v3
	v_cvt_pk_f16_f32 v80, v4, v5
	v_cvt_pk_f16_f32 v81, v6, v7
	global_store_dwordx4 v[88:89], v[74:77], off offset:1984
	s_waitcnt vmcnt(6)
	v_mfma_f32_16x16x32_f16 a[8:11], v[74:77], a[104:107], a[8:11]
	v_mfma_f32_16x16x32_f16 a[8:11], v[78:81], a[104:107], a[8:11]
	v_mfma_f32_16x16x32_f16 a[8:11], v[74:77], a[108:111], a[8:11]
	v_mfma_f32_16x16x32_f16 a[4:7], v[74:77], a[112:115], a[4:7]
	v_mfma_f32_16x16x32_f16 a[4:7], v[78:81], a[112:115], a[4:7]
	v_mfma_f32_16x16x32_f16 a[4:7], v[74:77], a[116:119], a[4:7]
	v_mfma_f32_16x16x32_f16 a[0:3], v[74:77], a[120:123], a[0:3]
	v_mfma_f32_16x16x32_f16 a[0:3], v[78:81], a[120:123], a[0:3]
	v_mfma_f32_16x16x32_f16 a[0:3], v[74:77], a[124:127], a[0:3]
	s_nop 7
	s_nop 6
	v_accvgpr_read_b32 v0, a0
	v_accvgpr_read_b32 v4, a4
	v_accvgpr_read_b32 v8, a8
	v_accvgpr_read_b32 v1, a1
	v_accvgpr_read_b32 v2, a2
	v_accvgpr_read_b32 v3, a3
	v_accvgpr_read_b32 v5, a5
	v_accvgpr_read_b32 v6, a6
	v_accvgpr_read_b32 v7, a7
	v_accvgpr_read_b32 v9, a9
	v_accvgpr_read_b32 v10, a10
	v_accvgpr_read_b32 v11, a11
	ds_write2_b32 v55, v8, v4 offset1:16
	ds_write2_b32 v55, v10, v6 offset0:96 offset1:112
	ds_write2_b32 v55, v0, v9 offset0:32 offset1:48
	ds_write2_b32 v55, v5, v1 offset0:64 offset1:80
	ds_write2_b32 v55, v2, v11 offset0:128 offset1:144
	ds_write2_b32 v55, v7, v3 offset0:160 offset1:176
	s_and_saveexec_b64 s[34:35], s[2:3]
	s_cbranch_execz .LBB0_544
	global_load_dwordx4 v[4:7], v149, s[8:9]
	ds_read_b128 v[0:3], v13
	s_mov_b32 s28, 0x3fb8aa3b
	s_mov_b32 s38, 0xc2ce8ed0
	s_mov_b32 s39, 0x42b17218
	v_mov_b32_e32 v33, 0x7f800000
	v_readlane_b32 s48, v253, 35
	v_readlane_b32 s54, v253, 41
	v_readlane_b32 s55, v253, 42
	v_readlane_b32 s49, v253, 36
	v_readlane_b32 s50, v253, 37
	v_readlane_b32 s51, v253, 38
	v_readlane_b32 s52, v253, 39
	v_readlane_b32 s53, v253, 40
	v_readlane_b32 s56, v253, 43
	v_readlane_b32 s57, v253, 44
	v_readlane_b32 s58, v253, 45
	v_readlane_b32 s59, v253, 46
	v_readlane_b32 s60, v253, 47
	v_readlane_b32 s61, v253, 48
	v_readlane_b32 s62, v253, 49
	v_readlane_b32 s63, v253, 50
	s_waitcnt vmcnt(0) lgkmcnt(0)
; DI void row2_phase(const Params& P, int l, int r_begin, char* smem) {
;     ...
;     if (lane < 16) {
;       const int r = r0 + lane;
;       const float* L = lg + lane * 48;
;       float gl[4]; int gi = 0;
; #pragma unroll
;       for (int j = 0; j < 4; j++) gl[j] = L[j] + P.b_group[l * 4 + j];
;       float gm = gl[0];
; #pragma unroll
;       for (int j = 1; j < 4; j++) if (gl[j] > gm) { gm = gl[j]; gi = j; }
;       float gs = 0.f;
; #pragma unroll
;       for (int j = 0; j < 4; j++) gs += expf(gl[j] - gm);
;       const float pg = 1.f / gs;
;       float el[8];
; #pragma unroll
;       for (int j = 0; j < 8; j++) el[j] = L[4 + gi * 8 + j] + P.b_router[l * 32 + gi * 8 + j];
	v_pk_add_f32 v[0:1], v[0:1], v[4:5]
	s_nop 0
	v_cmp_gt_f32_e32 vcc, v1, v0
	v_add_f32_e32 v2, v2, v6
	v_add_f32_e32 v3, v3, v7
	v_cndmask_b32_e32 v4, v0, v1, vcc
	v_cmp_gt_f32_e64 s[0:1], v2, v4
	s_nop 1
	v_cndmask_b32_e64 v4, v4, v2, s[0:1]
	v_cmp_gt_f32_e64 s[4:5], v3, v4
	s_nop 1
	v_cndmask_b32_e64 v4, v4, v3, s[4:5]
	v_sub_f32_e32 v5, v0, v4
	v_sub_f32_e32 v0, v1, v4
	v_mul_f32_e32 v1, 0x3fb8aa3b, v0
	v_fma_f32 v6, v0, s28, -v1
	v_rndne_f32_e32 v7, v1
	v_fmac_f32_e32 v6, 0x32a5705f, v0
	v_sub_f32_e32 v1, v1, v7
	v_add_f32_e32 v1, v1, v6
	v_exp_f32_e32 v1, v1
	v_cvt_i32_f32_e32 v6, v7
	v_cmp_ngt_f32_e64 s[6:7], s38, v0
	v_ldexp_f32 v1, v1, v6
	s_nop 0
	v_cndmask_b32_e64 v1, 0, v1, s[6:7]
	v_cmp_nlt_f32_e64 s[6:7], s39, v0
	v_sub_f32_e32 v0, v2, v4
	s_nop 0
	v_cndmask_b32_e64 v21, v33, v1, s[6:7]
	v_mul_f32_e32 v1, 0x3fb8aa3b, v0
	v_fma_f32 v2, v0, s28, -v1
	v_rndne_f32_e32 v6, v1
	v_fmac_f32_e32 v2, 0x32a5705f, v0
	v_sub_f32_e32 v1, v1, v6
	v_add_f32_e32 v1, v1, v2
	v_exp_f32_e32 v1, v1
	v_cvt_i32_f32_e32 v2, v6
	v_cmp_ngt_f32_e64 s[6:7], s38, v0
	v_ldexp_f32 v1, v1, v2
	s_nop 0
	v_cndmask_b32_e64 v1, 0, v1, s[6:7]
	v_cmp_nlt_f32_e64 s[6:7], s39, v0
	v_sub_f32_e32 v0, v3, v4
	v_or_b32_e32 v4, v56, v53
	v_cndmask_b32_e64 v30, v33, v1, s[6:7]
	v_mul_f32_e32 v1, 0x3fb8aa3b, v0
	v_fma_f32 v2, v0, s28, -v1
	v_rndne_f32_e32 v3, v1
	v_fmac_f32_e32 v2, 0x32a5705f, v0
	v_sub_f32_e32 v1, v1, v3
	v_add_f32_e32 v1, v1, v2
	v_exp_f32_e32 v1, v1
	v_cvt_i32_f32_e32 v2, v3
	v_cmp_ngt_f32_e64 s[6:7], s38, v0
	v_ldexp_f32 v1, v1, v2
	s_nop 0
	v_cndmask_b32_e64 v1, 0, v1, s[6:7]
	v_cmp_nlt_f32_e64 s[6:7], s39, v0
	v_cndmask_b32_e64 v0, 0, 8, vcc
	v_cndmask_b32_e64 v0, v0, 16, s[0:1]
	v_cndmask_b32_e64 v32, v0, 24, s[4:5]
	v_cndmask_b32_e64 v31, v33, v1, s[6:7]
	v_or_b32_e32 v0, s23, v32
	v_mov_b32_e32 v1, v149
	v_lshl_add_u32 v6, v32, 2, v13
	v_lshl_add_u64 v[10:11], v[0:1], 2, s[54:55]
	ds_read_b128 v[0:3], v6 offset:16
	ds_read_b128 v[6:9], v6 offset:32
	global_load_dwordx4 v[22:25], v[10:11], off offset:16
	global_load_dwordx4 v[26:29], v[10:11], off
	v_mul_f32_e32 v10, 0x3fb8aa3b, v5
	v_fma_f32 v11, v5, s28, -v10
	v_fmac_f32_e32 v11, 0x32a5705f, v5
	v_cmp_ngt_f32_e32 vcc, s38, v5
	s_mov_b32 s6, 0xff61b1e6
	s_waitcnt vmcnt(1) lgkmcnt(0)
	v_add_f32_e32 v6, v6, v22
	v_rndne_f32_e32 v22, v10
	v_sub_f32_e32 v10, v10, v22
	v_add_f32_e32 v10, v10, v11
	v_exp_f32_e32 v10, v10
	v_cvt_i32_f32_e32 v11, v22
	s_waitcnt vmcnt(0)
; DI void row2_phase(const Params& P, int l, int r_begin, char* smem) {
;     ...
;       int i0 = 0; float v0 = el[0];
; #pragma unroll
;       for (int j = 1; j < 8; j++) if (el[j] > v0) { v0 = el[j]; i0 = j; }
;       int i1 = -1; float v1 = -3.0e38f;
; #pragma unroll
;       for (int j = 0; j < 8; j++) if (j != i0 && el[j] > v1) { v1 = el[j]; i1 = j; }
;       const float ex = expf(v1 - v0);
;       const float w0 = pg / (1.f + ex), w1 = pg * ex / (1.f + ex);
;       const int e0 = gi * 8 + i0, e1 = gi * 8 + i1;
;       int p0 = atomicAdd(&P.cnt[l * 32 + e0], 1); P.list[(size_t)e0 * LCAP + p0] = 2 * r; P.listW[(size_t)e0 * LCAP + p0] = w0;
;       int p1 = atomicAdd(&P.cnt[l * 32 + e1], 1); P.list[(size_t)e1 * LCAP + p1] = 2 * r + 1; P.listW[(size_t)e1 * LCAP + p1] = w1;
	v_pk_add_f32 v[0:1], v[0:1], v[26:27]
	v_add_f32_e32 v2, v2, v28
	v_add_f32_e32 v3, v3, v29
	v_ldexp_f32 v10, v10, v11
	v_cndmask_b32_e32 v10, 0, v10, vcc
	v_cmp_nlt_f32_e32 vcc, s39, v5
	v_add_f32_e32 v7, v7, v23
	v_add_f32_e32 v8, v8, v24
	v_cndmask_b32_e32 v5, v33, v10, vcc
	v_cmp_gt_f32_e32 vcc, v1, v0
	v_add_f32_e32 v9, v9, v25
	v_cmp_nlt_f32_e64 s[6:7], s6, v0
	v_cndmask_b32_e32 v11, v0, v1, vcc
	v_cndmask_b32_e64 v10, 0, 1, vcc
	v_cmp_gt_f32_e32 vcc, v2, v11
	v_mov_b32_e32 v22, 0xff61b1e6
	v_add_f32_e32 v5, v5, v21
	v_cndmask_b32_e32 v11, v11, v2, vcc
	v_cndmask_b32_e64 v10, v10, 2, vcc
	v_cmp_gt_f32_e32 vcc, v3, v11
	v_add_f32_e32 v5, v30, v5
	v_add_f32_e32 v5, v31, v5
	v_cndmask_b32_e32 v11, v11, v3, vcc
	v_cndmask_b32_e64 v10, v10, 3, vcc
	v_cmp_gt_f32_e32 vcc, v6, v11
	s_nop 1
	v_cndmask_b32_e32 v11, v11, v6, vcc
	v_cndmask_b32_e64 v10, v10, 4, vcc
	v_cmp_gt_f32_e32 vcc, v7, v11
	s_nop 1
	v_cndmask_b32_e32 v11, v11, v7, vcc
	v_cndmask_b32_e64 v10, v10, 5, vcc
	v_cmp_gt_f32_e32 vcc, v8, v11
	s_nop 1
	v_cndmask_b32_e32 v11, v11, v8, vcc
	v_cndmask_b32_e64 v10, v10, 6, vcc
	v_cmp_ngt_f32_e64 s[0:1], v9, v11
	s_nop 1
	v_cndmask_b32_e64 v10, 7, v10, s[0:1]
	v_cmp_eq_u32_e64 s[4:5], 0, v10
	s_or_b64 s[4:5], s[4:5], s[6:7]
	v_cndmask_b32_e64 v11, v9, v11, s[0:1]
	v_cndmask_b32_e64 v0, v0, v22, s[4:5]
	v_cndmask_b32_e64 v21, 0, -1, s[4:5]
	v_cmp_ne_u32_e64 s[4:5], 1, v10
	v_cmp_gt_f32_e64 s[6:7], v1, v0
	s_and_b64 s[4:5], s[4:5], s[6:7]
	v_cndmask_b32_e64 v0, v0, v1, s[4:5]
	v_cndmask_b32_e64 v21, v21, 1, s[4:5]
	v_cmp_ne_u32_e64 s[4:5], 2, v10
	v_cmp_gt_f32_e64 s[6:7], v2, v0
	s_and_b64 s[4:5], s[4:5], s[6:7]
	v_cndmask_b32_e64 v0, v0, v2, s[4:5]
	v_cndmask_b32_e64 v1, v21, 2, s[4:5]
	v_cmp_ne_u32_e64 s[4:5], 3, v10
	v_cmp_gt_f32_e64 s[6:7], v3, v0
	s_and_b64 s[4:5], s[4:5], s[6:7]
	v_cndmask_b32_e64 v0, v0, v3, s[4:5]
	v_cndmask_b32_e64 v1, v1, 3, s[4:5]
	v_cmp_ne_u32_e64 s[4:5], 4, v10
	v_cmp_gt_f32_e64 s[6:7], v6, v0
	s_and_b64 s[4:5], s[4:5], s[6:7]
	v_cndmask_b32_e64 v0, v0, v6, s[4:5]
	v_cndmask_b32_e64 v1, v1, 4, s[4:5]
	v_cmp_ne_u32_e64 s[4:5], 5, v10
	v_cmp_gt_f32_e64 s[6:7], v7, v0
	s_and_b64 s[4:5], s[4:5], s[6:7]
	v_cndmask_b32_e64 v0, v0, v7, s[4:5]
	v_cndmask_b32_e64 v1, v1, 5, s[4:5]
	s_and_b64 s[4:5], vcc, s[0:1]
	v_cmp_ngt_f32_e32 vcc, v8, v0
	s_or_b64 vcc, s[4:5], vcc
	v_readlane_b32 s4, v255, 24
	v_cndmask_b32_e32 v0, v8, v0, vcc
	v_cndmask_b32_e32 v1, 6, v1, vcc
	v_cmp_gt_f32_e32 vcc, v9, v0
	s_and_b64 vcc, s[0:1], vcc
	v_div_scale_f32 v2, s[0:1], v5, v5, 1.0
	v_rcp_f32_e32 v3, v2
	v_cndmask_b32_e64 v1, v1, 7, vcc
	v_cndmask_b32_e32 v0, v0, v9, vcc
	v_sub_f32_e32 v0, v0, v11
	v_fma_f32 v6, -v2, v3, 1.0
	v_fmac_f32_e32 v3, v6, v3
	v_div_scale_f32 v6, vcc, 1.0, v5, 1.0
	v_mul_f32_e32 v7, v6, v3
	v_fma_f32 v8, -v2, v7, v6
	v_fmac_f32_e32 v7, v8, v3
	v_fma_f32 v2, -v2, v7, v6
	v_div_fmas_f32 v2, v2, v3, v7
	v_mul_f32_e32 v3, 0x3fb8aa3b, v0
	v_div_fixup_f32 v2, v2, v5, 1.0
	v_fma_f32 v5, v0, s28, -v3
	v_rndne_f32_e32 v6, v3
	v_fmac_f32_e32 v5, 0x32a5705f, v0
	v_sub_f32_e32 v3, v3, v6
	v_add_f32_e32 v3, v3, v5
	v_exp_f32_e32 v3, v3
	v_cvt_i32_f32_e32 v5, v6
	v_cmp_ngt_f32_e32 vcc, s38, v0
	s_mov_b32 s28, 0x21000
	v_readlane_b32 s6, v254, 0
	v_ldexp_f32 v3, v3, v5
	v_cndmask_b32_e32 v3, 0, v3, vcc
	v_cmp_nlt_f32_e32 vcc, s39, v0
	v_readlane_b32 s5, v255, 25
	v_readlane_b32 s7, v254, 1
	v_cndmask_b32_e32 v0, v33, v3, vcc
	v_add_f32_e32 v3, 1.0, v0
	v_div_scale_f32 v5, s[0:1], v3, v3, v2
	v_rcp_f32_e32 v6, v5
	v_mul_f32_e32 v0, v2, v0
	v_fma_f32 v7, -v5, v6, 1.0
	v_fmac_f32_e32 v6, v7, v6
	v_div_scale_f32 v7, vcc, v2, v3, v2
	v_mul_f32_e32 v8, v7, v6
	v_fma_f32 v9, -v5, v8, v7
	v_fmac_f32_e32 v8, v9, v6
	v_fma_f32 v5, -v5, v8, v7
	v_div_fmas_f32 v5, v5, v6, v8
	v_div_fixup_f32 v8, v5, v3, v2
	v_div_scale_f32 v2, s[0:1], v3, v3, v0
	v_rcp_f32_e32 v5, v2
	v_readlane_b32 s0, v253, 63
	v_readlane_b32 s1, v255, 0
	v_fma_f32 v6, -v2, v5, 1.0
	v_fmac_f32_e32 v5, v6, v5
	v_div_scale_f32 v6, vcc, v0, v3, v0
	v_mul_f32_e32 v7, v6, v5
	v_fma_f32 v9, -v2, v7, v6
	v_fmac_f32_e32 v7, v9, v5
	v_fma_f32 v2, -v2, v7, v6
	v_div_fmas_f32 v2, v2, v5, v7
	v_or_b32_e32 v5, v10, v32
	v_div_fixup_f32 v2, v2, v3, v0
	v_add_u32_e32 v3, v1, v32
	v_or_b32_e32 v0, s23, v5
	v_mov_b32_e32 v1, v149
	v_mov_b32_e32 v9, 1
	v_mov_b32_e32 v6, 2
	v_mov_b32_e32 v7, 0x3080
	ds_add_rtn_u32 v7, v7, v6
	v_lshlrev_b32_e32 v0, 2, v5
	v_add_u32_e32 v0, 0x3000, v0
	ds_add_rtn_u32 v0, v0, v9
	v_lshlrev_b32_e32 v1, 2, v3
	v_add_u32_e32 v1, 0x3000, v1
	ds_add_rtn_u32 v1, v1, v9
	v_lshlrev_b32_e32 v6, 1, v4
	v_or_b32_e32 v9, 1, v6
	s_waitcnt lgkmcnt(0)
	v_lshl_or_b32 v0, v0, 5, v5
	v_lshl_or_b32 v1, v1, 5, v3
	v_lshlrev_b32_e32 v7, 4, v7
	v_add_u32_e32 v7, 0x10000, v7
	ds_write_b32 v7, v0
	ds_write_b32 v7, v6 offset:4
	ds_write_b32 v7, v8 offset:8
	ds_write_b32 v7, v1 offset:16
	ds_write_b32 v7, v9 offset:20
	ds_write_b32 v7, v2 offset:24
	s_branch .LBB0_544
